# 16-byte data stores inside the layer loop made write-through (sc0 sc1) so the grid barrier's L2 release flush has less dirty data
# speedup vs baseline: 1.0157x; 1.0157x over previous
; __device__ __forceinline__ unsigned cvtpk(float lo, float hi) { f32x2 v = {lo, hi}; bf16x2_t b = __builtin_convertvector(v, bf16x2_t); return __builtin_bit_cast(unsigned, b); }
;     __device__ __forceinline__ void operator()(AccRef acc, const Unit& u, int wr, int wc, int fr, int fq) const {
;     ...
;                     f32x4 v0 = acc[ai][bj][m][0] * rs, v1 = acc[ai][bj][m][1] * rs;
;                     if (u.pn == 6 || (u.pn == 7 && bj == 0)) {
;                         float s = (v0[0] * v0[0] + v0[1] * v0[1]) + (v0[2] * v0[2] + v0[3] * v0[3]) + (v1[0] * v1[0] + v1[1] * v1[1]) + (v1[2] * v1[2] + v1[3] * v1[3]);
;                         s += __shfl_xor(s, 16); s += __shfl_xor(s, 32);
;                         if (fq == 0) { if (u.pn == 6) ssqq[(size_t)row * 8 + bj * 4 + wc] = s; else ssqkv[(size_t)row * 4 + wc] = s; }
;                     }
;                     if (u.pn == 7 && bj == 1 && wc == 0) { const int pos = row & (SEQ - 1); rope8(v0, v1, cost + pos * 16, sint + pos * 16, fq); }
;                     u32x4 w; w.x = cvtpk(v0[0], v0[1]); w.y = cvtpk(v0[2], v0[3]); w.z = cvtpk(v1[0], v1[1]); w.w = cvtpk(v1[2], v1[3]);
;                     st16_wt(rowp + bj * 128, w);
.LBB0_166:
	v_lshl_or_b32 v150, s18, 8, v166
	s_waitcnt lgkmcnt(0)
	v_mov_b64_e32 v[128:129], s[90:91]
	v_ashrrev_i32_e32 v151, 31, v150
	v_mad_i64_i32 v[128:129], s[20:21], v148, s27, v[128:129]
	v_mov_b32_e32 v157, v156
	v_lshl_add_u64 v[152:153], v[150:151], 1, v[128:129]
	v_cvt_pk_bf16_f32 v158, v154, v155
	v_cvt_pk_bf16_f32 v159, v124, v125
	v_cvt_pk_bf16_f32 v160, v126, v127
	v_cvt_pk_bf16_f32 v161, v122, v123
	v_mov_b32_e32 v122, v156
	v_mov_b32_e32 v123, v156
	v_cndmask_b32_e64 v0, 0, 1, s[46:47]
	global_store_dwordx4 v[152:153], v[158:161], off sc0 sc1
	v_pk_mul_f32 v[154:155], v[120:121], v[122:123]
	v_cmp_ne_u32_e64 s[44:45], 1, v0
	v_pk_mul_f32 v[160:161], v[118:119], v[156:157]
	v_pk_mul_f32 v[158:159], v[116:117], v[122:123]
	v_pk_mul_f32 v[156:157], v[114:115], v[156:157]
	s_andn2_b64 vcc, exec, s[46:47]
	s_mov_b64 s[20:21], -1
	s_cbranch_vccnz .LBB0_168
	s_mov_b64 s[20:21], 0

; __device__ __forceinline__ unsigned cvtpk(float lo, float hi) { f32x2 v = {lo, hi}; bf16x2_t b = __builtin_convertvector(v, bf16x2_t); return __builtin_bit_cast(unsigned, b); }
;     __device__ __forceinline__ void operator()(AccRef acc, const Unit& u, int wr, int wc, int fr, int fq) const {
;     ...
;                 const int row = row0 + ai * 128 + m * 16;
;                 const float rs = rsqrtf(ssq_sum<4>(ssqx + (size_t)row * 4) * (1.0f / DM) + EPS);
;                 bf16_t* rowp = O + (size_t)row * NPROJ + col0;
; #pragma unroll
;                 for (int bj = 0; bj < 2; ++bj) {
;                     f32x4 v0 = acc[ai][bj][m][0] * rs, v1 = acc[ai][bj][m][1] * rs;
;                     if (u.pn == 6 || (u.pn == 7 && bj == 0)) {
;                         float s = (v0[0] * v0[0] + v0[1] * v0[1]) + (v0[2] * v0[2] + v0[3] * v0[3]) + (v1[0] * v1[0] + v1[1] * v1[1]) + (v1[2] * v1[2] + v1[3] * v1[3]);
;                         s += __shfl_xor(s, 16); s += __shfl_xor(s, 32);
;                         if (fq == 0) { if (u.pn == 6) ssqq[(size_t)row * 8 + bj * 4 + wc] = s; else ssqkv[(size_t)row * 4 + wc] = s; }
;                     }
;                     if (u.pn == 7 && bj == 1 && wc == 0) { const int pos = row & (SEQ - 1); rope8(v0, v1, cost + pos * 16, sint + pos * 16, fq); }
;                     u32x4 w; w.x = cvtpk(v0[0], v0[1]); w.y = cvtpk(v0[2], v0[3]); w.z = cvtpk(v1[0], v1[1]); w.w = cvtpk(v1[2], v1[3]);
;                     st16_wt(rowp + bj * 128, w);
.LBB0_174:
	s_waitcnt lgkmcnt(0)
	v_cvt_pk_bf16_f32 v114, v160, v161
	v_cvt_pk_bf16_f32 v115, v154, v155
	v_cvt_pk_bf16_f32 v116, v156, v157
	v_cvt_pk_bf16_f32 v117, v158, v159
	v_or_b32_e32 v124, 16, v148
	global_store_dwordx4 v[152:153], v[114:117], off offset:256 sc0 sc1
	v_ashrrev_i32_e32 v125, 31, v124
	v_cndmask_b32_e64 v0, 0, 1, s[16:17]
	v_and_b32_e32 v114, 0xff, v124
	v_lshlrev_b32_e32 v114, 4, v114
	v_add_u32_e32 v114, 0x21400, v114
	ds_read_b128 v[114:117], v114
	v_cmp_ne_u32_e64 s[48:49], 1, v0
	v_lshlrev_b64 v[126:127], 5, v[124:125]
	s_andn2_b64 vcc, exec, s[16:17]
	s_waitcnt lgkmcnt(0)
	v_mov_b32_e32 v118, v115
	v_mov_b32_e32 v119, v116
	v_mov_b32_e32 v115, v117
	v_pk_add_f32 v[114:115], v[118:119], v[114:115]
	s_nop 0
	v_add_f32_e32 v114, v114, v115
	v_add_f32_e32 v114, 0, v114
	v_fmamk_f32 v114, v114, 0x3a800000, v212
	v_mul_f32_e32 v115, 0x4b800000, v114
	v_cmp_gt_f32_e64 s[50:51], s69, v114
	s_nop 1
	v_cndmask_b32_e64 v114, v114, v115, s[50:51]
	v_rsq_f32_e32 v114, v114
	s_nop 0
	v_mul_f32_e32 v0, 0x45800000, v114
	v_cndmask_b32_e64 v118, v114, v0, s[50:51]
	v_pk_mul_f32 v[112:113], v[112:113], v[118:119] op_sel_hi:[1,0]
	v_pk_mul_f32 v[110:111], v[110:111], v[118:119] op_sel_hi:[1,0]
	v_pk_mul_f32 v[108:109], v[108:109], v[118:119] op_sel_hi:[1,0]
	v_pk_mul_f32 v[106:107], v[106:107], v[118:119] op_sel_hi:[1,0]
	s_cbranch_vccnz .LBB0_178
	v_mul_f32_e32 v0, v111, v111
	v_mul_f32_e32 v114, v113, v113
	v_fmac_f32_e32 v0, v110, v110
	v_fmac_f32_e32 v114, v112, v112
	v_add_f32_e32 v0, v0, v114
	v_mul_f32_e32 v114, v107, v107
	v_fmac_f32_e32 v114, v106, v106
	v_add_f32_e32 v0, v114, v0
	v_mul_f32_e32 v114, v109, v109
	v_fmac_f32_e32 v114, v108, v108
	v_and_b32_e32 v115, 64, v213
	v_add_f32_e32 v0, v114, v0
	v_xor_b32_e32 v114, 16, v213
	v_add_u32_e32 v115, 64, v115
	v_cmp_lt_i32_e32 vcc, v114, v115
	s_nop 1
	v_cndmask_b32_e32 v114, v213, v114, vcc
	v_lshlrev_b32_e32 v114, 2, v114
	ds_bpermute_b32 v114, v114, v0
	s_waitcnt lgkmcnt(0)
	v_add_f32_e32 v0, v0, v114
	v_xor_b32_e32 v114, 32, v213
	v_cmp_lt_i32_e32 vcc, v114, v115
	s_nop 1
	v_cndmask_b32_e32 v114, v213, v114, vcc
	v_lshlrev_b32_e32 v114, 2, v114
	ds_bpermute_b32 v114, v114, v0
	s_and_saveexec_b64 s[16:17], s[38:39]
	s_cbranch_execz .LBB0_177
	v_lshlrev_b64 v[116:117], 2, v[124:125]
	v_lshl_add_u64 v[120:121], s[78:79], 0, v[126:127]
	v_lshl_add_u64 v[116:117], v[116:117], 2, s[88:89]
	v_cndmask_b32_e64 v117, v117, v121, s[42:43]
	v_cndmask_b32_e64 v116, v116, v120, s[42:43]
	s_lshl_b32 s72, s4, 2
	v_lshl_add_u64 v[116:117], v[116:117], 0, s[72:73]
	s_waitcnt lgkmcnt(0)
	v_add_f32_e32 v0, v0, v114
	global_store_dword v[116:117], v0, off

; __device__ __forceinline__ unsigned cvtpk(float lo, float hi) { f32x2 v = {lo, hi}; bf16x2_t b = __builtin_convertvector(v, bf16x2_t); return __builtin_bit_cast(unsigned, b); }
;     __device__ __forceinline__ void operator()(AccRef acc, const Unit& u, int wr, int wc, int fr, int fq) const {
;     ...
;                     f32x4 v0 = acc[ai][bj][m][0] * rs, v1 = acc[ai][bj][m][1] * rs;
;                     if (u.pn == 6 || (u.pn == 7 && bj == 0)) {
;                         float s = (v0[0] * v0[0] + v0[1] * v0[1]) + (v0[2] * v0[2] + v0[3] * v0[3]) + (v1[0] * v1[0] + v1[1] * v1[1]) + (v1[2] * v1[2] + v1[3] * v1[3]);
;                         s += __shfl_xor(s, 16); s += __shfl_xor(s, 32);
;                         if (fq == 0) { if (u.pn == 6) ssqq[(size_t)row * 8 + bj * 4 + wc] = s; else ssqkv[(size_t)row * 4 + wc] = s; }
;                     }
;                     if (u.pn == 7 && bj == 1 && wc == 0) { const int pos = row & (SEQ - 1); rope8(v0, v1, cost + pos * 16, sint + pos * 16, fq); }
;                     u32x4 w; w.x = cvtpk(v0[0], v0[1]); w.y = cvtpk(v0[2], v0[3]); w.z = cvtpk(v1[0], v1[1]); w.w = cvtpk(v1[2], v1[3]);
;                     st16_wt(rowp + bj * 128, w);
.LBB0_178:
	s_waitcnt lgkmcnt(0)
	v_mov_b64_e32 v[114:115], s[90:91]
	v_mov_b32_e32 v119, v118
	v_mad_i64_i32 v[114:115], s[16:17], v124, s27, v[114:115]
	v_cvt_pk_bf16_f32 v110, v110, v111
	v_cvt_pk_bf16_f32 v111, v112, v113
	v_cvt_pk_bf16_f32 v112, v106, v107
	v_mov_b32_e32 v106, v118
	v_mov_b32_e32 v107, v118
	v_lshl_add_u64 v[114:115], v[150:151], 1, v[114:115]
	v_cvt_pk_bf16_f32 v113, v108, v109
	v_pk_mul_f32 v[116:117], v[104:105], v[106:107]
	v_pk_mul_f32 v[122:123], v[102:103], v[118:119]
	v_pk_mul_f32 v[120:121], v[100:101], v[106:107]
	v_pk_mul_f32 v[118:119], v[98:99], v[118:119]
	s_and_b64 vcc, exec, s[44:45]
	s_mov_b64 s[16:17], -1
	global_store_dwordx4 v[114:115], v[110:113], off sc0 sc1
	s_cbranch_vccz .LBB0_233
	s_andn2_b64 vcc, exec, s[16:17]
	s_cbranch_vccz .LBB0_234

; __device__ __forceinline__ unsigned cvtpk(float lo, float hi) { f32x2 v = {lo, hi}; bf16x2_t b = __builtin_convertvector(v, bf16x2_t); return __builtin_bit_cast(unsigned, b); }
;     __device__ __forceinline__ void operator()(AccRef acc, const Unit& u, int wr, int wc, int fr, int fq) const {
;     ...
;                 const int row = row0 + ai * 128 + m * 16;
;                 const float rs = rsqrtf(ssq_sum<4>(ssqx + (size_t)row * 4) * (1.0f / DM) + EPS);
;                 bf16_t* rowp = O + (size_t)row * NPROJ + col0;
; #pragma unroll
;                 for (int bj = 0; bj < 2; ++bj) {
;                     f32x4 v0 = acc[ai][bj][m][0] * rs, v1 = acc[ai][bj][m][1] * rs;
;                     if (u.pn == 6 || (u.pn == 7 && bj == 0)) {
;                         float s = (v0[0] * v0[0] + v0[1] * v0[1]) + (v0[2] * v0[2] + v0[3] * v0[3]) + (v1[0] * v1[0] + v1[1] * v1[1]) + (v1[2] * v1[2] + v1[3] * v1[3]);
;                         s += __shfl_xor(s, 16); s += __shfl_xor(s, 32);
;                         if (fq == 0) { if (u.pn == 6) ssqq[(size_t)row * 8 + bj * 4 + wc] = s; else ssqkv[(size_t)row * 4 + wc] = s; }
;                     }
;                     if (u.pn == 7 && bj == 1 && wc == 0) { const int pos = row & (SEQ - 1); rope8(v0, v1, cost + pos * 16, sint + pos * 16, fq); }
;                     u32x4 w; w.x = cvtpk(v0[0], v0[1]); w.y = cvtpk(v0[2], v0[3]); w.z = cvtpk(v1[0], v1[1]); w.w = cvtpk(v1[2], v1[3]);
;                     st16_wt(rowp + bj * 128, w);
.LBB0_182:
	s_waitcnt lgkmcnt(0)
	v_cvt_pk_bf16_f32 v98, v122, v123
	v_cvt_pk_bf16_f32 v99, v116, v117
	v_cvt_pk_bf16_f32 v100, v118, v119
	v_cvt_pk_bf16_f32 v101, v120, v121
	v_or_b32_e32 v108, 32, v148
	global_store_dwordx4 v[114:115], v[98:101], off offset:256 sc0 sc1
	v_ashrrev_i32_e32 v109, 31, v108
	s_and_b64 vcc, exec, s[48:49]
	v_and_b32_e32 v98, 0xff, v108
	v_lshlrev_b32_e32 v98, 4, v98
	v_add_u32_e32 v98, 0x21400, v98
	ds_read_b128 v[98:101], v98
	v_lshlrev_b64 v[110:111], 5, v[108:109]
	s_waitcnt lgkmcnt(0)
	v_mov_b32_e32 v102, v99
	v_mov_b32_e32 v103, v100
	v_mov_b32_e32 v99, v101
	v_pk_add_f32 v[98:99], v[102:103], v[98:99]
	s_nop 0
	v_add_f32_e32 v0, v98, v99
	v_add_f32_e32 v0, 0, v0
	v_fmamk_f32 v0, v0, 0x3a800000, v212
	v_mul_f32_e32 v98, 0x4b800000, v0
	v_cmp_gt_f32_e64 s[50:51], s69, v0
	s_nop 1
	v_cndmask_b32_e64 v0, v0, v98, s[50:51]
	v_rsq_f32_e32 v0, v0
	s_nop 0
	v_mul_f32_e32 v98, 0x45800000, v0
	v_cndmask_b32_e64 v102, v0, v98, s[50:51]
	v_pk_mul_f32 v[96:97], v[96:97], v[102:103] op_sel_hi:[1,0]
	v_pk_mul_f32 v[94:95], v[94:95], v[102:103] op_sel_hi:[1,0]
	v_pk_mul_f32 v[92:93], v[92:93], v[102:103] op_sel_hi:[1,0]
	v_pk_mul_f32 v[90:91], v[90:91], v[102:103] op_sel_hi:[1,0]
	s_cbranch_vccnz .LBB0_186
	v_mul_f32_e32 v0, v95, v95
	v_mul_f32_e32 v98, v97, v97
	v_fmac_f32_e32 v0, v94, v94
	v_fmac_f32_e32 v98, v96, v96
	v_add_f32_e32 v0, v0, v98
	v_mul_f32_e32 v98, v91, v91
	v_fmac_f32_e32 v98, v90, v90
	v_add_f32_e32 v0, v98, v0
	v_mul_f32_e32 v98, v93, v93
	v_fmac_f32_e32 v98, v92, v92
	v_and_b32_e32 v99, 64, v213
	v_add_f32_e32 v0, v98, v0
	v_xor_b32_e32 v98, 16, v213
	v_add_u32_e32 v99, 64, v99
	v_cmp_lt_i32_e32 vcc, v98, v99
	s_nop 1
	v_cndmask_b32_e32 v98, v213, v98, vcc
	v_lshlrev_b32_e32 v98, 2, v98
	ds_bpermute_b32 v98, v98, v0
	s_waitcnt lgkmcnt(0)
	v_add_f32_e32 v0, v0, v98
	v_xor_b32_e32 v98, 32, v213
	v_cmp_lt_i32_e32 vcc, v98, v99
	s_nop 1
	v_cndmask_b32_e32 v98, v213, v98, vcc
	v_lshlrev_b32_e32 v98, 2, v98
	ds_bpermute_b32 v98, v98, v0
	s_and_saveexec_b64 s[16:17], s[38:39]
	s_cbranch_execz .LBB0_185
	v_lshlrev_b64 v[100:101], 2, v[108:109]
	v_lshl_add_u64 v[104:105], s[78:79], 0, v[110:111]
	v_lshl_add_u64 v[100:101], v[100:101], 2, s[88:89]
	v_cndmask_b32_e64 v101, v101, v105, s[42:43]
	v_cndmask_b32_e64 v100, v100, v104, s[42:43]
	s_lshl_b32 s72, s4, 2
	v_lshl_add_u64 v[100:101], v[100:101], 0, s[72:73]
	s_waitcnt lgkmcnt(0)
	v_add_f32_e32 v0, v0, v98
	global_store_dword v[100:101], v0, off

; __device__ __forceinline__ unsigned cvtpk(float lo, float hi) { f32x2 v = {lo, hi}; bf16x2_t b = __builtin_convertvector(v, bf16x2_t); return __builtin_bit_cast(unsigned, b); }
;     __device__ __forceinline__ void operator()(AccRef acc, const Unit& u, int wr, int wc, int fr, int fq) const {
;     ...
;                     f32x4 v0 = acc[ai][bj][m][0] * rs, v1 = acc[ai][bj][m][1] * rs;
;                     if (u.pn == 6 || (u.pn == 7 && bj == 0)) {
;                         float s = (v0[0] * v0[0] + v0[1] * v0[1]) + (v0[2] * v0[2] + v0[3] * v0[3]) + (v1[0] * v1[0] + v1[1] * v1[1]) + (v1[2] * v1[2] + v1[3] * v1[3]);
;                         s += __shfl_xor(s, 16); s += __shfl_xor(s, 32);
;                         if (fq == 0) { if (u.pn == 6) ssqq[(size_t)row * 8 + bj * 4 + wc] = s; else ssqkv[(size_t)row * 4 + wc] = s; }
;                     }
;                     if (u.pn == 7 && bj == 1 && wc == 0) { const int pos = row & (SEQ - 1); rope8(v0, v1, cost + pos * 16, sint + pos * 16, fq); }
;                     u32x4 w; w.x = cvtpk(v0[0], v0[1]); w.y = cvtpk(v0[2], v0[3]); w.z = cvtpk(v1[0], v1[1]); w.w = cvtpk(v1[2], v1[3]);
;                     st16_wt(rowp + bj * 128, w);
.LBB0_186:
	s_waitcnt lgkmcnt(0)
	v_mov_b64_e32 v[98:99], s[90:91]
	v_mov_b32_e32 v103, v102
	v_mad_i64_i32 v[98:99], s[16:17], v108, s27, v[98:99]
	v_cvt_pk_bf16_f32 v94, v94, v95
	v_cvt_pk_bf16_f32 v95, v96, v97
	v_cvt_pk_bf16_f32 v96, v90, v91
	v_mov_b32_e32 v90, v102
	v_mov_b32_e32 v91, v102
	v_lshl_add_u64 v[98:99], v[150:151], 1, v[98:99]
	v_cvt_pk_bf16_f32 v97, v92, v93
	v_pk_mul_f32 v[100:101], v[88:89], v[90:91]
	v_pk_mul_f32 v[106:107], v[86:87], v[102:103]
	v_pk_mul_f32 v[104:105], v[84:85], v[90:91]
	v_pk_mul_f32 v[102:103], v[82:83], v[102:103]
	s_and_b64 vcc, exec, s[44:45]
	s_mov_b64 s[16:17], -1
	global_store_dwordx4 v[98:99], v[94:97], off sc0 sc1
	s_cbranch_vccz .LBB0_237
	s_andn2_b64 vcc, exec, s[16:17]
	s_cbranch_vccz .LBB0_238

; __device__ __forceinline__ unsigned cvtpk(float lo, float hi) { f32x2 v = {lo, hi}; bf16x2_t b = __builtin_convertvector(v, bf16x2_t); return __builtin_bit_cast(unsigned, b); }
;     __device__ __forceinline__ void operator()(AccRef acc, const Unit& u, int wr, int wc, int fr, int fq) const {
;     ...
;                 const int row = row0 + ai * 128 + m * 16;
;                 const float rs = rsqrtf(ssq_sum<4>(ssqx + (size_t)row * 4) * (1.0f / DM) + EPS);
;                 bf16_t* rowp = O + (size_t)row * NPROJ + col0;
; #pragma unroll
;                 for (int bj = 0; bj < 2; ++bj) {
;                     f32x4 v0 = acc[ai][bj][m][0] * rs, v1 = acc[ai][bj][m][1] * rs;
;                     if (u.pn == 6 || (u.pn == 7 && bj == 0)) {
;                         float s = (v0[0] * v0[0] + v0[1] * v0[1]) + (v0[2] * v0[2] + v0[3] * v0[3]) + (v1[0] * v1[0] + v1[1] * v1[1]) + (v1[2] * v1[2] + v1[3] * v1[3]);
;                         s += __shfl_xor(s, 16); s += __shfl_xor(s, 32);
;                         if (fq == 0) { if (u.pn == 6) ssqq[(size_t)row * 8 + bj * 4 + wc] = s; else ssqkv[(size_t)row * 4 + wc] = s; }
;                     }
;                     if (u.pn == 7 && bj == 1 && wc == 0) { const int pos = row & (SEQ - 1); rope8(v0, v1, cost + pos * 16, sint + pos * 16, fq); }
;                     u32x4 w; w.x = cvtpk(v0[0], v0[1]); w.y = cvtpk(v0[2], v0[3]); w.z = cvtpk(v1[0], v1[1]); w.w = cvtpk(v1[2], v1[3]);
;                     st16_wt(rowp + bj * 128, w);
.LBB0_190:
	s_waitcnt lgkmcnt(0)
	v_cvt_pk_bf16_f32 v82, v106, v107
	v_cvt_pk_bf16_f32 v83, v100, v101
	v_cvt_pk_bf16_f32 v84, v102, v103
	v_cvt_pk_bf16_f32 v85, v104, v105
	v_or_b32_e32 v92, 48, v148
	global_store_dwordx4 v[98:99], v[82:85], off offset:256 sc0 sc1
	v_ashrrev_i32_e32 v93, 31, v92
	s_and_b64 vcc, exec, s[48:49]
	v_and_b32_e32 v82, 0xff, v92
	v_lshlrev_b32_e32 v82, 4, v82
	v_add_u32_e32 v82, 0x21400, v82
	ds_read_b128 v[82:85], v82
	v_lshlrev_b64 v[94:95], 5, v[92:93]
	s_waitcnt lgkmcnt(0)
	v_mov_b32_e32 v86, v83
	v_mov_b32_e32 v87, v84
	v_mov_b32_e32 v83, v85
	v_pk_add_f32 v[82:83], v[86:87], v[82:83]
	s_nop 0
	v_add_f32_e32 v0, v82, v83
	v_add_f32_e32 v0, 0, v0
	v_fmamk_f32 v0, v0, 0x3a800000, v212
	v_mul_f32_e32 v82, 0x4b800000, v0
	v_cmp_gt_f32_e64 s[50:51], s69, v0
	s_nop 1
	v_cndmask_b32_e64 v0, v0, v82, s[50:51]
	v_rsq_f32_e32 v0, v0
	s_nop 0
	v_mul_f32_e32 v82, 0x45800000, v0
	v_cndmask_b32_e64 v86, v0, v82, s[50:51]
	v_pk_mul_f32 v[80:81], v[80:81], v[86:87] op_sel_hi:[1,0]
	v_pk_mul_f32 v[78:79], v[78:79], v[86:87] op_sel_hi:[1,0]
	v_pk_mul_f32 v[76:77], v[76:77], v[86:87] op_sel_hi:[1,0]
	v_pk_mul_f32 v[74:75], v[74:75], v[86:87] op_sel_hi:[1,0]
	s_cbranch_vccnz .LBB0_194
	v_mul_f32_e32 v0, v79, v79
	v_mul_f32_e32 v82, v81, v81
	v_fmac_f32_e32 v0, v78, v78
	v_fmac_f32_e32 v82, v80, v80
	v_add_f32_e32 v0, v0, v82
	v_mul_f32_e32 v82, v75, v75
	v_fmac_f32_e32 v82, v74, v74
	v_add_f32_e32 v0, v82, v0
	v_mul_f32_e32 v82, v77, v77
	v_fmac_f32_e32 v82, v76, v76
	v_and_b32_e32 v83, 64, v213
	v_add_f32_e32 v0, v82, v0
	v_xor_b32_e32 v82, 16, v213
	v_add_u32_e32 v83, 64, v83
	v_cmp_lt_i32_e32 vcc, v82, v83
	s_nop 1
	v_cndmask_b32_e32 v82, v213, v82, vcc
	v_lshlrev_b32_e32 v82, 2, v82
	ds_bpermute_b32 v82, v82, v0
	s_waitcnt lgkmcnt(0)
	v_add_f32_e32 v0, v0, v82
	v_xor_b32_e32 v82, 32, v213
	v_cmp_lt_i32_e32 vcc, v82, v83
	s_nop 1
	v_cndmask_b32_e32 v82, v213, v82, vcc
	v_lshlrev_b32_e32 v82, 2, v82
	ds_bpermute_b32 v82, v82, v0
	s_and_saveexec_b64 s[16:17], s[38:39]
	s_cbranch_execz .LBB0_193
	v_lshlrev_b64 v[84:85], 2, v[92:93]
	v_lshl_add_u64 v[88:89], s[78:79], 0, v[94:95]
	v_lshl_add_u64 v[84:85], v[84:85], 2, s[88:89]
	v_cndmask_b32_e64 v85, v85, v89, s[42:43]
	v_cndmask_b32_e64 v84, v84, v88, s[42:43]
	s_lshl_b32 s72, s4, 2
	v_lshl_add_u64 v[84:85], v[84:85], 0, s[72:73]
	s_waitcnt lgkmcnt(0)
	v_add_f32_e32 v0, v0, v82
	global_store_dword v[84:85], v0, off

; __device__ __forceinline__ unsigned cvtpk(float lo, float hi) { f32x2 v = {lo, hi}; bf16x2_t b = __builtin_convertvector(v, bf16x2_t); return __builtin_bit_cast(unsigned, b); }
;     __device__ __forceinline__ void operator()(AccRef acc, const Unit& u, int wr, int wc, int fr, int fq) const {
;     ...
;                     f32x4 v0 = acc[ai][bj][m][0] * rs, v1 = acc[ai][bj][m][1] * rs;
;                     if (u.pn == 6 || (u.pn == 7 && bj == 0)) {
;                         float s = (v0[0] * v0[0] + v0[1] * v0[1]) + (v0[2] * v0[2] + v0[3] * v0[3]) + (v1[0] * v1[0] + v1[1] * v1[1]) + (v1[2] * v1[2] + v1[3] * v1[3]);
;                         s += __shfl_xor(s, 16); s += __shfl_xor(s, 32);
;                         if (fq == 0) { if (u.pn == 6) ssqq[(size_t)row * 8 + bj * 4 + wc] = s; else ssqkv[(size_t)row * 4 + wc] = s; }
;                     }
;                     if (u.pn == 7 && bj == 1 && wc == 0) { const int pos = row & (SEQ - 1); rope8(v0, v1, cost + pos * 16, sint + pos * 16, fq); }
;                     u32x4 w; w.x = cvtpk(v0[0], v0[1]); w.y = cvtpk(v0[2], v0[3]); w.z = cvtpk(v1[0], v1[1]); w.w = cvtpk(v1[2], v1[3]);
;                     st16_wt(rowp + bj * 128, w);
.LBB0_194:
	s_waitcnt lgkmcnt(0)
	v_mov_b64_e32 v[82:83], s[90:91]
	v_mov_b32_e32 v87, v86
	v_mad_i64_i32 v[82:83], s[16:17], v92, s27, v[82:83]
	v_cvt_pk_bf16_f32 v78, v78, v79
	v_cvt_pk_bf16_f32 v79, v80, v81
	v_cvt_pk_bf16_f32 v80, v74, v75
	v_mov_b32_e32 v74, v86
	v_mov_b32_e32 v75, v86
	v_lshl_add_u64 v[82:83], v[150:151], 1, v[82:83]
	v_cvt_pk_bf16_f32 v81, v76, v77
	v_pk_mul_f32 v[84:85], v[72:73], v[74:75]
	v_pk_mul_f32 v[90:91], v[70:71], v[86:87]
	v_pk_mul_f32 v[88:89], v[68:69], v[74:75]
	v_pk_mul_f32 v[86:87], v[66:67], v[86:87]
	s_and_b64 vcc, exec, s[44:45]
	s_mov_b64 s[16:17], -1
	global_store_dwordx4 v[82:83], v[78:81], off sc0 sc1
	s_cbranch_vccz .LBB0_241
	s_andn2_b64 vcc, exec, s[16:17]
	s_cbranch_vccz .LBB0_242

; __device__ __forceinline__ unsigned cvtpk(float lo, float hi) { f32x2 v = {lo, hi}; bf16x2_t b = __builtin_convertvector(v, bf16x2_t); return __builtin_bit_cast(unsigned, b); }
;     __device__ __forceinline__ void operator()(AccRef acc, const Unit& u, int wr, int wc, int fr, int fq) const {
;     ...
;                 const int row = row0 + ai * 128 + m * 16;
;                 const float rs = rsqrtf(ssq_sum<4>(ssqx + (size_t)row * 4) * (1.0f / DM) + EPS);
;                 bf16_t* rowp = O + (size_t)row * NPROJ + col0;
; #pragma unroll
;                 for (int bj = 0; bj < 2; ++bj) {
;                     f32x4 v0 = acc[ai][bj][m][0] * rs, v1 = acc[ai][bj][m][1] * rs;
;                     if (u.pn == 6 || (u.pn == 7 && bj == 0)) {
;                         float s = (v0[0] * v0[0] + v0[1] * v0[1]) + (v0[2] * v0[2] + v0[3] * v0[3]) + (v1[0] * v1[0] + v1[1] * v1[1]) + (v1[2] * v1[2] + v1[3] * v1[3]);
;                         s += __shfl_xor(s, 16); s += __shfl_xor(s, 32);
;                         if (fq == 0) { if (u.pn == 6) ssqq[(size_t)row * 8 + bj * 4 + wc] = s; else ssqkv[(size_t)row * 4 + wc] = s; }
;                     }
;                     if (u.pn == 7 && bj == 1 && wc == 0) { const int pos = row & (SEQ - 1); rope8(v0, v1, cost + pos * 16, sint + pos * 16, fq); }
;                     u32x4 w; w.x = cvtpk(v0[0], v0[1]); w.y = cvtpk(v0[2], v0[3]); w.z = cvtpk(v1[0], v1[1]); w.w = cvtpk(v1[2], v1[3]);
;                     st16_wt(rowp + bj * 128, w);
.LBB0_198:
	s_waitcnt lgkmcnt(0)
	v_cvt_pk_bf16_f32 v66, v90, v91
	v_cvt_pk_bf16_f32 v67, v84, v85
	v_cvt_pk_bf16_f32 v68, v86, v87
	v_cvt_pk_bf16_f32 v69, v88, v89
	v_add_u32_e32 v76, 0x80, v148
	global_store_dwordx4 v[82:83], v[66:69], off offset:256 sc0 sc1
	v_ashrrev_i32_e32 v77, 31, v76
	s_and_b64 vcc, exec, s[48:49]
	v_and_b32_e32 v66, 0xff, v76
	v_lshlrev_b32_e32 v66, 4, v66
	v_add_u32_e32 v66, 0x21400, v66
	ds_read_b128 v[66:69], v66
	v_lshlrev_b64 v[78:79], 5, v[76:77]
	s_waitcnt lgkmcnt(0)
	v_mov_b32_e32 v70, v67
	v_mov_b32_e32 v71, v68
	v_mov_b32_e32 v67, v69
	v_pk_add_f32 v[66:67], v[70:71], v[66:67]
	s_nop 0
	v_add_f32_e32 v0, v66, v67
	v_add_f32_e32 v0, 0, v0
	v_fmamk_f32 v0, v0, 0x3a800000, v212
	v_mul_f32_e32 v66, 0x4b800000, v0
	v_cmp_gt_f32_e64 s[50:51], s69, v0
	s_nop 1
	v_cndmask_b32_e64 v0, v0, v66, s[50:51]
	v_rsq_f32_e32 v0, v0
	s_nop 0
	v_mul_f32_e32 v66, 0x45800000, v0
	v_cndmask_b32_e64 v70, v0, v66, s[50:51]
	v_pk_mul_f32 v[64:65], v[64:65], v[70:71] op_sel_hi:[1,0]
	v_pk_mul_f32 v[62:63], v[62:63], v[70:71] op_sel_hi:[1,0]
	v_pk_mul_f32 v[60:61], v[60:61], v[70:71] op_sel_hi:[1,0]
	v_pk_mul_f32 v[58:59], v[58:59], v[70:71] op_sel_hi:[1,0]
	s_cbranch_vccnz .LBB0_202
	v_mul_f32_e32 v0, v63, v63
	v_mul_f32_e32 v66, v65, v65
	v_fmac_f32_e32 v0, v62, v62
	v_fmac_f32_e32 v66, v64, v64
	v_add_f32_e32 v0, v0, v66
	v_mul_f32_e32 v66, v59, v59
	v_fmac_f32_e32 v66, v58, v58
	v_add_f32_e32 v0, v66, v0
	v_mul_f32_e32 v66, v61, v61
	v_fmac_f32_e32 v66, v60, v60
	v_and_b32_e32 v67, 64, v213
	v_add_f32_e32 v0, v66, v0
	v_xor_b32_e32 v66, 16, v213
	v_add_u32_e32 v67, 64, v67
	v_cmp_lt_i32_e32 vcc, v66, v67
	s_nop 1
	v_cndmask_b32_e32 v66, v213, v66, vcc
	v_lshlrev_b32_e32 v66, 2, v66
	ds_bpermute_b32 v66, v66, v0
	s_waitcnt lgkmcnt(0)
	v_add_f32_e32 v0, v0, v66
	v_xor_b32_e32 v66, 32, v213
	v_cmp_lt_i32_e32 vcc, v66, v67
	s_nop 1
	v_cndmask_b32_e32 v66, v213, v66, vcc
	v_lshlrev_b32_e32 v66, 2, v66
	ds_bpermute_b32 v66, v66, v0
	s_and_saveexec_b64 s[16:17], s[38:39]
	s_cbranch_execz .LBB0_201
	v_lshlrev_b64 v[68:69], 2, v[76:77]
	v_lshl_add_u64 v[72:73], s[78:79], 0, v[78:79]
	v_lshl_add_u64 v[68:69], v[68:69], 2, s[88:89]
	v_cndmask_b32_e64 v69, v69, v73, s[42:43]
	v_cndmask_b32_e64 v68, v68, v72, s[42:43]
	s_lshl_b32 s72, s4, 2
	v_lshl_add_u64 v[68:69], v[68:69], 0, s[72:73]
	s_waitcnt lgkmcnt(0)
	v_add_f32_e32 v0, v0, v66
	global_store_dword v[68:69], v0, off

; __device__ __forceinline__ unsigned cvtpk(float lo, float hi) { f32x2 v = {lo, hi}; bf16x2_t b = __builtin_convertvector(v, bf16x2_t); return __builtin_bit_cast(unsigned, b); }
;     __device__ __forceinline__ void operator()(AccRef acc, const Unit& u, int wr, int wc, int fr, int fq) const {
;     ...
;                     f32x4 v0 = acc[ai][bj][m][0] * rs, v1 = acc[ai][bj][m][1] * rs;
;                     if (u.pn == 6 || (u.pn == 7 && bj == 0)) {
;                         float s = (v0[0] * v0[0] + v0[1] * v0[1]) + (v0[2] * v0[2] + v0[3] * v0[3]) + (v1[0] * v1[0] + v1[1] * v1[1]) + (v1[2] * v1[2] + v1[3] * v1[3]);
;                         s += __shfl_xor(s, 16); s += __shfl_xor(s, 32);
;                         if (fq == 0) { if (u.pn == 6) ssqq[(size_t)row * 8 + bj * 4 + wc] = s; else ssqkv[(size_t)row * 4 + wc] = s; }
;                     }
;                     if (u.pn == 7 && bj == 1 && wc == 0) { const int pos = row & (SEQ - 1); rope8(v0, v1, cost + pos * 16, sint + pos * 16, fq); }
;                     u32x4 w; w.x = cvtpk(v0[0], v0[1]); w.y = cvtpk(v0[2], v0[3]); w.z = cvtpk(v1[0], v1[1]); w.w = cvtpk(v1[2], v1[3]);
;                     st16_wt(rowp + bj * 128, w);
.LBB0_202:
	s_waitcnt lgkmcnt(0)
	v_mov_b64_e32 v[66:67], s[90:91]
	v_mov_b32_e32 v71, v70
	v_mad_i64_i32 v[66:67], s[16:17], v76, s27, v[66:67]
	v_cvt_pk_bf16_f32 v62, v62, v63
	v_cvt_pk_bf16_f32 v63, v64, v65
	v_cvt_pk_bf16_f32 v64, v58, v59
	v_mov_b32_e32 v58, v70
	v_mov_b32_e32 v59, v70
	v_lshl_add_u64 v[66:67], v[150:151], 1, v[66:67]
	v_cvt_pk_bf16_f32 v65, v60, v61
	v_pk_mul_f32 v[68:69], v[56:57], v[58:59]
	v_pk_mul_f32 v[74:75], v[54:55], v[70:71]
	v_pk_mul_f32 v[72:73], v[52:53], v[58:59]
	v_pk_mul_f32 v[70:71], v[50:51], v[70:71]
	s_and_b64 vcc, exec, s[44:45]
	s_mov_b64 s[16:17], -1
	global_store_dwordx4 v[66:67], v[62:65], off sc0 sc1
	s_cbranch_vccz .LBB0_245
	s_andn2_b64 vcc, exec, s[16:17]
	s_cbranch_vccz .LBB0_246

; __device__ __forceinline__ unsigned cvtpk(float lo, float hi) { f32x2 v = {lo, hi}; bf16x2_t b = __builtin_convertvector(v, bf16x2_t); return __builtin_bit_cast(unsigned, b); }
;     __device__ __forceinline__ void operator()(AccRef acc, const Unit& u, int wr, int wc, int fr, int fq) const {
;     ...
;                 const int row = row0 + ai * 128 + m * 16;
;                 const float rs = rsqrtf(ssq_sum<4>(ssqx + (size_t)row * 4) * (1.0f / DM) + EPS);
;                 bf16_t* rowp = O + (size_t)row * NPROJ + col0;
; #pragma unroll
;                 for (int bj = 0; bj < 2; ++bj) {
;                     f32x4 v0 = acc[ai][bj][m][0] * rs, v1 = acc[ai][bj][m][1] * rs;
;                     if (u.pn == 6 || (u.pn == 7 && bj == 0)) {
;                         float s = (v0[0] * v0[0] + v0[1] * v0[1]) + (v0[2] * v0[2] + v0[3] * v0[3]) + (v1[0] * v1[0] + v1[1] * v1[1]) + (v1[2] * v1[2] + v1[3] * v1[3]);
;                         s += __shfl_xor(s, 16); s += __shfl_xor(s, 32);
;                         if (fq == 0) { if (u.pn == 6) ssqq[(size_t)row * 8 + bj * 4 + wc] = s; else ssqkv[(size_t)row * 4 + wc] = s; }
;                     }
;                     if (u.pn == 7 && bj == 1 && wc == 0) { const int pos = row & (SEQ - 1); rope8(v0, v1, cost + pos * 16, sint + pos * 16, fq); }
;                     u32x4 w; w.x = cvtpk(v0[0], v0[1]); w.y = cvtpk(v0[2], v0[3]); w.z = cvtpk(v1[0], v1[1]); w.w = cvtpk(v1[2], v1[3]);
;                     st16_wt(rowp + bj * 128, w);
.LBB0_206:
	s_waitcnt lgkmcnt(0)
	v_cvt_pk_bf16_f32 v50, v74, v75
	v_cvt_pk_bf16_f32 v51, v68, v69
	v_cvt_pk_bf16_f32 v52, v70, v71
	v_cvt_pk_bf16_f32 v53, v72, v73
	v_add_u32_e32 v60, 0x90, v148
	global_store_dwordx4 v[66:67], v[50:53], off offset:256 sc0 sc1
	v_ashrrev_i32_e32 v61, 31, v60
	s_and_b64 vcc, exec, s[48:49]
	v_and_b32_e32 v50, 0xff, v60
	v_lshlrev_b32_e32 v50, 4, v50
	v_add_u32_e32 v50, 0x21400, v50
	ds_read_b128 v[50:53], v50
	v_lshlrev_b64 v[62:63], 5, v[60:61]
	s_waitcnt lgkmcnt(0)
	v_mov_b32_e32 v54, v51
	v_mov_b32_e32 v55, v52
	v_mov_b32_e32 v51, v53
	v_pk_add_f32 v[50:51], v[54:55], v[50:51]
	s_nop 0
	v_add_f32_e32 v0, v50, v51
	v_add_f32_e32 v0, 0, v0
	v_fmamk_f32 v0, v0, 0x3a800000, v212
	v_mul_f32_e32 v50, 0x4b800000, v0
	v_cmp_gt_f32_e64 s[50:51], s69, v0
	s_nop 1
	v_cndmask_b32_e64 v0, v0, v50, s[50:51]
	v_rsq_f32_e32 v0, v0
	s_nop 0
	v_mul_f32_e32 v50, 0x45800000, v0
	v_cndmask_b32_e64 v54, v0, v50, s[50:51]
	v_pk_mul_f32 v[48:49], v[48:49], v[54:55] op_sel_hi:[1,0]
	v_pk_mul_f32 v[46:47], v[46:47], v[54:55] op_sel_hi:[1,0]
	v_pk_mul_f32 v[44:45], v[44:45], v[54:55] op_sel_hi:[1,0]
	v_pk_mul_f32 v[42:43], v[42:43], v[54:55] op_sel_hi:[1,0]
	s_cbranch_vccnz .LBB0_210
	v_mul_f32_e32 v0, v47, v47
	v_mul_f32_e32 v50, v49, v49
	v_fmac_f32_e32 v0, v46, v46
	v_fmac_f32_e32 v50, v48, v48
	v_add_f32_e32 v0, v0, v50
	v_mul_f32_e32 v50, v43, v43
	v_fmac_f32_e32 v50, v42, v42
	v_add_f32_e32 v0, v50, v0
	v_mul_f32_e32 v50, v45, v45
	v_fmac_f32_e32 v50, v44, v44
	v_and_b32_e32 v51, 64, v213
	v_add_f32_e32 v0, v50, v0
	v_xor_b32_e32 v50, 16, v213
	v_add_u32_e32 v51, 64, v51
	v_cmp_lt_i32_e32 vcc, v50, v51
	s_nop 1
	v_cndmask_b32_e32 v50, v213, v50, vcc
	v_lshlrev_b32_e32 v50, 2, v50
	ds_bpermute_b32 v50, v50, v0
	s_waitcnt lgkmcnt(0)
	v_add_f32_e32 v0, v0, v50
	v_xor_b32_e32 v50, 32, v213
	v_cmp_lt_i32_e32 vcc, v50, v51
	s_nop 1
	v_cndmask_b32_e32 v50, v213, v50, vcc
	v_lshlrev_b32_e32 v50, 2, v50
	ds_bpermute_b32 v50, v50, v0
	s_and_saveexec_b64 s[16:17], s[38:39]
	s_cbranch_execz .LBB0_209
	v_lshlrev_b64 v[52:53], 2, v[60:61]
	v_lshl_add_u64 v[56:57], s[78:79], 0, v[62:63]
	v_lshl_add_u64 v[52:53], v[52:53], 2, s[88:89]
	v_cndmask_b32_e64 v53, v53, v57, s[42:43]
	v_cndmask_b32_e64 v52, v52, v56, s[42:43]
	s_lshl_b32 s72, s4, 2
	v_lshl_add_u64 v[52:53], v[52:53], 0, s[72:73]
	s_waitcnt lgkmcnt(0)
	v_add_f32_e32 v0, v0, v50
	global_store_dword v[52:53], v0, off

; __device__ __forceinline__ unsigned cvtpk(float lo, float hi) { f32x2 v = {lo, hi}; bf16x2_t b = __builtin_convertvector(v, bf16x2_t); return __builtin_bit_cast(unsigned, b); }
;     __device__ __forceinline__ void operator()(AccRef acc, const Unit& u, int wr, int wc, int fr, int fq) const {
;     ...
;                     f32x4 v0 = acc[ai][bj][m][0] * rs, v1 = acc[ai][bj][m][1] * rs;
;                     if (u.pn == 6 || (u.pn == 7 && bj == 0)) {
;                         float s = (v0[0] * v0[0] + v0[1] * v0[1]) + (v0[2] * v0[2] + v0[3] * v0[3]) + (v1[0] * v1[0] + v1[1] * v1[1]) + (v1[2] * v1[2] + v1[3] * v1[3]);
;                         s += __shfl_xor(s, 16); s += __shfl_xor(s, 32);
;                         if (fq == 0) { if (u.pn == 6) ssqq[(size_t)row * 8 + bj * 4 + wc] = s; else ssqkv[(size_t)row * 4 + wc] = s; }
;                     }
;                     if (u.pn == 7 && bj == 1 && wc == 0) { const int pos = row & (SEQ - 1); rope8(v0, v1, cost + pos * 16, sint + pos * 16, fq); }
;                     u32x4 w; w.x = cvtpk(v0[0], v0[1]); w.y = cvtpk(v0[2], v0[3]); w.z = cvtpk(v1[0], v1[1]); w.w = cvtpk(v1[2], v1[3]);
;                     st16_wt(rowp + bj * 128, w);
.LBB0_210:
	s_waitcnt lgkmcnt(0)
	v_mov_b64_e32 v[50:51], s[90:91]
	v_mov_b32_e32 v55, v54
	v_mad_i64_i32 v[50:51], s[16:17], v60, s27, v[50:51]
	v_cvt_pk_bf16_f32 v46, v46, v47
	v_cvt_pk_bf16_f32 v47, v48, v49
	v_cvt_pk_bf16_f32 v48, v42, v43
	v_mov_b32_e32 v42, v54
	v_mov_b32_e32 v43, v54
	v_lshl_add_u64 v[50:51], v[150:151], 1, v[50:51]
	v_cvt_pk_bf16_f32 v49, v44, v45
	v_pk_mul_f32 v[52:53], v[40:41], v[42:43]
	v_pk_mul_f32 v[58:59], v[38:39], v[54:55]
	v_pk_mul_f32 v[56:57], v[36:37], v[42:43]
	v_pk_mul_f32 v[54:55], v[34:35], v[54:55]
	s_and_b64 vcc, exec, s[44:45]
	s_mov_b64 s[16:17], -1
	global_store_dwordx4 v[50:51], v[46:49], off sc0 sc1
	s_cbranch_vccz .LBB0_249
	s_andn2_b64 vcc, exec, s[16:17]
	s_cbranch_vccz .LBB0_250

; __device__ __forceinline__ unsigned cvtpk(float lo, float hi) { f32x2 v = {lo, hi}; bf16x2_t b = __builtin_convertvector(v, bf16x2_t); return __builtin_bit_cast(unsigned, b); }
;     __device__ __forceinline__ void operator()(AccRef acc, const Unit& u, int wr, int wc, int fr, int fq) const {
;     ...
;                 const int row = row0 + ai * 128 + m * 16;
;                 const float rs = rsqrtf(ssq_sum<4>(ssqx + (size_t)row * 4) * (1.0f / DM) + EPS);
;                 bf16_t* rowp = O + (size_t)row * NPROJ + col0;
; #pragma unroll
;                 for (int bj = 0; bj < 2; ++bj) {
;                     f32x4 v0 = acc[ai][bj][m][0] * rs, v1 = acc[ai][bj][m][1] * rs;
;                     if (u.pn == 6 || (u.pn == 7 && bj == 0)) {
;                         float s = (v0[0] * v0[0] + v0[1] * v0[1]) + (v0[2] * v0[2] + v0[3] * v0[3]) + (v1[0] * v1[0] + v1[1] * v1[1]) + (v1[2] * v1[2] + v1[3] * v1[3]);
;                         s += __shfl_xor(s, 16); s += __shfl_xor(s, 32);
;                         if (fq == 0) { if (u.pn == 6) ssqq[(size_t)row * 8 + bj * 4 + wc] = s; else ssqkv[(size_t)row * 4 + wc] = s; }
;                     }
;                     if (u.pn == 7 && bj == 1 && wc == 0) { const int pos = row & (SEQ - 1); rope8(v0, v1, cost + pos * 16, sint + pos * 16, fq); }
;                     u32x4 w; w.x = cvtpk(v0[0], v0[1]); w.y = cvtpk(v0[2], v0[3]); w.z = cvtpk(v1[0], v1[1]); w.w = cvtpk(v1[2], v1[3]);
;                     st16_wt(rowp + bj * 128, w);
.LBB0_214:
	s_waitcnt lgkmcnt(0)
	v_cvt_pk_bf16_f32 v34, v58, v59
	v_cvt_pk_bf16_f32 v35, v52, v53
	v_cvt_pk_bf16_f32 v36, v54, v55
	v_cvt_pk_bf16_f32 v37, v56, v57
	v_add_u32_e32 v44, 0xa0, v148
	global_store_dwordx4 v[50:51], v[34:37], off offset:256 sc0 sc1
	v_ashrrev_i32_e32 v45, 31, v44
	s_and_b64 vcc, exec, s[48:49]
	v_and_b32_e32 v34, 0xff, v44
	v_lshlrev_b32_e32 v34, 4, v34
	v_add_u32_e32 v34, 0x21400, v34
	ds_read_b128 v[34:37], v34
	v_lshlrev_b64 v[46:47], 5, v[44:45]
	s_waitcnt lgkmcnt(0)
	v_mov_b32_e32 v38, v35
	v_mov_b32_e32 v39, v36
	v_mov_b32_e32 v35, v37
	v_pk_add_f32 v[34:35], v[38:39], v[34:35]
	s_nop 0
	v_add_f32_e32 v0, v34, v35
	v_add_f32_e32 v0, 0, v0
	v_fmamk_f32 v0, v0, 0x3a800000, v212
	v_mul_f32_e32 v34, 0x4b800000, v0
	v_cmp_gt_f32_e64 s[50:51], s69, v0
	s_nop 1
	v_cndmask_b32_e64 v0, v0, v34, s[50:51]
	v_rsq_f32_e32 v0, v0
	s_nop 0
	v_mul_f32_e32 v34, 0x45800000, v0
	v_cndmask_b32_e64 v38, v0, v34, s[50:51]
	v_pk_mul_f32 v[32:33], v[32:33], v[38:39] op_sel_hi:[1,0]
	v_pk_mul_f32 v[30:31], v[30:31], v[38:39] op_sel_hi:[1,0]
	v_pk_mul_f32 v[28:29], v[28:29], v[38:39] op_sel_hi:[1,0]
	v_pk_mul_f32 v[26:27], v[26:27], v[38:39] op_sel_hi:[1,0]
	s_cbranch_vccnz .LBB0_218
	v_mul_f32_e32 v0, v31, v31
	v_mul_f32_e32 v34, v33, v33
	v_fmac_f32_e32 v0, v30, v30
	v_fmac_f32_e32 v34, v32, v32
	v_add_f32_e32 v0, v0, v34
	v_mul_f32_e32 v34, v27, v27
	v_fmac_f32_e32 v34, v26, v26
	v_add_f32_e32 v0, v34, v0
	v_mul_f32_e32 v34, v29, v29
	v_fmac_f32_e32 v34, v28, v28
	v_and_b32_e32 v35, 64, v213
	v_add_f32_e32 v0, v34, v0
	v_xor_b32_e32 v34, 16, v213
	v_add_u32_e32 v35, 64, v35
	v_cmp_lt_i32_e32 vcc, v34, v35
	s_nop 1
	v_cndmask_b32_e32 v34, v213, v34, vcc
	v_lshlrev_b32_e32 v34, 2, v34
	ds_bpermute_b32 v34, v34, v0
	s_waitcnt lgkmcnt(0)
	v_add_f32_e32 v0, v0, v34
	v_xor_b32_e32 v34, 32, v213
	v_cmp_lt_i32_e32 vcc, v34, v35
	s_nop 1
	v_cndmask_b32_e32 v34, v213, v34, vcc
	v_lshlrev_b32_e32 v34, 2, v34
	ds_bpermute_b32 v34, v34, v0
	s_and_saveexec_b64 s[16:17], s[38:39]
	s_cbranch_execz .LBB0_217
	v_lshlrev_b64 v[36:37], 2, v[44:45]
	v_lshl_add_u64 v[40:41], s[78:79], 0, v[46:47]
	v_lshl_add_u64 v[36:37], v[36:37], 2, s[88:89]
	v_cndmask_b32_e64 v37, v37, v41, s[42:43]
	v_cndmask_b32_e64 v36, v36, v40, s[42:43]
	s_lshl_b32 s72, s4, 2
	v_lshl_add_u64 v[36:37], v[36:37], 0, s[72:73]
	s_waitcnt lgkmcnt(0)
	v_add_f32_e32 v0, v0, v34
	global_store_dword v[36:37], v0, off

; __device__ __forceinline__ unsigned cvtpk(float lo, float hi) { f32x2 v = {lo, hi}; bf16x2_t b = __builtin_convertvector(v, bf16x2_t); return __builtin_bit_cast(unsigned, b); }
;     __device__ __forceinline__ void operator()(AccRef acc, const Unit& u, int wr, int wc, int fr, int fq) const {
;     ...
;                     f32x4 v0 = acc[ai][bj][m][0] * rs, v1 = acc[ai][bj][m][1] * rs;
;                     if (u.pn == 6 || (u.pn == 7 && bj == 0)) {
;                         float s = (v0[0] * v0[0] + v0[1] * v0[1]) + (v0[2] * v0[2] + v0[3] * v0[3]) + (v1[0] * v1[0] + v1[1] * v1[1]) + (v1[2] * v1[2] + v1[3] * v1[3]);
;                         s += __shfl_xor(s, 16); s += __shfl_xor(s, 32);
;                         if (fq == 0) { if (u.pn == 6) ssqq[(size_t)row * 8 + bj * 4 + wc] = s; else ssqkv[(size_t)row * 4 + wc] = s; }
;                     }
;                     if (u.pn == 7 && bj == 1 && wc == 0) { const int pos = row & (SEQ - 1); rope8(v0, v1, cost + pos * 16, sint + pos * 16, fq); }
;                     u32x4 w; w.x = cvtpk(v0[0], v0[1]); w.y = cvtpk(v0[2], v0[3]); w.z = cvtpk(v1[0], v1[1]); w.w = cvtpk(v1[2], v1[3]);
;                     st16_wt(rowp + bj * 128, w);
.LBB0_218:
	s_waitcnt lgkmcnt(0)
	v_mov_b64_e32 v[34:35], s[90:91]
	v_mov_b32_e32 v39, v38
	v_mad_i64_i32 v[34:35], s[16:17], v44, s27, v[34:35]
	v_cvt_pk_bf16_f32 v30, v30, v31
	v_cvt_pk_bf16_f32 v31, v32, v33
	v_cvt_pk_bf16_f32 v32, v26, v27
	v_mov_b32_e32 v26, v38
	v_mov_b32_e32 v27, v38
	v_lshl_add_u64 v[34:35], v[150:151], 1, v[34:35]
	v_cvt_pk_bf16_f32 v33, v28, v29
	v_pk_mul_f32 v[36:37], v[24:25], v[26:27]
	v_pk_mul_f32 v[42:43], v[22:23], v[38:39]
	v_pk_mul_f32 v[40:41], v[20:21], v[26:27]
	v_pk_mul_f32 v[38:39], v[18:19], v[38:39]
	s_and_b64 vcc, exec, s[44:45]
	s_mov_b64 s[16:17], -1
	global_store_dwordx4 v[34:35], v[30:33], off sc0 sc1
	s_cbranch_vccz .LBB0_253
	s_andn2_b64 vcc, exec, s[16:17]
	s_cbranch_vccz .LBB0_254

; __device__ __forceinline__ unsigned cvtpk(float lo, float hi) { f32x2 v = {lo, hi}; bf16x2_t b = __builtin_convertvector(v, bf16x2_t); return __builtin_bit_cast(unsigned, b); }
;     __device__ __forceinline__ void operator()(AccRef acc, const Unit& u, int wr, int wc, int fr, int fq) const {
;     ...
;                 const int row = row0 + ai * 128 + m * 16;
;                 const float rs = rsqrtf(ssq_sum<4>(ssqx + (size_t)row * 4) * (1.0f / DM) + EPS);
;                 bf16_t* rowp = O + (size_t)row * NPROJ + col0;
; #pragma unroll
;                 for (int bj = 0; bj < 2; ++bj) {
;                     f32x4 v0 = acc[ai][bj][m][0] * rs, v1 = acc[ai][bj][m][1] * rs;
;                     if (u.pn == 6 || (u.pn == 7 && bj == 0)) {
;                         float s = (v0[0] * v0[0] + v0[1] * v0[1]) + (v0[2] * v0[2] + v0[3] * v0[3]) + (v1[0] * v1[0] + v1[1] * v1[1]) + (v1[2] * v1[2] + v1[3] * v1[3]);
;                         s += __shfl_xor(s, 16); s += __shfl_xor(s, 32);
;                         if (fq == 0) { if (u.pn == 6) ssqq[(size_t)row * 8 + bj * 4 + wc] = s; else ssqkv[(size_t)row * 4 + wc] = s; }
;                     }
;                     if (u.pn == 7 && bj == 1 && wc == 0) { const int pos = row & (SEQ - 1); rope8(v0, v1, cost + pos * 16, sint + pos * 16, fq); }
;                     u32x4 w; w.x = cvtpk(v0[0], v0[1]); w.y = cvtpk(v0[2], v0[3]); w.z = cvtpk(v1[0], v1[1]); w.w = cvtpk(v1[2], v1[3]);
;                     st16_wt(rowp + bj * 128, w);
.LBB0_222:
	s_waitcnt lgkmcnt(0)
	v_cvt_pk_bf16_f32 v18, v42, v43
	v_cvt_pk_bf16_f32 v19, v36, v37
	v_cvt_pk_bf16_f32 v20, v38, v39
	v_cvt_pk_bf16_f32 v21, v40, v41
	v_add_u32_e32 v28, 0xb0, v148
	global_store_dwordx4 v[34:35], v[18:21], off offset:256 sc0 sc1
	v_ashrrev_i32_e32 v29, 31, v28
	s_and_b64 vcc, exec, s[48:49]
	v_and_b32_e32 v18, 0xff, v28
	v_lshlrev_b32_e32 v18, 4, v18
	v_add_u32_e32 v18, 0x21400, v18
	ds_read_b128 v[18:21], v18
	v_lshlrev_b64 v[30:31], 5, v[28:29]
	s_waitcnt lgkmcnt(0)
	v_mov_b32_e32 v22, v19
	v_mov_b32_e32 v23, v20
	v_mov_b32_e32 v19, v21
	v_pk_add_f32 v[18:19], v[22:23], v[18:19]
	s_nop 0
	v_add_f32_e32 v0, v18, v19
	v_add_f32_e32 v0, 0, v0
	v_fmamk_f32 v0, v0, 0x3a800000, v212
	v_mul_f32_e32 v18, 0x4b800000, v0
	v_cmp_gt_f32_e64 s[50:51], s69, v0
	s_nop 1
	v_cndmask_b32_e64 v0, v0, v18, s[50:51]
	v_rsq_f32_e32 v0, v0
	s_nop 0
	v_mul_f32_e32 v18, 0x45800000, v0
	v_cndmask_b32_e64 v22, v0, v18, s[50:51]
	v_pk_mul_f32 v[16:17], v[16:17], v[22:23] op_sel_hi:[1,0]
	v_pk_mul_f32 v[14:15], v[14:15], v[22:23] op_sel_hi:[1,0]
	v_pk_mul_f32 v[12:13], v[12:13], v[22:23] op_sel_hi:[1,0]
	v_pk_mul_f32 v[10:11], v[10:11], v[22:23] op_sel_hi:[1,0]
	s_cbranch_vccnz .LBB0_226
	v_mul_f32_e32 v0, v15, v15
	v_mul_f32_e32 v18, v17, v17
	v_fmac_f32_e32 v0, v14, v14
	v_fmac_f32_e32 v18, v16, v16
	v_add_f32_e32 v0, v0, v18
	v_mul_f32_e32 v18, v11, v11
	v_fmac_f32_e32 v18, v10, v10
	v_add_f32_e32 v0, v18, v0
	v_mul_f32_e32 v18, v13, v13
	v_fmac_f32_e32 v18, v12, v12
	v_and_b32_e32 v19, 64, v213
	v_add_f32_e32 v0, v18, v0
	v_xor_b32_e32 v18, 16, v213
	v_add_u32_e32 v19, 64, v19
	v_cmp_lt_i32_e32 vcc, v18, v19
	s_nop 1
	v_cndmask_b32_e32 v18, v213, v18, vcc
	v_lshlrev_b32_e32 v18, 2, v18
	ds_bpermute_b32 v18, v18, v0
	s_waitcnt lgkmcnt(0)
	v_add_f32_e32 v0, v0, v18
	v_xor_b32_e32 v18, 32, v213
	v_cmp_lt_i32_e32 vcc, v18, v19
	s_nop 1
	v_cndmask_b32_e32 v18, v213, v18, vcc
	v_lshlrev_b32_e32 v18, 2, v18
	ds_bpermute_b32 v18, v18, v0
	s_and_saveexec_b64 s[16:17], s[38:39]
	s_cbranch_execz .LBB0_225
	v_lshlrev_b64 v[20:21], 2, v[28:29]
	v_lshl_add_u64 v[24:25], s[78:79], 0, v[30:31]
	v_lshl_add_u64 v[20:21], v[20:21], 2, s[88:89]
	v_cndmask_b32_e64 v21, v21, v25, s[42:43]
	v_cndmask_b32_e64 v20, v20, v24, s[42:43]
	s_lshl_b32 s72, s4, 2
	v_lshl_add_u64 v[20:21], v[20:21], 0, s[72:73]
	s_waitcnt lgkmcnt(0)
	v_add_f32_e32 v0, v0, v18
	global_store_dword v[20:21], v0, off

; __device__ __forceinline__ unsigned cvtpk(float lo, float hi) { f32x2 v = {lo, hi}; bf16x2_t b = __builtin_convertvector(v, bf16x2_t); return __builtin_bit_cast(unsigned, b); }
;     __device__ __forceinline__ void operator()(AccRef acc, const Unit& u, int wr, int wc, int fr, int fq) const {
;     ...
;                     f32x4 v0 = acc[ai][bj][m][0] * rs, v1 = acc[ai][bj][m][1] * rs;
;                     if (u.pn == 6 || (u.pn == 7 && bj == 0)) {
;                         float s = (v0[0] * v0[0] + v0[1] * v0[1]) + (v0[2] * v0[2] + v0[3] * v0[3]) + (v1[0] * v1[0] + v1[1] * v1[1]) + (v1[2] * v1[2] + v1[3] * v1[3]);
;                         s += __shfl_xor(s, 16); s += __shfl_xor(s, 32);
;                         if (fq == 0) { if (u.pn == 6) ssqq[(size_t)row * 8 + bj * 4 + wc] = s; else ssqkv[(size_t)row * 4 + wc] = s; }
;                     }
;                     if (u.pn == 7 && bj == 1 && wc == 0) { const int pos = row & (SEQ - 1); rope8(v0, v1, cost + pos * 16, sint + pos * 16, fq); }
;                     u32x4 w; w.x = cvtpk(v0[0], v0[1]); w.y = cvtpk(v0[2], v0[3]); w.z = cvtpk(v1[0], v1[1]); w.w = cvtpk(v1[2], v1[3]);
;                     st16_wt(rowp + bj * 128, w);
.LBB0_226:
	s_waitcnt lgkmcnt(0)
	v_mov_b64_e32 v[18:19], s[90:91]
	v_mov_b32_e32 v23, v22
	v_mad_i64_i32 v[18:19], s[16:17], v28, s27, v[18:19]
	v_cvt_pk_bf16_f32 v14, v14, v15
	v_cvt_pk_bf16_f32 v15, v16, v17
	v_cvt_pk_bf16_f32 v16, v10, v11
	v_mov_b32_e32 v10, v22
	v_mov_b32_e32 v11, v22
	v_lshl_add_u64 v[18:19], v[150:151], 1, v[18:19]
	v_cvt_pk_bf16_f32 v17, v12, v13
	v_pk_mul_f32 v[20:21], v[8:9], v[10:11]
	v_pk_mul_f32 v[26:27], v[6:7], v[22:23]
	v_pk_mul_f32 v[24:25], v[4:5], v[10:11]
	v_pk_mul_f32 v[22:23], v[2:3], v[22:23]
	s_and_b64 vcc, exec, s[44:45]
	s_mov_b64 s[16:17], -1
	global_store_dwordx4 v[18:19], v[14:17], off sc0 sc1
	s_cbranch_vccz .LBB0_257
	s_andn2_b64 vcc, exec, s[16:17]
	s_cbranch_vccz .LBB0_258

; __device__ __forceinline__ unsigned cvtpk(float lo, float hi) { f32x2 v = {lo, hi}; bf16x2_t b = __builtin_convertvector(v, bf16x2_t); return __builtin_bit_cast(unsigned, b); }
;     __device__ __forceinline__ void operator()(AccRef acc, const Unit& u, int wr, int wc, int fr, int fq) const {
;     ...
;                     if (u.pn == 7 && bj == 1 && wc == 0) { const int pos = row & (SEQ - 1); rope8(v0, v1, cost + pos * 16, sint + pos * 16, fq); }
;                     u32x4 w; w.x = cvtpk(v0[0], v0[1]); w.y = cvtpk(v0[2], v0[3]); w.z = cvtpk(v1[0], v1[1]); w.w = cvtpk(v1[2], v1[3]);
;                     st16_wt(rowp + bj * 128, w);
.LBB0_230:
	s_waitcnt lgkmcnt(0)
	v_cvt_pk_bf16_f32 v2, v26, v27
	v_cvt_pk_bf16_f32 v3, v20, v21
	v_cvt_pk_bf16_f32 v4, v22, v23
	v_cvt_pk_bf16_f32 v5, v24, v25
	global_store_dwordx4 v[18:19], v[2:5], off offset:256 sc0 sc1
	s_and_b64 vcc, exec, s[40:41]
	s_mov_b64 s[16:17], -1
	s_cbranch_vccnz .LBB0_146
	s_andn2_b64 vcc, exec, s[80:81]
	s_cbranch_vccnz .LBB0_145
	s_barrier
	s_branch .LBB0_145

; __device__ __forceinline__ unsigned cvtpk(float lo, float hi) { f32x2 v = {lo, hi}; bf16x2_t b = __builtin_convertvector(v, bf16x2_t); return __builtin_bit_cast(unsigned, b); }
; __device__ __forceinline__ void rope8(f32x4& v0, f32x4& v1, const float* cosr, const float* sinr, int fq) {
;     const int j0 = 8 * (fq & 1);
;     const f32x4 c0 = *(const f32x4*)(cosr + j0), c1 = *(const f32x4*)(cosr + j0 + 4), s0 = *(const f32x4*)(sinr + j0), s1 = *(const f32x4*)(sinr + j0 + 4);
;     const float sg = (fq < 2) ? -1.f : 1.f;
; #pragma unroll
;     for (int i = 0; i < 4; ++i) {
;         const float p0 = __shfl_xor(v0[i], 32), p1 = __shfl_xor(v1[i], 32);
;         v0[i] = v0[i] * c0[i] + sg * p0 * s0[i]; v1[i] = v1[i] * c1[i] + sg * p1 * s1[i];
;     }
; }
;     __device__ __forceinline__ void operator()(AccRef acc, const Unit& u, int wr, int wc, int fr, int fq) const {
;     ...
;                 const int row = row0 + ai * 128 + m * 16;
;                 const float rs = rsqrtf(ssq_sum<NS>(ssq + (size_t)row * NS) * inv_n + EPS);
;                 bf16_t* rowp = O + (size_t)row * ldc + col0;
; #pragma unroll
;                 for (int bj = 0; bj < 2; ++bj) {
;                     f32x4 v0 = acc[ai][bj][m][0] * rs, v1 = acc[ai][bj][m][1] * rs;
;                     if (ROPE) { const int g32 = u.pn * 8 + bj * 4 + wc; if (g32 % 3 == 2) { const int pos = row & (SEQ - 1); rope8(v0, v1, cost + pos * 16, sint + pos * 16, fq); } }
;                     u32x4 w; w.x = cvtpk(v0[0], v0[1]); w.y = cvtpk(v0[2], v0[3]); w.z = cvtpk(v1[0], v1[1]); w.w = cvtpk(v1[2], v1[3]);
;                     st16_wt(rowp + bj * 128, w);
;                 }
.LBB0_333:
	v_lshl_or_b32 v130, s4, 8, v172
	v_mov_b64_e32 v[122:123], s[92:93]
	s_or_b32 s4, s5, 4
	v_mad_i64_i32 v[122:123], s[6:7], v156, s37, v[122:123]
	s_mul_hi_i32 s5, s4, 0x55555556
	s_lshr_b32 s6, s5, 31
	s_add_i32 s5, s5, s6
	v_ashrrev_i32_e32 v131, 31, v130
	s_mul_i32 s5, s5, 3
	v_lshl_add_u64 v[132:133], v[130:131], 1, v[122:123]
	v_cvt_pk_bf16_f32 v122, v166, v167
	v_cvt_pk_bf16_f32 v123, v162, v163
	v_cvt_pk_bf16_f32 v124, v160, v161
	v_cvt_pk_bf16_f32 v125, v164, v165
	s_sub_i32 s4, s4, s5
	v_mov_b32_e32 v159, v158
	global_store_dwordx4 v[132:133], v[122:125], off sc0 sc1
	s_cmp_eq_u32 s4, 2
	v_pk_mul_f32 v[162:163], v[118:119], v[158:159]
	v_mov_b32_e32 v122, v158
	v_mov_b32_e32 v123, v158
	v_pk_mul_f32 v[134:135], v[120:121], v[122:123]
	v_pk_mul_f32 v[160:161], v[116:117], v[122:123]
	s_cselect_b64 s[10:11], -1, 0
	s_cmp_lg_u32 s4, 2
	v_pk_mul_f32 v[136:137], v[114:115], v[158:159]
	s_cbranch_scc1 .LBB0_335
	v_lshl_add_u64 v[114:115], v[148:149], 0, v[0:1]
	global_load_dwordx4 v[122:125], v[114:115], off
	global_load_dwordx4 v[118:121], v[114:115], off offset:16
	v_lshl_add_u64 v[114:115], v[150:151], 0, v[0:1]
	global_load_dwordx4 v[126:129], v[114:115], off
	s_nop 0
	global_load_dwordx4 v[114:117], v[114:115], off offset:16
	v_and_b32_e32 v157, 64, v213
	v_xor_b32_e32 v0, 32, v213
	v_add_u32_e32 v157, 64, v157
	v_cmp_lt_i32_e32 vcc, v0, v157
	v_mov_b32_e32 v166, v136
	s_waitcnt vmcnt(0)
	v_pk_mul_f32 v[122:123], v[162:163], v[122:123]
	v_cndmask_b32_e32 v0, v213, v0, vcc
	v_lshlrev_b32_e32 v157, 2, v0
	ds_bpermute_b32 v0, v157, v136
	v_mov_b32_e32 v167, v114
	v_mov_b32_e32 v158, v118
	ds_bpermute_b32 v164, v157, v162
	ds_bpermute_b32 v165, v157, v163
	s_waitcnt lgkmcnt(0)
	v_mul_f32_e32 v159, v146, v0
	v_mul_f32_e32 v0, v114, v159
	v_pk_fma_f32 v[158:159], v[166:167], v[158:159], v[0:1] op_sel_hi:[1,1,0]
	ds_bpermute_b32 v0, v157, v137
	v_pk_mul_f32 v[162:163], v[146:147], v[164:165]
	v_mov_b32_e32 v114, v137
	v_mov_b32_e32 v164, v119
	v_mov_b32_e32 v166, v160
	s_waitcnt lgkmcnt(0)
	v_mul_f32_e32 v165, v146, v0
	v_mul_f32_e32 v0, v137, v119
	v_pk_fma_f32 v[136:137], v[114:115], v[164:165], v[0:1] op_sel_hi:[1,1,0]
	ds_bpermute_b32 v0, v157, v134
	ds_bpermute_b32 v115, v157, v160
	v_mov_b32_e32 v167, v116
	v_mov_b32_e32 v164, v120
	v_mul_f32_e32 v114, v134, v124
	s_waitcnt lgkmcnt(1)
	v_mul_f32_e32 v0, v146, v0
	s_waitcnt lgkmcnt(0)
	v_mul_f32_e32 v165, v146, v115
	v_mul_f32_e32 v118, v128, v0
	v_mul_f32_e32 v0, v116, v165
	v_pk_fma_f32 v[164:165], v[166:167], v[164:165], v[0:1] op_sel_hi:[1,1,0]
	ds_bpermute_b32 v0, v157, v135
	ds_bpermute_b32 v116, v157, v161
	v_mov_b32_e32 v128, v135
	v_mov_b32_e32 v166, v125
	v_pk_fma_f32 v[162:163], v[126:127], v[162:163], v[122:123]
	s_waitcnt lgkmcnt(1)
	v_mul_f32_e32 v167, v146, v0
	v_pk_mul_f32 v[124:125], v[128:129], v[166:167]
	v_mov_b32_e32 v136, v158
	v_mov_b32_e32 v115, v124
	v_mov_b32_e32 v119, v125
	v_pk_add_f32 v[134:135], v[114:115], v[118:119]
	s_waitcnt lgkmcnt(0)
	v_mul_f32_e32 v115, v146, v116
	v_mov_b32_e32 v116, v161
	v_mov_b32_e32 v114, v121
	v_mul_f32_e32 v0, v117, v115
	v_pk_fma_f32 v[114:115], v[116:117], v[114:115], v[0:1] op_sel_hi:[1,1,0]
	v_mov_b32_e32 v160, v164
	v_mov_b32_e32 v161, v114
.LBB0_335:
	v_or_b32_e32 v124, 16, v156
	v_cvt_pk_bf16_f32 v114, v162, v163
	v_cvt_pk_bf16_f32 v115, v134, v135
	v_cvt_pk_bf16_f32 v116, v136, v137
	v_cvt_pk_bf16_f32 v117, v160, v161
	v_ashrrev_i32_e32 v125, 31, v124
	global_store_dwordx4 v[132:133], v[114:117], off offset:256 sc0 sc1
	s_nop 1
	v_lshlrev_b64 v[114:115], 5, v[124:125]
	v_and_b32_e32 v118, 0x1fff, v114
	v_add_u32_e32 v118, 0x21400, v118
	ds_read_b128 v[114:117], v118
	s_nop 0
	ds_read_b128 v[118:121], v118 offset:16
	s_waitcnt lgkmcnt(0)
	v_mov_b32_e32 v122, v114
	v_mov_b32_e32 v123, v118
	v_mov_b32_e32 v118, v115
	v_pk_add_f32 v[114:115], v[122:123], v[118:119]
	v_mov_b32_e32 v118, v116
	v_mov_b32_e32 v119, v120
	v_mov_b32_e32 v120, v117
	v_pk_add_f32 v[116:117], v[118:119], v[120:121]
	s_nop 0
	v_pk_add_f32 v[114:115], v[114:115], v[116:117]
	s_nop 0
	v_add_f32_e32 v0, 0, v114
	v_add_f32_e32 v0, v0, v115
	v_fmamk_f32 v0, v0, 0x3b800000, v212
	v_cmp_gt_f32_e32 vcc, s69, v0
	v_mul_f32_e32 v114, 0x4b800000, v0
	s_nop 0
	v_cndmask_b32_e32 v0, v0, v114, vcc
	v_rsq_f32_e32 v0, v0
	s_nop 0
	v_mul_f32_e32 v114, 0x45800000, v0
	v_cndmask_b32_e32 v122, v0, v114, vcc
	v_lshlrev_b32_e32 v0, 4, v124
	v_and_b32_e32 v0, 0x7df0, v0
	v_pk_mul_f32 v[126:127], v[106:107], v[122:123] op_sel_hi:[1,0]
	v_cndmask_b32_e64 v106, 0, 1, s[0:1]
	v_pk_mul_f32 v[128:129], v[112:113], v[122:123] op_sel_hi:[1,0]
	v_pk_mul_f32 v[134:135], v[110:111], v[122:123] op_sel_hi:[1,0]
	v_pk_mul_f32 v[132:133], v[108:109], v[122:123] op_sel_hi:[1,0]
	v_cmp_ne_u32_e64 s[40:41], 1, v106
	s_andn2_b64 vcc, exec, s[0:1]
	v_lshlrev_b32_e32 v0, 2, v0
	s_cbranch_vccnz .LBB0_337
; __device__ __forceinline__ unsigned cvtpk(float lo, float hi) { f32x2 v = {lo, hi}; bf16x2_t b = __builtin_convertvector(v, bf16x2_t); return __builtin_bit_cast(unsigned, b); }
; __device__ __forceinline__ void rope8(f32x4& v0, f32x4& v1, const float* cosr, const float* sinr, int fq) {
;     const int j0 = 8 * (fq & 1);
;     const f32x4 c0 = *(const f32x4*)(cosr + j0), c1 = *(const f32x4*)(cosr + j0 + 4), s0 = *(const f32x4*)(sinr + j0), s1 = *(const f32x4*)(sinr + j0 + 4);
;     const float sg = (fq < 2) ? -1.f : 1.f;
; #pragma unroll
;     for (int i = 0; i < 4; ++i) {
;         const float p0 = __shfl_xor(v0[i], 32), p1 = __shfl_xor(v1[i], 32);
;         v0[i] = v0[i] * c0[i] + sg * p0 * s0[i]; v1[i] = v1[i] * c1[i] + sg * p1 * s1[i];
;     }
; }
;     __device__ __forceinline__ void operator()(AccRef acc, const Unit& u, int wr, int wc, int fr, int fq) const {
;     ...
;                 const int row = row0 + ai * 128 + m * 16;
;                 const float rs = rsqrtf(ssq_sum<NS>(ssq + (size_t)row * NS) * inv_n + EPS);
;                 bf16_t* rowp = O + (size_t)row * ldc + col0;
; #pragma unroll
;                 for (int bj = 0; bj < 2; ++bj) {
;                     f32x4 v0 = acc[ai][bj][m][0] * rs, v1 = acc[ai][bj][m][1] * rs;
;                     if (ROPE) { const int g32 = u.pn * 8 + bj * 4 + wc; if (g32 % 3 == 2) { const int pos = row & (SEQ - 1); rope8(v0, v1, cost + pos * 16, sint + pos * 16, fq); } }
;                     u32x4 w; w.x = cvtpk(v0[0], v0[1]); w.y = cvtpk(v0[2], v0[3]); w.z = cvtpk(v1[0], v1[1]); w.w = cvtpk(v1[2], v1[3]);
;                     st16_wt(rowp + bj * 128, w);
;                 }
	v_lshl_add_u64 v[106:107], v[148:149], 0, v[0:1]
	global_load_dwordx4 v[114:117], v[106:107], off
	global_load_dwordx4 v[110:113], v[106:107], off offset:16
	v_lshl_add_u64 v[106:107], v[150:151], 0, v[0:1]
	global_load_dwordx4 v[118:121], v[106:107], off
	s_nop 0
	global_load_dwordx4 v[106:109], v[106:107], off offset:16
	v_and_b32_e32 v125, 64, v213
	v_xor_b32_e32 v123, 32, v213
	v_add_u32_e32 v125, 64, v125
	v_cmp_lt_i32_e32 vcc, v123, v125
	v_mov_b32_e32 v160, v126
	s_waitcnt vmcnt(0)
	v_pk_mul_f32 v[114:115], v[134:135], v[114:115]
	v_cndmask_b32_e32 v123, v213, v123, vcc
	v_lshlrev_b32_e32 v123, 2, v123
	ds_bpermute_b32 v125, v123, v126
	v_mov_b32_e32 v161, v106
	v_mov_b32_e32 v136, v110
	ds_bpermute_b32 v158, v123, v134
	ds_bpermute_b32 v159, v123, v135
	s_waitcnt lgkmcnt(0)
	v_mul_f32_e32 v137, v146, v125
	v_mul_f32_e32 v106, v106, v137
	v_pk_fma_f32 v[136:137], v[160:161], v[136:137], v[106:107] op_sel_hi:[1,1,0]
	ds_bpermute_b32 v106, v123, v127
	v_pk_mul_f32 v[134:135], v[146:147], v[158:159]
	v_mov_b32_e32 v158, v111
	v_mul_f32_e32 v110, v127, v111
	v_mov_b32_e32 v160, v132
	s_waitcnt lgkmcnt(0)
	v_mul_f32_e32 v159, v146, v106
	v_mov_b32_e32 v106, v127
	v_pk_fma_f32 v[126:127], v[106:107], v[158:159], v[110:111] op_sel_hi:[1,1,0]
	ds_bpermute_b32 v107, v123, v128
	ds_bpermute_b32 v111, v123, v132
	v_mov_b32_e32 v161, v108
	v_mov_b32_e32 v158, v112
	v_mul_f32_e32 v106, v128, v116
	s_waitcnt lgkmcnt(1)
	v_mul_f32_e32 v107, v146, v107
	v_mul_f32_e32 v110, v120, v107
	ds_bpermute_b32 v107, v123, v129
	s_waitcnt lgkmcnt(1)
	v_mul_f32_e32 v159, v146, v111
	v_mul_f32_e32 v108, v108, v159
	v_pk_fma_f32 v[158:159], v[160:161], v[158:159], v[108:109] op_sel_hi:[1,1,0]
	ds_bpermute_b32 v108, v123, v133
	s_waitcnt lgkmcnt(1)
	v_mul_f32_e32 v161, v146, v107
	v_mov_b32_e32 v120, v129
	v_mov_b32_e32 v160, v117
	v_pk_mul_f32 v[116:117], v[120:121], v[160:161]
	v_pk_fma_f32 v[134:135], v[118:119], v[134:135], v[114:115]
	v_mov_b32_e32 v107, v116
	v_mov_b32_e32 v111, v117
	v_pk_add_f32 v[128:129], v[106:107], v[110:111]
	s_waitcnt lgkmcnt(0)
	v_mul_f32_e32 v107, v146, v108
	v_mov_b32_e32 v108, v133
	v_mov_b32_e32 v106, v113
	v_mul_f32_e32 v110, v109, v107
	v_pk_fma_f32 v[106:107], v[108:109], v[106:107], v[110:111] op_sel_hi:[1,1,0]
	v_mov_b32_e32 v126, v136
	v_mov_b32_e32 v132, v158
	v_mov_b32_e32 v133, v106
.LBB0_337:
	v_mov_b64_e32 v[106:107], s[92:93]
	v_mad_i64_i32 v[106:107], s[0:1], v124, s37, v[106:107]
	v_lshl_add_u64 v[114:115], v[130:131], 1, v[106:107]
	v_cvt_pk_bf16_f32 v106, v134, v135
	v_cvt_pk_bf16_f32 v107, v128, v129
	v_cvt_pk_bf16_f32 v108, v126, v127
	v_cvt_pk_bf16_f32 v109, v132, v133
	global_store_dwordx4 v[114:115], v[106:109], off sc0 sc1
	v_mov_b32_e32 v123, v122
	v_pk_mul_f32 v[124:125], v[102:103], v[122:123]
	v_mov_b32_e32 v106, v122
	v_mov_b32_e32 v107, v122
	v_pk_mul_f32 v[120:121], v[100:101], v[106:107]
	v_cndmask_b32_e64 v100, 0, 1, s[10:11]
	v_pk_mul_f32 v[116:117], v[104:105], v[106:107]
	v_cmp_ne_u32_e64 s[42:43], 1, v100
	s_andn2_b64 vcc, exec, s[10:11]
	v_pk_mul_f32 v[118:119], v[98:99], v[122:123]
	s_cbranch_vccnz .LBB0_339
	v_lshl_add_u64 v[98:99], v[148:149], 0, v[0:1]
	global_load_dwordx4 v[106:109], v[98:99], off
	global_load_dwordx4 v[102:105], v[98:99], off offset:16
	v_lshl_add_u64 v[98:99], v[150:151], 0, v[0:1]
	global_load_dwordx4 v[110:113], v[98:99], off
	s_nop 0
	global_load_dwordx4 v[98:101], v[98:99], off offset:16
	v_and_b32_e32 v122, 64, v213
	v_xor_b32_e32 v0, 32, v213
	v_add_u32_e32 v122, 64, v122
	v_cmp_lt_i32_e32 vcc, v0, v122
	v_mov_b32_e32 v128, v118
	s_waitcnt vmcnt(0)
	v_pk_mul_f32 v[106:107], v[124:125], v[106:107]
	v_cndmask_b32_e32 v0, v213, v0, vcc
	v_lshlrev_b32_e32 v132, 2, v0
	ds_bpermute_b32 v0, v132, v118
	v_mov_b32_e32 v129, v98
	v_mov_b32_e32 v122, v102
	ds_bpermute_b32 v126, v132, v124
	ds_bpermute_b32 v127, v132, v125
	s_waitcnt lgkmcnt(0)
	v_mul_f32_e32 v123, v146, v0
	v_mul_f32_e32 v0, v98, v123
	v_pk_fma_f32 v[122:123], v[128:129], v[122:123], v[0:1] op_sel_hi:[1,1,0]
	ds_bpermute_b32 v0, v132, v119
	v_pk_mul_f32 v[124:125], v[146:147], v[126:127]
	v_mov_b32_e32 v98, v119
	v_mov_b32_e32 v126, v103
	v_mov_b32_e32 v128, v120
	s_waitcnt lgkmcnt(0)
	v_mul_f32_e32 v127, v146, v0
	v_mul_f32_e32 v0, v119, v103
	v_pk_fma_f32 v[118:119], v[98:99], v[126:127], v[0:1] op_sel_hi:[1,1,0]
	ds_bpermute_b32 v0, v132, v116
	ds_bpermute_b32 v99, v132, v120
	v_mov_b32_e32 v129, v100
	v_mov_b32_e32 v126, v104
	v_mul_f32_e32 v98, v116, v108
	s_waitcnt lgkmcnt(1)
	v_mul_f32_e32 v0, v146, v0
	s_waitcnt lgkmcnt(0)
	v_mul_f32_e32 v127, v146, v99
	v_mul_f32_e32 v102, v112, v0
	v_mul_f32_e32 v0, v100, v127
	v_pk_fma_f32 v[126:127], v[128:129], v[126:127], v[0:1] op_sel_hi:[1,1,0]
	ds_bpermute_b32 v0, v132, v117
	ds_bpermute_b32 v100, v132, v121
	v_mov_b32_e32 v112, v117
	v_mov_b32_e32 v128, v109
	v_pk_fma_f32 v[124:125], v[110:111], v[124:125], v[106:107]
	s_waitcnt lgkmcnt(1)
	v_mul_f32_e32 v129, v146, v0
	v_pk_mul_f32 v[108:109], v[112:113], v[128:129]
	v_mov_b32_e32 v118, v122
	v_mov_b32_e32 v99, v108
	v_mov_b32_e32 v103, v109
	v_pk_add_f32 v[116:117], v[98:99], v[102:103]
	s_waitcnt lgkmcnt(0)
	v_mul_f32_e32 v99, v146, v100
	v_mov_b32_e32 v100, v121
	v_mov_b32_e32 v98, v105
	v_mul_f32_e32 v0, v101, v99
	v_pk_fma_f32 v[98:99], v[100:101], v[98:99], v[0:1] op_sel_hi:[1,1,0]
	v_mov_b32_e32 v120, v126
	v_mov_b32_e32 v121, v98
; __device__ __forceinline__ unsigned cvtpk(float lo, float hi) { f32x2 v = {lo, hi}; bf16x2_t b = __builtin_convertvector(v, bf16x2_t); return __builtin_bit_cast(unsigned, b); }
; __device__ __forceinline__ void rope8(f32x4& v0, f32x4& v1, const float* cosr, const float* sinr, int fq) {
;     const int j0 = 8 * (fq & 1);
;     const f32x4 c0 = *(const f32x4*)(cosr + j0), c1 = *(const f32x4*)(cosr + j0 + 4), s0 = *(const f32x4*)(sinr + j0), s1 = *(const f32x4*)(sinr + j0 + 4);
;     const float sg = (fq < 2) ? -1.f : 1.f;
; #pragma unroll
;     for (int i = 0; i < 4; ++i) {
;         const float p0 = __shfl_xor(v0[i], 32), p1 = __shfl_xor(v1[i], 32);
;         v0[i] = v0[i] * c0[i] + sg * p0 * s0[i]; v1[i] = v1[i] * c1[i] + sg * p1 * s1[i];
;     }
;     __device__ __forceinline__ void operator()(AccRef acc, const Unit& u, int wr, int wc, int fr, int fq) const {
;     ...
;                 const int row = row0 + ai * 128 + m * 16;
;                 const float rs = rsqrtf(ssq_sum<NS>(ssq + (size_t)row * NS) * inv_n + EPS);
;                 bf16_t* rowp = O + (size_t)row * ldc + col0;
; #pragma unroll
;                 for (int bj = 0; bj < 2; ++bj) {
;                     f32x4 v0 = acc[ai][bj][m][0] * rs, v1 = acc[ai][bj][m][1] * rs;
;                     if (ROPE) { const int g32 = u.pn * 8 + bj * 4 + wc; if (g32 % 3 == 2) { const int pos = row & (SEQ - 1); rope8(v0, v1, cost + pos * 16, sint + pos * 16, fq); } }
;                     u32x4 w; w.x = cvtpk(v0[0], v0[1]); w.y = cvtpk(v0[2], v0[3]); w.z = cvtpk(v1[0], v1[1]); w.w = cvtpk(v1[2], v1[3]);
;                     st16_wt(rowp + bj * 128, w);
.LBB0_339:
	v_or_b32_e32 v106, 32, v156
	v_cvt_pk_bf16_f32 v98, v124, v125
	v_cvt_pk_bf16_f32 v99, v116, v117
	v_cvt_pk_bf16_f32 v100, v118, v119
	v_cvt_pk_bf16_f32 v101, v120, v121
	v_ashrrev_i32_e32 v107, 31, v106
	global_store_dwordx4 v[114:115], v[98:101], off offset:256 sc0 sc1
	s_and_b64 vcc, exec, s[40:41]
	s_nop 0
	v_lshlrev_b64 v[98:99], 5, v[106:107]
	v_and_b32_e32 v102, 0x1fff, v98
	v_add_u32_e32 v102, 0x21400, v102
	ds_read_b128 v[98:101], v102
	s_nop 0
	ds_read_b128 v[102:105], v102 offset:16
	s_waitcnt lgkmcnt(0)
	v_mov_b32_e32 v108, v98
	v_mov_b32_e32 v109, v102
	v_mov_b32_e32 v102, v99
	v_mov_b32_e32 v98, v100
	v_mov_b32_e32 v99, v104
	v_mov_b32_e32 v104, v101
	v_pk_add_f32 v[100:101], v[108:109], v[102:103]
	v_pk_add_f32 v[98:99], v[98:99], v[104:105]
	s_nop 0
	v_pk_add_f32 v[98:99], v[100:101], v[98:99]
	s_nop 0
	v_add_f32_e32 v0, 0, v98
	v_add_f32_e32 v0, v0, v99
	v_fmamk_f32 v0, v0, 0x3b800000, v212
	v_mul_f32_e32 v98, 0x4b800000, v0
	v_cmp_gt_f32_e64 s[44:45], s69, v0
	s_nop 1
	v_cndmask_b32_e64 v0, v0, v98, s[44:45]
	v_rsq_f32_e32 v0, v0
	v_lshlrev_b32_e32 v98, 4, v106
	v_and_b32_e32 v98, 0x7ef0, v98
	v_mul_f32_e32 v99, 0x45800000, v0
	v_cndmask_b32_e64 v108, v0, v99, s[44:45]
	v_pk_mul_f32 v[112:113], v[96:97], v[108:109] op_sel_hi:[1,0]
	v_pk_mul_f32 v[118:119], v[94:95], v[108:109] op_sel_hi:[1,0]
	v_pk_mul_f32 v[114:115], v[92:93], v[108:109] op_sel_hi:[1,0]
	v_pk_mul_f32 v[110:111], v[90:91], v[108:109] op_sel_hi:[1,0]
	v_lshlrev_b32_e32 v0, 2, v98
	s_cbranch_vccnz .LBB0_341
	v_lshl_add_u64 v[90:91], v[148:149], 0, v[0:1]
	global_load_dwordx4 v[98:101], v[90:91], off
	global_load_dwordx4 v[94:97], v[90:91], off offset:16
	v_lshl_add_u64 v[90:91], v[150:151], 0, v[0:1]
	global_load_dwordx4 v[102:105], v[90:91], off
	s_nop 0
	global_load_dwordx4 v[90:93], v[90:91], off offset:16
	v_and_b32_e32 v109, 64, v213
	v_xor_b32_e32 v107, 32, v213
	v_add_u32_e32 v109, 64, v109
	v_cmp_lt_i32_e32 vcc, v107, v109
	v_mov_b32_e32 v122, v110
	s_waitcnt vmcnt(0)
	v_pk_mul_f32 v[98:99], v[118:119], v[98:99]
	v_cndmask_b32_e32 v107, v213, v107, vcc
	v_lshlrev_b32_e32 v107, 2, v107
	ds_bpermute_b32 v109, v107, v110
	v_mov_b32_e32 v123, v90
	v_mov_b32_e32 v116, v94
	ds_bpermute_b32 v120, v107, v118
	ds_bpermute_b32 v121, v107, v119
	s_waitcnt lgkmcnt(0)
	v_mul_f32_e32 v117, v146, v109
	v_mul_f32_e32 v90, v90, v117
	v_pk_fma_f32 v[116:117], v[122:123], v[116:117], v[90:91] op_sel_hi:[1,1,0]
	ds_bpermute_b32 v90, v107, v111
	v_pk_mul_f32 v[118:119], v[146:147], v[120:121]
	v_mov_b32_e32 v120, v95
	v_mul_f32_e32 v94, v111, v95
	v_mov_b32_e32 v122, v114
	s_waitcnt lgkmcnt(0)
	v_mul_f32_e32 v121, v146, v90
	v_mov_b32_e32 v90, v111
	v_pk_fma_f32 v[110:111], v[90:91], v[120:121], v[94:95] op_sel_hi:[1,1,0]
	ds_bpermute_b32 v91, v107, v112
	ds_bpermute_b32 v95, v107, v114
	v_mov_b32_e32 v123, v92
	v_mov_b32_e32 v120, v96
	v_mul_f32_e32 v90, v112, v100
	s_waitcnt lgkmcnt(1)
	v_mul_f32_e32 v91, v146, v91
	v_mul_f32_e32 v94, v104, v91
	ds_bpermute_b32 v91, v107, v113
	s_waitcnt lgkmcnt(1)
	v_mul_f32_e32 v121, v146, v95
	v_mul_f32_e32 v92, v92, v121
	v_pk_fma_f32 v[120:121], v[122:123], v[120:121], v[92:93] op_sel_hi:[1,1,0]
	ds_bpermute_b32 v92, v107, v115
	s_waitcnt lgkmcnt(1)
	v_mul_f32_e32 v123, v146, v91
	v_mov_b32_e32 v104, v113
	v_mov_b32_e32 v122, v101
	v_pk_mul_f32 v[100:101], v[104:105], v[122:123]
	v_pk_fma_f32 v[118:119], v[102:103], v[118:119], v[98:99]
	v_mov_b32_e32 v91, v100
	v_mov_b32_e32 v95, v101
	v_pk_add_f32 v[112:113], v[90:91], v[94:95]
	s_waitcnt lgkmcnt(0)
	v_mul_f32_e32 v91, v146, v92
	v_mov_b32_e32 v92, v115
	v_mov_b32_e32 v90, v97
	v_mul_f32_e32 v94, v93, v91
	v_pk_fma_f32 v[90:91], v[92:93], v[90:91], v[94:95] op_sel_hi:[1,1,0]
	v_mov_b32_e32 v110, v116
	v_mov_b32_e32 v114, v120
	v_mov_b32_e32 v115, v90
.LBB0_341:
	v_mov_b64_e32 v[90:91], s[92:93]
	v_mad_i64_i32 v[90:91], s[0:1], v106, s37, v[90:91]
	v_lshl_add_u64 v[98:99], v[130:131], 1, v[90:91]
	v_cvt_pk_bf16_f32 v90, v118, v119
	v_cvt_pk_bf16_f32 v91, v112, v113
	v_cvt_pk_bf16_f32 v92, v110, v111
	v_cvt_pk_bf16_f32 v93, v114, v115
	v_mov_b32_e32 v109, v108
	global_store_dwordx4 v[98:99], v[90:93], off sc0 sc1
	v_pk_mul_f32 v[110:111], v[86:87], v[108:109]
	s_and_b64 vcc, exec, s[42:43]
	v_mov_b32_e32 v90, v108
	v_mov_b32_e32 v91, v108
	v_pk_mul_f32 v[100:101], v[88:89], v[90:91]
	v_pk_mul_f32 v[104:105], v[84:85], v[90:91]
	v_pk_mul_f32 v[102:103], v[82:83], v[108:109]
	s_cbranch_vccnz .LBB0_343
	v_lshl_add_u64 v[82:83], v[148:149], 0, v[0:1]
	global_load_dwordx4 v[90:93], v[82:83], off
	global_load_dwordx4 v[86:89], v[82:83], off offset:16
	v_lshl_add_u64 v[82:83], v[150:151], 0, v[0:1]
	global_load_dwordx4 v[94:97], v[82:83], off
	s_nop 0
	global_load_dwordx4 v[82:85], v[82:83], off offset:16
	v_and_b32_e32 v106, 64, v213
	v_xor_b32_e32 v0, 32, v213
	v_add_u32_e32 v106, 64, v106
	v_cmp_lt_i32_e32 vcc, v0, v106
	v_mov_b32_e32 v112, v102
	s_waitcnt vmcnt(0)
	v_pk_mul_f32 v[90:91], v[110:111], v[90:91]
	v_cndmask_b32_e32 v0, v213, v0, vcc
	v_lshlrev_b32_e32 v114, 2, v0
	ds_bpermute_b32 v0, v114, v102
	v_mov_b32_e32 v113, v82
	v_mov_b32_e32 v106, v86
	ds_bpermute_b32 v108, v114, v110
	ds_bpermute_b32 v109, v114, v111
	s_waitcnt lgkmcnt(0)
	v_mul_f32_e32 v107, v146, v0
	v_mul_f32_e32 v0, v82, v107
	v_pk_fma_f32 v[106:107], v[112:113], v[106:107], v[0:1] op_sel_hi:[1,1,0]
	ds_bpermute_b32 v0, v114, v103
	v_mov_b32_e32 v82, v103
	v_mov_b32_e32 v110, v87
	v_mov_b32_e32 v112, v104
	v_mov_b32_e32 v113, v84
	s_waitcnt lgkmcnt(0)
	v_mul_f32_e32 v111, v146, v0
	v_mul_f32_e32 v0, v103, v87
	v_pk_fma_f32 v[102:103], v[82:83], v[110:111], v[0:1] op_sel_hi:[1,1,0]
	ds_bpermute_b32 v0, v114, v100
	ds_bpermute_b32 v83, v114, v104
	v_mov_b32_e32 v110, v88
	v_mul_f32_e32 v82, v100, v92
	v_pk_mul_f32 v[108:109], v[146:147], v[108:109]
	s_waitcnt lgkmcnt(1)
	v_mul_f32_e32 v0, v146, v0
	s_waitcnt lgkmcnt(0)
	v_mul_f32_e32 v111, v146, v83
	v_mul_f32_e32 v86, v96, v0
	v_mul_f32_e32 v0, v84, v111
	v_pk_fma_f32 v[112:113], v[112:113], v[110:111], v[0:1] op_sel_hi:[1,1,0]
	ds_bpermute_b32 v0, v114, v101
	ds_bpermute_b32 v84, v114, v105
	v_mov_b32_e32 v96, v101
	v_mov_b32_e32 v110, v93
	v_mov_b32_e32 v102, v106
	s_waitcnt lgkmcnt(1)
	v_mul_f32_e32 v111, v146, v0
	v_pk_mul_f32 v[92:93], v[96:97], v[110:111]
	v_pk_fma_f32 v[110:111], v[94:95], v[108:109], v[90:91]
	v_mov_b32_e32 v83, v92
	v_mov_b32_e32 v87, v93
	v_pk_add_f32 v[100:101], v[82:83], v[86:87]
	s_waitcnt lgkmcnt(0)
	v_mul_f32_e32 v83, v146, v84
	v_mov_b32_e32 v84, v105
	v_mov_b32_e32 v82, v89
	v_mul_f32_e32 v0, v85, v83
	v_pk_fma_f32 v[82:83], v[84:85], v[82:83], v[0:1] op_sel_hi:[1,1,0]
	v_mov_b32_e32 v104, v112
	v_mov_b32_e32 v105, v82
; __device__ __forceinline__ unsigned cvtpk(float lo, float hi) { f32x2 v = {lo, hi}; bf16x2_t b = __builtin_convertvector(v, bf16x2_t); return __builtin_bit_cast(unsigned, b); }
; __device__ __forceinline__ void rope8(f32x4& v0, f32x4& v1, const float* cosr, const float* sinr, int fq) {
;     const int j0 = 8 * (fq & 1);
;     const f32x4 c0 = *(const f32x4*)(cosr + j0), c1 = *(const f32x4*)(cosr + j0 + 4), s0 = *(const f32x4*)(sinr + j0), s1 = *(const f32x4*)(sinr + j0 + 4);
;     const float sg = (fq < 2) ? -1.f : 1.f;
; #pragma unroll
;     for (int i = 0; i < 4; ++i) {
;         const float p0 = __shfl_xor(v0[i], 32), p1 = __shfl_xor(v1[i], 32);
;         v0[i] = v0[i] * c0[i] + sg * p0 * s0[i]; v1[i] = v1[i] * c1[i] + sg * p1 * s1[i];
;     }
;     __device__ __forceinline__ void operator()(AccRef acc, const Unit& u, int wr, int wc, int fr, int fq) const {
;     ...
;                 const int row = row0 + ai * 128 + m * 16;
;                 const float rs = rsqrtf(ssq_sum<NS>(ssq + (size_t)row * NS) * inv_n + EPS);
;                 bf16_t* rowp = O + (size_t)row * ldc + col0;
; #pragma unroll
;                 for (int bj = 0; bj < 2; ++bj) {
;                     f32x4 v0 = acc[ai][bj][m][0] * rs, v1 = acc[ai][bj][m][1] * rs;
;                     if (ROPE) { const int g32 = u.pn * 8 + bj * 4 + wc; if (g32 % 3 == 2) { const int pos = row & (SEQ - 1); rope8(v0, v1, cost + pos * 16, sint + pos * 16, fq); } }
;                     u32x4 w; w.x = cvtpk(v0[0], v0[1]); w.y = cvtpk(v0[2], v0[3]); w.z = cvtpk(v1[0], v1[1]); w.w = cvtpk(v1[2], v1[3]);
;                     st16_wt(rowp + bj * 128, w);
.LBB0_343:
	v_or_b32_e32 v90, 48, v156
	v_cvt_pk_bf16_f32 v82, v110, v111
	v_cvt_pk_bf16_f32 v83, v100, v101
	v_cvt_pk_bf16_f32 v84, v102, v103
	v_cvt_pk_bf16_f32 v85, v104, v105
	v_ashrrev_i32_e32 v91, 31, v90
	global_store_dwordx4 v[98:99], v[82:85], off offset:256 sc0 sc1
	s_and_b64 vcc, exec, s[40:41]
	s_nop 0
	v_lshlrev_b64 v[82:83], 5, v[90:91]
	v_and_b32_e32 v86, 0x1fff, v82
	v_add_u32_e32 v86, 0x21400, v86
	ds_read_b128 v[82:85], v86
	s_nop 0
	ds_read_b128 v[86:89], v86 offset:16
	s_waitcnt lgkmcnt(0)
	v_mov_b32_e32 v92, v82
	v_mov_b32_e32 v93, v86
	v_mov_b32_e32 v86, v83
	v_mov_b32_e32 v82, v84
	v_mov_b32_e32 v83, v88
	v_mov_b32_e32 v88, v85
	v_pk_add_f32 v[84:85], v[92:93], v[86:87]
	v_pk_add_f32 v[82:83], v[82:83], v[88:89]
	s_nop 0
	v_pk_add_f32 v[82:83], v[84:85], v[82:83]
	s_nop 0
	v_add_f32_e32 v0, 0, v82
	v_add_f32_e32 v0, v0, v83
	v_fmamk_f32 v0, v0, 0x3b800000, v212
	v_mul_f32_e32 v82, 0x4b800000, v0
	v_cmp_gt_f32_e64 s[44:45], s69, v0
	s_nop 1
	v_cndmask_b32_e64 v0, v0, v82, s[44:45]
	v_rsq_f32_e32 v0, v0
	v_lshlrev_b32_e32 v82, 4, v90
	v_and_b32_e32 v82, 0x7ff0, v82
	v_mul_f32_e32 v83, 0x45800000, v0
	v_cndmask_b32_e64 v92, v0, v83, s[44:45]
	v_pk_mul_f32 v[96:97], v[80:81], v[92:93] op_sel_hi:[1,0]
	v_pk_mul_f32 v[102:103], v[78:79], v[92:93] op_sel_hi:[1,0]
	v_pk_mul_f32 v[98:99], v[76:77], v[92:93] op_sel_hi:[1,0]
	v_pk_mul_f32 v[94:95], v[74:75], v[92:93] op_sel_hi:[1,0]
	v_lshlrev_b32_e32 v0, 2, v82
	s_cbranch_vccnz .LBB0_345
	v_lshl_add_u64 v[74:75], v[148:149], 0, v[0:1]
	global_load_dwordx4 v[82:85], v[74:75], off
	global_load_dwordx4 v[78:81], v[74:75], off offset:16
	v_lshl_add_u64 v[74:75], v[150:151], 0, v[0:1]
	global_load_dwordx4 v[86:89], v[74:75], off
	s_nop 0
	global_load_dwordx4 v[74:77], v[74:75], off offset:16
	v_and_b32_e32 v93, 64, v213
	v_xor_b32_e32 v91, 32, v213
	v_add_u32_e32 v93, 64, v93
	v_cmp_lt_i32_e32 vcc, v91, v93
	v_mov_b32_e32 v106, v94
	s_waitcnt vmcnt(0)
	v_pk_mul_f32 v[82:83], v[102:103], v[82:83]
	v_cndmask_b32_e32 v91, v213, v91, vcc
	v_lshlrev_b32_e32 v91, 2, v91
	ds_bpermute_b32 v93, v91, v94
	v_mov_b32_e32 v107, v74
	v_mov_b32_e32 v100, v78
	ds_bpermute_b32 v104, v91, v102
	ds_bpermute_b32 v105, v91, v103
	s_waitcnt lgkmcnt(0)
	v_mul_f32_e32 v101, v146, v93
	v_mul_f32_e32 v74, v74, v101
	v_pk_fma_f32 v[100:101], v[106:107], v[100:101], v[74:75] op_sel_hi:[1,1,0]
	ds_bpermute_b32 v74, v91, v95
	v_pk_mul_f32 v[102:103], v[146:147], v[104:105]
	v_mov_b32_e32 v104, v79
	v_mul_f32_e32 v78, v95, v79
	v_mov_b32_e32 v106, v98
	s_waitcnt lgkmcnt(0)
	v_mul_f32_e32 v105, v146, v74
	v_mov_b32_e32 v74, v95
	v_pk_fma_f32 v[94:95], v[74:75], v[104:105], v[78:79] op_sel_hi:[1,1,0]
	ds_bpermute_b32 v75, v91, v96
	ds_bpermute_b32 v79, v91, v98
	v_mov_b32_e32 v107, v76
	v_mov_b32_e32 v104, v80
	v_mul_f32_e32 v74, v96, v84
	s_waitcnt lgkmcnt(1)
	v_mul_f32_e32 v75, v146, v75
	v_mul_f32_e32 v78, v88, v75
	ds_bpermute_b32 v75, v91, v97
	s_waitcnt lgkmcnt(1)
	v_mul_f32_e32 v105, v146, v79
	v_mul_f32_e32 v76, v76, v105
	v_pk_fma_f32 v[104:105], v[106:107], v[104:105], v[76:77] op_sel_hi:[1,1,0]
	ds_bpermute_b32 v76, v91, v99
	s_waitcnt lgkmcnt(1)
	v_mul_f32_e32 v107, v146, v75
	v_mov_b32_e32 v88, v97
	v_mov_b32_e32 v106, v85
	v_pk_mul_f32 v[84:85], v[88:89], v[106:107]
	v_pk_fma_f32 v[102:103], v[86:87], v[102:103], v[82:83]
	v_mov_b32_e32 v75, v84
	v_mov_b32_e32 v79, v85
	v_pk_add_f32 v[96:97], v[74:75], v[78:79]
	s_waitcnt lgkmcnt(0)
	v_mul_f32_e32 v75, v146, v76
	v_mov_b32_e32 v76, v99
	v_mov_b32_e32 v74, v81
	v_mul_f32_e32 v78, v77, v75
	v_pk_fma_f32 v[74:75], v[76:77], v[74:75], v[78:79] op_sel_hi:[1,1,0]
	v_mov_b32_e32 v94, v100
	v_mov_b32_e32 v98, v104
	v_mov_b32_e32 v99, v74
.LBB0_345:
	v_mov_b64_e32 v[74:75], s[92:93]
	v_mad_i64_i32 v[74:75], s[0:1], v90, s37, v[74:75]
	v_lshl_add_u64 v[82:83], v[130:131], 1, v[74:75]
	v_cvt_pk_bf16_f32 v74, v102, v103
	v_cvt_pk_bf16_f32 v75, v96, v97
	v_cvt_pk_bf16_f32 v76, v94, v95
	v_cvt_pk_bf16_f32 v77, v98, v99
	v_mov_b32_e32 v93, v92
	global_store_dwordx4 v[82:83], v[74:77], off sc0 sc1
	v_pk_mul_f32 v[94:95], v[70:71], v[92:93]
	s_and_b64 vcc, exec, s[42:43]
	v_mov_b32_e32 v74, v92
	v_mov_b32_e32 v75, v92
	v_pk_mul_f32 v[84:85], v[72:73], v[74:75]
	v_pk_mul_f32 v[88:89], v[68:69], v[74:75]
	v_pk_mul_f32 v[86:87], v[66:67], v[92:93]
	s_cbranch_vccnz .LBB0_347
	v_lshl_add_u64 v[66:67], v[148:149], 0, v[0:1]
	global_load_dwordx4 v[74:77], v[66:67], off
	global_load_dwordx4 v[70:73], v[66:67], off offset:16
	v_lshl_add_u64 v[66:67], v[150:151], 0, v[0:1]
	global_load_dwordx4 v[78:81], v[66:67], off
	s_nop 0
	global_load_dwordx4 v[66:69], v[66:67], off offset:16
	v_and_b32_e32 v90, 64, v213
	v_xor_b32_e32 v0, 32, v213
	v_add_u32_e32 v90, 64, v90
	v_cmp_lt_i32_e32 vcc, v0, v90
	v_mov_b32_e32 v96, v86
	s_waitcnt vmcnt(0)
	v_pk_mul_f32 v[74:75], v[94:95], v[74:75]
	v_cndmask_b32_e32 v0, v213, v0, vcc
	v_lshlrev_b32_e32 v98, 2, v0
	ds_bpermute_b32 v0, v98, v86
	v_mov_b32_e32 v97, v66
	v_mov_b32_e32 v90, v70
	ds_bpermute_b32 v92, v98, v94
	ds_bpermute_b32 v93, v98, v95
	s_waitcnt lgkmcnt(0)
	v_mul_f32_e32 v91, v146, v0
	v_mul_f32_e32 v0, v66, v91
	v_pk_fma_f32 v[90:91], v[96:97], v[90:91], v[0:1] op_sel_hi:[1,1,0]
	ds_bpermute_b32 v0, v98, v87
	v_mov_b32_e32 v66, v87
	v_mov_b32_e32 v94, v71
	v_mov_b32_e32 v96, v88
	v_mov_b32_e32 v97, v68
	s_waitcnt lgkmcnt(0)
	v_mul_f32_e32 v95, v146, v0
	v_mul_f32_e32 v0, v87, v71
	v_pk_fma_f32 v[86:87], v[66:67], v[94:95], v[0:1] op_sel_hi:[1,1,0]
	ds_bpermute_b32 v0, v98, v84
	ds_bpermute_b32 v67, v98, v88
	v_mov_b32_e32 v94, v72
	v_mul_f32_e32 v66, v84, v76
	v_pk_mul_f32 v[92:93], v[146:147], v[92:93]
	s_waitcnt lgkmcnt(1)
	v_mul_f32_e32 v0, v146, v0
	s_waitcnt lgkmcnt(0)
	v_mul_f32_e32 v95, v146, v67
	v_mul_f32_e32 v70, v80, v0
	v_mul_f32_e32 v0, v68, v95
	v_pk_fma_f32 v[96:97], v[96:97], v[94:95], v[0:1] op_sel_hi:[1,1,0]
	ds_bpermute_b32 v0, v98, v85
	ds_bpermute_b32 v68, v98, v89
	v_mov_b32_e32 v80, v85
	v_mov_b32_e32 v94, v77
	v_mov_b32_e32 v86, v90
	s_waitcnt lgkmcnt(1)
	v_mul_f32_e32 v95, v146, v0
	v_pk_mul_f32 v[76:77], v[80:81], v[94:95]
	v_pk_fma_f32 v[94:95], v[78:79], v[92:93], v[74:75]
	v_mov_b32_e32 v67, v76
	v_mov_b32_e32 v71, v77
	v_pk_add_f32 v[84:85], v[66:67], v[70:71]
	s_waitcnt lgkmcnt(0)
	v_mul_f32_e32 v67, v146, v68
	v_mov_b32_e32 v68, v89
	v_mov_b32_e32 v66, v73
	v_mul_f32_e32 v0, v69, v67
	v_pk_fma_f32 v[66:67], v[68:69], v[66:67], v[0:1] op_sel_hi:[1,1,0]
	v_mov_b32_e32 v88, v96
	v_mov_b32_e32 v89, v66
; __device__ __forceinline__ unsigned cvtpk(float lo, float hi) { f32x2 v = {lo, hi}; bf16x2_t b = __builtin_convertvector(v, bf16x2_t); return __builtin_bit_cast(unsigned, b); }
; __device__ __forceinline__ void rope8(f32x4& v0, f32x4& v1, const float* cosr, const float* sinr, int fq) {
;     const int j0 = 8 * (fq & 1);
;     const f32x4 c0 = *(const f32x4*)(cosr + j0), c1 = *(const f32x4*)(cosr + j0 + 4), s0 = *(const f32x4*)(sinr + j0), s1 = *(const f32x4*)(sinr + j0 + 4);
;     const float sg = (fq < 2) ? -1.f : 1.f;
; #pragma unroll
;     for (int i = 0; i < 4; ++i) {
;         const float p0 = __shfl_xor(v0[i], 32), p1 = __shfl_xor(v1[i], 32);
;         v0[i] = v0[i] * c0[i] + sg * p0 * s0[i]; v1[i] = v1[i] * c1[i] + sg * p1 * s1[i];
;     }
;     __device__ __forceinline__ void operator()(AccRef acc, const Unit& u, int wr, int wc, int fr, int fq) const {
;     ...
;                 const int row = row0 + ai * 128 + m * 16;
;                 const float rs = rsqrtf(ssq_sum<NS>(ssq + (size_t)row * NS) * inv_n + EPS);
;                 bf16_t* rowp = O + (size_t)row * ldc + col0;
; #pragma unroll
;                 for (int bj = 0; bj < 2; ++bj) {
;                     f32x4 v0 = acc[ai][bj][m][0] * rs, v1 = acc[ai][bj][m][1] * rs;
;                     if (ROPE) { const int g32 = u.pn * 8 + bj * 4 + wc; if (g32 % 3 == 2) { const int pos = row & (SEQ - 1); rope8(v0, v1, cost + pos * 16, sint + pos * 16, fq); } }
;                     u32x4 w; w.x = cvtpk(v0[0], v0[1]); w.y = cvtpk(v0[2], v0[3]); w.z = cvtpk(v1[0], v1[1]); w.w = cvtpk(v1[2], v1[3]);
;                     st16_wt(rowp + bj * 128, w);
.LBB0_347:
	v_add_u32_e32 v74, 0x80, v156
	v_cvt_pk_bf16_f32 v66, v94, v95
	v_cvt_pk_bf16_f32 v67, v84, v85
	v_cvt_pk_bf16_f32 v68, v86, v87
	v_cvt_pk_bf16_f32 v69, v88, v89
	v_ashrrev_i32_e32 v75, 31, v74
	global_store_dwordx4 v[82:83], v[66:69], off offset:256 sc0 sc1
	s_and_b64 vcc, exec, s[40:41]
	s_nop 0
	v_lshlrev_b64 v[66:67], 5, v[74:75]
	v_and_b32_e32 v70, 0x1fff, v66
	v_add_u32_e32 v70, 0x21400, v70
	ds_read_b128 v[66:69], v70
	s_nop 0
	ds_read_b128 v[70:73], v70 offset:16
	s_waitcnt lgkmcnt(0)
	v_mov_b32_e32 v76, v66
	v_mov_b32_e32 v77, v70
	v_mov_b32_e32 v70, v67
	v_mov_b32_e32 v66, v68
	v_mov_b32_e32 v67, v72
	v_mov_b32_e32 v72, v69
	v_pk_add_f32 v[68:69], v[76:77], v[70:71]
	v_pk_add_f32 v[66:67], v[66:67], v[72:73]
	s_nop 0
	v_pk_add_f32 v[66:67], v[68:69], v[66:67]
	s_nop 0
	v_add_f32_e32 v0, 0, v66
	v_add_f32_e32 v0, v0, v67
	v_fmamk_f32 v0, v0, 0x3b800000, v212
	v_mul_f32_e32 v66, 0x4b800000, v0
	v_cmp_gt_f32_e64 s[44:45], s69, v0
	s_nop 1
	v_cndmask_b32_e64 v0, v0, v66, s[44:45]
	v_rsq_f32_e32 v0, v0
	v_lshlrev_b32_e32 v66, 4, v74
	v_and_b32_e32 v66, 0x7cf0, v66
	v_mul_f32_e32 v67, 0x45800000, v0
	v_cndmask_b32_e64 v76, v0, v67, s[44:45]
	v_pk_mul_f32 v[80:81], v[64:65], v[76:77] op_sel_hi:[1,0]
	v_pk_mul_f32 v[86:87], v[62:63], v[76:77] op_sel_hi:[1,0]
	v_pk_mul_f32 v[82:83], v[60:61], v[76:77] op_sel_hi:[1,0]
	v_pk_mul_f32 v[78:79], v[58:59], v[76:77] op_sel_hi:[1,0]
	v_lshlrev_b32_e32 v0, 2, v66
	s_cbranch_vccnz .LBB0_349
	v_lshl_add_u64 v[58:59], v[148:149], 0, v[0:1]
	global_load_dwordx4 v[66:69], v[58:59], off
	global_load_dwordx4 v[62:65], v[58:59], off offset:16
	v_lshl_add_u64 v[58:59], v[150:151], 0, v[0:1]
	global_load_dwordx4 v[70:73], v[58:59], off
	s_nop 0
	global_load_dwordx4 v[58:61], v[58:59], off offset:16
	v_and_b32_e32 v77, 64, v213
	v_xor_b32_e32 v75, 32, v213
	v_add_u32_e32 v77, 64, v77
	v_cmp_lt_i32_e32 vcc, v75, v77
	v_mov_b32_e32 v90, v78
	s_waitcnt vmcnt(0)
	v_pk_mul_f32 v[66:67], v[86:87], v[66:67]
	v_cndmask_b32_e32 v75, v213, v75, vcc
	v_lshlrev_b32_e32 v75, 2, v75
	ds_bpermute_b32 v77, v75, v78
	v_mov_b32_e32 v91, v58
	v_mov_b32_e32 v84, v62
	ds_bpermute_b32 v88, v75, v86
	ds_bpermute_b32 v89, v75, v87
	s_waitcnt lgkmcnt(0)
	v_mul_f32_e32 v85, v146, v77
	v_mul_f32_e32 v58, v58, v85
	v_pk_fma_f32 v[84:85], v[90:91], v[84:85], v[58:59] op_sel_hi:[1,1,0]
	ds_bpermute_b32 v58, v75, v79
	v_pk_mul_f32 v[86:87], v[146:147], v[88:89]
	v_mov_b32_e32 v88, v63
	v_mul_f32_e32 v62, v79, v63
	v_mov_b32_e32 v90, v82
	s_waitcnt lgkmcnt(0)
	v_mul_f32_e32 v89, v146, v58
	v_mov_b32_e32 v58, v79
	v_pk_fma_f32 v[78:79], v[58:59], v[88:89], v[62:63] op_sel_hi:[1,1,0]
	ds_bpermute_b32 v59, v75, v80
	ds_bpermute_b32 v63, v75, v82
	v_mov_b32_e32 v91, v60
	v_mov_b32_e32 v88, v64
	v_mul_f32_e32 v58, v80, v68
	s_waitcnt lgkmcnt(1)
	v_mul_f32_e32 v59, v146, v59
	v_mul_f32_e32 v62, v72, v59
	ds_bpermute_b32 v59, v75, v81
	s_waitcnt lgkmcnt(1)
	v_mul_f32_e32 v89, v146, v63
	v_mul_f32_e32 v60, v60, v89
	v_pk_fma_f32 v[88:89], v[90:91], v[88:89], v[60:61] op_sel_hi:[1,1,0]
	ds_bpermute_b32 v60, v75, v83
	s_waitcnt lgkmcnt(1)
	v_mul_f32_e32 v91, v146, v59
	v_mov_b32_e32 v72, v81
	v_mov_b32_e32 v90, v69
	v_pk_mul_f32 v[68:69], v[72:73], v[90:91]
	v_pk_fma_f32 v[86:87], v[70:71], v[86:87], v[66:67]
	v_mov_b32_e32 v59, v68
	v_mov_b32_e32 v63, v69
	v_pk_add_f32 v[80:81], v[58:59], v[62:63]
	s_waitcnt lgkmcnt(0)
	v_mul_f32_e32 v59, v146, v60
	v_mov_b32_e32 v60, v83
	v_mov_b32_e32 v58, v65
	v_mul_f32_e32 v62, v61, v59
	v_pk_fma_f32 v[58:59], v[60:61], v[58:59], v[62:63] op_sel_hi:[1,1,0]
	v_mov_b32_e32 v78, v84
	v_mov_b32_e32 v82, v88
	v_mov_b32_e32 v83, v58
.LBB0_349:
	v_mov_b64_e32 v[58:59], s[92:93]
	v_mad_i64_i32 v[58:59], s[0:1], v74, s37, v[58:59]
	v_lshl_add_u64 v[66:67], v[130:131], 1, v[58:59]
	v_cvt_pk_bf16_f32 v58, v86, v87
	v_cvt_pk_bf16_f32 v59, v80, v81
	v_cvt_pk_bf16_f32 v60, v78, v79
	v_cvt_pk_bf16_f32 v61, v82, v83
	v_mov_b32_e32 v77, v76
	global_store_dwordx4 v[66:67], v[58:61], off sc0 sc1
	v_pk_mul_f32 v[78:79], v[54:55], v[76:77]
	s_and_b64 vcc, exec, s[42:43]
	v_mov_b32_e32 v58, v76
	v_mov_b32_e32 v59, v76
	v_pk_mul_f32 v[68:69], v[56:57], v[58:59]
	v_pk_mul_f32 v[72:73], v[52:53], v[58:59]
	v_pk_mul_f32 v[70:71], v[50:51], v[76:77]
	s_cbranch_vccnz .LBB0_351
	v_lshl_add_u64 v[50:51], v[148:149], 0, v[0:1]
	global_load_dwordx4 v[58:61], v[50:51], off
	global_load_dwordx4 v[54:57], v[50:51], off offset:16
	v_lshl_add_u64 v[50:51], v[150:151], 0, v[0:1]
	global_load_dwordx4 v[62:65], v[50:51], off
	s_nop 0
	global_load_dwordx4 v[50:53], v[50:51], off offset:16
	v_and_b32_e32 v74, 64, v213
	v_xor_b32_e32 v0, 32, v213
	v_add_u32_e32 v74, 64, v74
	v_cmp_lt_i32_e32 vcc, v0, v74
	v_mov_b32_e32 v80, v70
	s_waitcnt vmcnt(0)
	v_pk_mul_f32 v[58:59], v[78:79], v[58:59]
	v_cndmask_b32_e32 v0, v213, v0, vcc
	v_lshlrev_b32_e32 v82, 2, v0
	ds_bpermute_b32 v0, v82, v70
	v_mov_b32_e32 v81, v50
	v_mov_b32_e32 v74, v54
	ds_bpermute_b32 v76, v82, v78
	ds_bpermute_b32 v77, v82, v79
	s_waitcnt lgkmcnt(0)
	v_mul_f32_e32 v75, v146, v0
	v_mul_f32_e32 v0, v50, v75
	v_pk_fma_f32 v[74:75], v[80:81], v[74:75], v[0:1] op_sel_hi:[1,1,0]
	ds_bpermute_b32 v0, v82, v71
	v_mov_b32_e32 v50, v71
	v_mov_b32_e32 v78, v55
	v_mov_b32_e32 v80, v72
	v_mov_b32_e32 v81, v52
	s_waitcnt lgkmcnt(0)
	v_mul_f32_e32 v79, v146, v0
	v_mul_f32_e32 v0, v71, v55
	v_pk_fma_f32 v[70:71], v[50:51], v[78:79], v[0:1] op_sel_hi:[1,1,0]
	ds_bpermute_b32 v0, v82, v68
	ds_bpermute_b32 v51, v82, v72
	v_mov_b32_e32 v78, v56
	v_mul_f32_e32 v50, v68, v60
	v_pk_mul_f32 v[76:77], v[146:147], v[76:77]
	s_waitcnt lgkmcnt(1)
	v_mul_f32_e32 v0, v146, v0
	s_waitcnt lgkmcnt(0)
	v_mul_f32_e32 v79, v146, v51
	v_mul_f32_e32 v54, v64, v0
	v_mul_f32_e32 v0, v52, v79
	v_pk_fma_f32 v[80:81], v[80:81], v[78:79], v[0:1] op_sel_hi:[1,1,0]
	ds_bpermute_b32 v0, v82, v69
	ds_bpermute_b32 v52, v82, v73
	v_mov_b32_e32 v64, v69
	v_mov_b32_e32 v78, v61
	v_mov_b32_e32 v70, v74
	s_waitcnt lgkmcnt(1)
	v_mul_f32_e32 v79, v146, v0
	v_pk_mul_f32 v[60:61], v[64:65], v[78:79]
	v_pk_fma_f32 v[78:79], v[62:63], v[76:77], v[58:59]
	v_mov_b32_e32 v51, v60
	v_mov_b32_e32 v55, v61
	v_pk_add_f32 v[68:69], v[50:51], v[54:55]
	s_waitcnt lgkmcnt(0)
	v_mul_f32_e32 v51, v146, v52
	v_mov_b32_e32 v52, v73
	v_mov_b32_e32 v50, v57
	v_mul_f32_e32 v0, v53, v51
	v_pk_fma_f32 v[50:51], v[52:53], v[50:51], v[0:1] op_sel_hi:[1,1,0]
	v_mov_b32_e32 v72, v80
	v_mov_b32_e32 v73, v50
; __device__ __forceinline__ unsigned cvtpk(float lo, float hi) { f32x2 v = {lo, hi}; bf16x2_t b = __builtin_convertvector(v, bf16x2_t); return __builtin_bit_cast(unsigned, b); }
; __device__ __forceinline__ void rope8(f32x4& v0, f32x4& v1, const float* cosr, const float* sinr, int fq) {
;     const int j0 = 8 * (fq & 1);
;     const f32x4 c0 = *(const f32x4*)(cosr + j0), c1 = *(const f32x4*)(cosr + j0 + 4), s0 = *(const f32x4*)(sinr + j0), s1 = *(const f32x4*)(sinr + j0 + 4);
;     const float sg = (fq < 2) ? -1.f : 1.f;
; #pragma unroll
;     for (int i = 0; i < 4; ++i) {
;         const float p0 = __shfl_xor(v0[i], 32), p1 = __shfl_xor(v1[i], 32);
;         v0[i] = v0[i] * c0[i] + sg * p0 * s0[i]; v1[i] = v1[i] * c1[i] + sg * p1 * s1[i];
;     }
;     __device__ __forceinline__ void operator()(AccRef acc, const Unit& u, int wr, int wc, int fr, int fq) const {
;     ...
;                 const int row = row0 + ai * 128 + m * 16;
;                 const float rs = rsqrtf(ssq_sum<NS>(ssq + (size_t)row * NS) * inv_n + EPS);
;                 bf16_t* rowp = O + (size_t)row * ldc + col0;
; #pragma unroll
;                 for (int bj = 0; bj < 2; ++bj) {
;                     f32x4 v0 = acc[ai][bj][m][0] * rs, v1 = acc[ai][bj][m][1] * rs;
;                     if (ROPE) { const int g32 = u.pn * 8 + bj * 4 + wc; if (g32 % 3 == 2) { const int pos = row & (SEQ - 1); rope8(v0, v1, cost + pos * 16, sint + pos * 16, fq); } }
;                     u32x4 w; w.x = cvtpk(v0[0], v0[1]); w.y = cvtpk(v0[2], v0[3]); w.z = cvtpk(v1[0], v1[1]); w.w = cvtpk(v1[2], v1[3]);
;                     st16_wt(rowp + bj * 128, w);
.LBB0_351:
	v_add_u32_e32 v58, 0x90, v156
	v_cvt_pk_bf16_f32 v50, v78, v79
	v_cvt_pk_bf16_f32 v51, v68, v69
	v_cvt_pk_bf16_f32 v52, v70, v71
	v_cvt_pk_bf16_f32 v53, v72, v73
	v_ashrrev_i32_e32 v59, 31, v58
	global_store_dwordx4 v[66:67], v[50:53], off offset:256 sc0 sc1
	s_and_b64 vcc, exec, s[40:41]
	s_nop 0
	v_lshlrev_b64 v[50:51], 5, v[58:59]
	v_and_b32_e32 v54, 0x1fff, v50
	v_add_u32_e32 v54, 0x21400, v54
	ds_read_b128 v[50:53], v54
	s_nop 0
	ds_read_b128 v[54:57], v54 offset:16
	s_waitcnt lgkmcnt(0)
	v_mov_b32_e32 v60, v50
	v_mov_b32_e32 v61, v54
	v_mov_b32_e32 v54, v51
	v_mov_b32_e32 v50, v52
	v_mov_b32_e32 v51, v56
	v_mov_b32_e32 v56, v53
	v_pk_add_f32 v[52:53], v[60:61], v[54:55]
	v_pk_add_f32 v[50:51], v[50:51], v[56:57]
	s_nop 0
	v_pk_add_f32 v[50:51], v[52:53], v[50:51]
	s_nop 0
	v_add_f32_e32 v0, 0, v50
	v_add_f32_e32 v0, v0, v51
	v_fmamk_f32 v0, v0, 0x3b800000, v212
	v_mul_f32_e32 v50, 0x4b800000, v0
	v_cmp_gt_f32_e64 s[44:45], s69, v0
	s_nop 1
	v_cndmask_b32_e64 v0, v0, v50, s[44:45]
	v_rsq_f32_e32 v0, v0
	v_lshlrev_b32_e32 v50, 4, v58
	v_and_b32_e32 v50, 0x7df0, v50
	v_mul_f32_e32 v51, 0x45800000, v0
	v_cndmask_b32_e64 v60, v0, v51, s[44:45]
	v_pk_mul_f32 v[64:65], v[48:49], v[60:61] op_sel_hi:[1,0]
	v_pk_mul_f32 v[70:71], v[46:47], v[60:61] op_sel_hi:[1,0]
	v_pk_mul_f32 v[66:67], v[44:45], v[60:61] op_sel_hi:[1,0]
	v_pk_mul_f32 v[62:63], v[42:43], v[60:61] op_sel_hi:[1,0]
	v_lshlrev_b32_e32 v0, 2, v50
	s_cbranch_vccnz .LBB0_353
	v_lshl_add_u64 v[42:43], v[148:149], 0, v[0:1]
	global_load_dwordx4 v[50:53], v[42:43], off
	global_load_dwordx4 v[46:49], v[42:43], off offset:16
	v_lshl_add_u64 v[42:43], v[150:151], 0, v[0:1]
	global_load_dwordx4 v[54:57], v[42:43], off
	s_nop 0
	global_load_dwordx4 v[42:45], v[42:43], off offset:16
	v_and_b32_e32 v61, 64, v213
	v_xor_b32_e32 v59, 32, v213
	v_add_u32_e32 v61, 64, v61
	v_cmp_lt_i32_e32 vcc, v59, v61
	v_mov_b32_e32 v74, v62
	s_waitcnt vmcnt(0)
	v_pk_mul_f32 v[50:51], v[70:71], v[50:51]
	v_cndmask_b32_e32 v59, v213, v59, vcc
	v_lshlrev_b32_e32 v59, 2, v59
	ds_bpermute_b32 v61, v59, v62
	v_mov_b32_e32 v75, v42
	v_mov_b32_e32 v68, v46
	ds_bpermute_b32 v72, v59, v70
	ds_bpermute_b32 v73, v59, v71
	s_waitcnt lgkmcnt(0)
	v_mul_f32_e32 v69, v146, v61
	v_mul_f32_e32 v42, v42, v69
	v_pk_fma_f32 v[68:69], v[74:75], v[68:69], v[42:43] op_sel_hi:[1,1,0]
	ds_bpermute_b32 v42, v59, v63
	v_pk_mul_f32 v[70:71], v[146:147], v[72:73]
	v_mov_b32_e32 v72, v47
	v_mul_f32_e32 v46, v63, v47
	v_mov_b32_e32 v74, v66
	s_waitcnt lgkmcnt(0)
	v_mul_f32_e32 v73, v146, v42
	v_mov_b32_e32 v42, v63
	v_pk_fma_f32 v[62:63], v[42:43], v[72:73], v[46:47] op_sel_hi:[1,1,0]
	ds_bpermute_b32 v43, v59, v64
	ds_bpermute_b32 v47, v59, v66
	v_mov_b32_e32 v75, v44
	v_mov_b32_e32 v72, v48
	v_mul_f32_e32 v42, v64, v52
	s_waitcnt lgkmcnt(1)
	v_mul_f32_e32 v43, v146, v43
	v_mul_f32_e32 v46, v56, v43
	ds_bpermute_b32 v43, v59, v65
	s_waitcnt lgkmcnt(1)
	v_mul_f32_e32 v73, v146, v47
	v_mul_f32_e32 v44, v44, v73
	v_pk_fma_f32 v[72:73], v[74:75], v[72:73], v[44:45] op_sel_hi:[1,1,0]
	ds_bpermute_b32 v44, v59, v67
	s_waitcnt lgkmcnt(1)
	v_mul_f32_e32 v75, v146, v43
	v_mov_b32_e32 v56, v65
	v_mov_b32_e32 v74, v53
	v_pk_mul_f32 v[52:53], v[56:57], v[74:75]
	v_pk_fma_f32 v[70:71], v[54:55], v[70:71], v[50:51]
	v_mov_b32_e32 v43, v52
	v_mov_b32_e32 v47, v53
	v_pk_add_f32 v[64:65], v[42:43], v[46:47]
	s_waitcnt lgkmcnt(0)
	v_mul_f32_e32 v43, v146, v44
	v_mov_b32_e32 v44, v67
	v_mov_b32_e32 v42, v49
	v_mul_f32_e32 v46, v45, v43
	v_pk_fma_f32 v[42:43], v[44:45], v[42:43], v[46:47] op_sel_hi:[1,1,0]
	v_mov_b32_e32 v62, v68
	v_mov_b32_e32 v66, v72
	v_mov_b32_e32 v67, v42
.LBB0_353:
	v_mov_b64_e32 v[42:43], s[92:93]
	v_mad_i64_i32 v[42:43], s[0:1], v58, s37, v[42:43]
	v_lshl_add_u64 v[50:51], v[130:131], 1, v[42:43]
	v_cvt_pk_bf16_f32 v42, v70, v71
	v_cvt_pk_bf16_f32 v43, v64, v65
	v_cvt_pk_bf16_f32 v44, v62, v63
	v_cvt_pk_bf16_f32 v45, v66, v67
	v_mov_b32_e32 v61, v60
	global_store_dwordx4 v[50:51], v[42:45], off sc0 sc1
	v_pk_mul_f32 v[62:63], v[38:39], v[60:61]
	s_and_b64 vcc, exec, s[42:43]
	v_mov_b32_e32 v42, v60
	v_mov_b32_e32 v43, v60
	v_pk_mul_f32 v[52:53], v[40:41], v[42:43]
	v_pk_mul_f32 v[56:57], v[36:37], v[42:43]
	v_pk_mul_f32 v[54:55], v[34:35], v[60:61]
	s_cbranch_vccnz .LBB0_355
	v_lshl_add_u64 v[34:35], v[148:149], 0, v[0:1]
	global_load_dwordx4 v[42:45], v[34:35], off
	global_load_dwordx4 v[38:41], v[34:35], off offset:16
	v_lshl_add_u64 v[34:35], v[150:151], 0, v[0:1]
	global_load_dwordx4 v[46:49], v[34:35], off
	s_nop 0
	global_load_dwordx4 v[34:37], v[34:35], off offset:16
	v_and_b32_e32 v58, 64, v213
	v_xor_b32_e32 v0, 32, v213
	v_add_u32_e32 v58, 64, v58
	v_cmp_lt_i32_e32 vcc, v0, v58
	v_mov_b32_e32 v64, v54
	s_waitcnt vmcnt(0)
	v_pk_mul_f32 v[42:43], v[62:63], v[42:43]
	v_cndmask_b32_e32 v0, v213, v0, vcc
	v_lshlrev_b32_e32 v66, 2, v0
	ds_bpermute_b32 v0, v66, v54
	v_mov_b32_e32 v65, v34
	v_mov_b32_e32 v58, v38
	ds_bpermute_b32 v60, v66, v62
	ds_bpermute_b32 v61, v66, v63
	s_waitcnt lgkmcnt(0)
	v_mul_f32_e32 v59, v146, v0
	v_mul_f32_e32 v0, v34, v59
	v_pk_fma_f32 v[58:59], v[64:65], v[58:59], v[0:1] op_sel_hi:[1,1,0]
	ds_bpermute_b32 v0, v66, v55
	v_mov_b32_e32 v34, v55
	v_mov_b32_e32 v62, v39
	v_mov_b32_e32 v64, v56
	v_mov_b32_e32 v65, v36
	s_waitcnt lgkmcnt(0)
	v_mul_f32_e32 v63, v146, v0
	v_mul_f32_e32 v0, v55, v39
	v_pk_fma_f32 v[54:55], v[34:35], v[62:63], v[0:1] op_sel_hi:[1,1,0]
	ds_bpermute_b32 v0, v66, v52
	ds_bpermute_b32 v35, v66, v56
	v_mov_b32_e32 v62, v40
	v_mul_f32_e32 v34, v52, v44
	v_pk_mul_f32 v[60:61], v[146:147], v[60:61]
	s_waitcnt lgkmcnt(1)
	v_mul_f32_e32 v0, v146, v0
	s_waitcnt lgkmcnt(0)
	v_mul_f32_e32 v63, v146, v35
	v_mul_f32_e32 v38, v48, v0
	v_mul_f32_e32 v0, v36, v63
	v_pk_fma_f32 v[64:65], v[64:65], v[62:63], v[0:1] op_sel_hi:[1,1,0]
	ds_bpermute_b32 v0, v66, v53
	ds_bpermute_b32 v36, v66, v57
	v_mov_b32_e32 v48, v53
	v_mov_b32_e32 v62, v45
	v_mov_b32_e32 v54, v58
	s_waitcnt lgkmcnt(1)
	v_mul_f32_e32 v63, v146, v0
	v_pk_mul_f32 v[44:45], v[48:49], v[62:63]
	v_pk_fma_f32 v[62:63], v[46:47], v[60:61], v[42:43]
	v_mov_b32_e32 v35, v44
	v_mov_b32_e32 v39, v45
	v_pk_add_f32 v[52:53], v[34:35], v[38:39]
	s_waitcnt lgkmcnt(0)
	v_mul_f32_e32 v35, v146, v36
	v_mov_b32_e32 v36, v57
	v_mov_b32_e32 v34, v41
	v_mul_f32_e32 v0, v37, v35
	v_pk_fma_f32 v[34:35], v[36:37], v[34:35], v[0:1] op_sel_hi:[1,1,0]
	v_mov_b32_e32 v56, v64
	v_mov_b32_e32 v57, v34
; __device__ __forceinline__ unsigned cvtpk(float lo, float hi) { f32x2 v = {lo, hi}; bf16x2_t b = __builtin_convertvector(v, bf16x2_t); return __builtin_bit_cast(unsigned, b); }
; __device__ __forceinline__ void rope8(f32x4& v0, f32x4& v1, const float* cosr, const float* sinr, int fq) {
;     const int j0 = 8 * (fq & 1);
;     const f32x4 c0 = *(const f32x4*)(cosr + j0), c1 = *(const f32x4*)(cosr + j0 + 4), s0 = *(const f32x4*)(sinr + j0), s1 = *(const f32x4*)(sinr + j0 + 4);
;     const float sg = (fq < 2) ? -1.f : 1.f;
; #pragma unroll
;     for (int i = 0; i < 4; ++i) {
;         const float p0 = __shfl_xor(v0[i], 32), p1 = __shfl_xor(v1[i], 32);
;         v0[i] = v0[i] * c0[i] + sg * p0 * s0[i]; v1[i] = v1[i] * c1[i] + sg * p1 * s1[i];
;     }
;     __device__ __forceinline__ void operator()(AccRef acc, const Unit& u, int wr, int wc, int fr, int fq) const {
;     ...
;                 const int row = row0 + ai * 128 + m * 16;
;                 const float rs = rsqrtf(ssq_sum<NS>(ssq + (size_t)row * NS) * inv_n + EPS);
;                 bf16_t* rowp = O + (size_t)row * ldc + col0;
; #pragma unroll
;                 for (int bj = 0; bj < 2; ++bj) {
;                     f32x4 v0 = acc[ai][bj][m][0] * rs, v1 = acc[ai][bj][m][1] * rs;
;                     if (ROPE) { const int g32 = u.pn * 8 + bj * 4 + wc; if (g32 % 3 == 2) { const int pos = row & (SEQ - 1); rope8(v0, v1, cost + pos * 16, sint + pos * 16, fq); } }
;                     u32x4 w; w.x = cvtpk(v0[0], v0[1]); w.y = cvtpk(v0[2], v0[3]); w.z = cvtpk(v1[0], v1[1]); w.w = cvtpk(v1[2], v1[3]);
;                     st16_wt(rowp + bj * 128, w);
.LBB0_355:
	v_add_u32_e32 v42, 0xa0, v156
	v_cvt_pk_bf16_f32 v34, v62, v63
	v_cvt_pk_bf16_f32 v35, v52, v53
	v_cvt_pk_bf16_f32 v36, v54, v55
	v_cvt_pk_bf16_f32 v37, v56, v57
	v_ashrrev_i32_e32 v43, 31, v42
	global_store_dwordx4 v[50:51], v[34:37], off offset:256 sc0 sc1
	s_and_b64 vcc, exec, s[40:41]
	s_nop 0
	v_lshlrev_b64 v[34:35], 5, v[42:43]
	v_and_b32_e32 v38, 0x1fff, v34
	v_add_u32_e32 v38, 0x21400, v38
	ds_read_b128 v[34:37], v38
	s_nop 0
	ds_read_b128 v[38:41], v38 offset:16
	s_waitcnt lgkmcnt(0)
	v_mov_b32_e32 v44, v34
	v_mov_b32_e32 v45, v38
	v_mov_b32_e32 v38, v35
	v_mov_b32_e32 v34, v36
	v_mov_b32_e32 v35, v40
	v_mov_b32_e32 v40, v37
	v_pk_add_f32 v[36:37], v[44:45], v[38:39]
	v_pk_add_f32 v[34:35], v[34:35], v[40:41]
	s_nop 0
	v_pk_add_f32 v[34:35], v[36:37], v[34:35]
	s_nop 0
	v_add_f32_e32 v0, 0, v34
	v_add_f32_e32 v0, v0, v35
	v_fmamk_f32 v0, v0, 0x3b800000, v212
	v_mul_f32_e32 v34, 0x4b800000, v0
	v_cmp_gt_f32_e64 s[44:45], s69, v0
	s_nop 1
	v_cndmask_b32_e64 v0, v0, v34, s[44:45]
	v_rsq_f32_e32 v0, v0
	v_lshlrev_b32_e32 v34, 4, v42
	v_and_b32_e32 v34, 0x7ef0, v34
	v_mul_f32_e32 v35, 0x45800000, v0
	v_cndmask_b32_e64 v44, v0, v35, s[44:45]
	v_pk_mul_f32 v[48:49], v[32:33], v[44:45] op_sel_hi:[1,0]
	v_pk_mul_f32 v[54:55], v[30:31], v[44:45] op_sel_hi:[1,0]
	v_pk_mul_f32 v[50:51], v[28:29], v[44:45] op_sel_hi:[1,0]
	v_pk_mul_f32 v[46:47], v[26:27], v[44:45] op_sel_hi:[1,0]
	v_lshlrev_b32_e32 v0, 2, v34
	s_cbranch_vccnz .LBB0_357
	v_lshl_add_u64 v[26:27], v[148:149], 0, v[0:1]
	global_load_dwordx4 v[34:37], v[26:27], off
	global_load_dwordx4 v[30:33], v[26:27], off offset:16
	v_lshl_add_u64 v[26:27], v[150:151], 0, v[0:1]
	global_load_dwordx4 v[38:41], v[26:27], off
	s_nop 0
	global_load_dwordx4 v[26:29], v[26:27], off offset:16
	v_and_b32_e32 v45, 64, v213
	v_xor_b32_e32 v43, 32, v213
	v_add_u32_e32 v45, 64, v45
	v_cmp_lt_i32_e32 vcc, v43, v45
	v_mov_b32_e32 v58, v46
	s_waitcnt vmcnt(0)
	v_pk_mul_f32 v[34:35], v[54:55], v[34:35]
	v_cndmask_b32_e32 v43, v213, v43, vcc
	v_lshlrev_b32_e32 v43, 2, v43
	ds_bpermute_b32 v45, v43, v46
	v_mov_b32_e32 v59, v26
	v_mov_b32_e32 v52, v30
	ds_bpermute_b32 v56, v43, v54
	ds_bpermute_b32 v57, v43, v55
	s_waitcnt lgkmcnt(0)
	v_mul_f32_e32 v53, v146, v45
	v_mul_f32_e32 v26, v26, v53
	v_pk_fma_f32 v[52:53], v[58:59], v[52:53], v[26:27] op_sel_hi:[1,1,0]
	ds_bpermute_b32 v26, v43, v47
	v_pk_mul_f32 v[54:55], v[146:147], v[56:57]
	v_mov_b32_e32 v56, v31
	v_mul_f32_e32 v30, v47, v31
	v_mov_b32_e32 v58, v50
	s_waitcnt lgkmcnt(0)
	v_mul_f32_e32 v57, v146, v26
	v_mov_b32_e32 v26, v47
	v_pk_fma_f32 v[46:47], v[26:27], v[56:57], v[30:31] op_sel_hi:[1,1,0]
	ds_bpermute_b32 v27, v43, v48
	ds_bpermute_b32 v31, v43, v50
	v_mov_b32_e32 v59, v28
	v_mov_b32_e32 v56, v32
	v_mul_f32_e32 v26, v48, v36
	s_waitcnt lgkmcnt(1)
	v_mul_f32_e32 v27, v146, v27
	v_mul_f32_e32 v30, v40, v27
	ds_bpermute_b32 v27, v43, v49
	s_waitcnt lgkmcnt(1)
	v_mul_f32_e32 v57, v146, v31
	v_mul_f32_e32 v28, v28, v57
	v_pk_fma_f32 v[56:57], v[58:59], v[56:57], v[28:29] op_sel_hi:[1,1,0]
	ds_bpermute_b32 v28, v43, v51
	s_waitcnt lgkmcnt(1)
	v_mul_f32_e32 v59, v146, v27
	v_mov_b32_e32 v40, v49
	v_mov_b32_e32 v58, v37
	v_pk_mul_f32 v[36:37], v[40:41], v[58:59]
	v_pk_fma_f32 v[54:55], v[38:39], v[54:55], v[34:35]
	v_mov_b32_e32 v27, v36
	v_mov_b32_e32 v31, v37
	v_pk_add_f32 v[48:49], v[26:27], v[30:31]
	s_waitcnt lgkmcnt(0)
	v_mul_f32_e32 v27, v146, v28
	v_mov_b32_e32 v28, v51
	v_mov_b32_e32 v26, v33
	v_mul_f32_e32 v30, v29, v27
	v_pk_fma_f32 v[26:27], v[28:29], v[26:27], v[30:31] op_sel_hi:[1,1,0]
	v_mov_b32_e32 v46, v52
	v_mov_b32_e32 v50, v56
	v_mov_b32_e32 v51, v26
.LBB0_357:
	v_mov_b64_e32 v[26:27], s[92:93]
	v_mad_i64_i32 v[26:27], s[0:1], v42, s37, v[26:27]
	v_lshl_add_u64 v[34:35], v[130:131], 1, v[26:27]
	v_cvt_pk_bf16_f32 v26, v54, v55
	v_cvt_pk_bf16_f32 v27, v48, v49
	v_cvt_pk_bf16_f32 v28, v46, v47
	v_cvt_pk_bf16_f32 v29, v50, v51
	v_mov_b32_e32 v45, v44
	global_store_dwordx4 v[34:35], v[26:29], off sc0 sc1
	v_pk_mul_f32 v[46:47], v[22:23], v[44:45]
	s_and_b64 vcc, exec, s[42:43]
	v_mov_b32_e32 v26, v44
	v_mov_b32_e32 v27, v44
	v_pk_mul_f32 v[36:37], v[24:25], v[26:27]
	v_pk_mul_f32 v[40:41], v[20:21], v[26:27]
	v_pk_mul_f32 v[38:39], v[18:19], v[44:45]
	s_cbranch_vccnz .LBB0_359
	v_lshl_add_u64 v[18:19], v[148:149], 0, v[0:1]
	global_load_dwordx4 v[26:29], v[18:19], off
	global_load_dwordx4 v[22:25], v[18:19], off offset:16
	v_lshl_add_u64 v[18:19], v[150:151], 0, v[0:1]
	global_load_dwordx4 v[30:33], v[18:19], off
	s_nop 0
	global_load_dwordx4 v[18:21], v[18:19], off offset:16
	v_and_b32_e32 v42, 64, v213
	v_xor_b32_e32 v0, 32, v213
	v_add_u32_e32 v42, 64, v42
	v_cmp_lt_i32_e32 vcc, v0, v42
	v_mov_b32_e32 v48, v38
	s_waitcnt vmcnt(0)
	v_pk_mul_f32 v[26:27], v[46:47], v[26:27]
	v_cndmask_b32_e32 v0, v213, v0, vcc
	v_lshlrev_b32_e32 v50, 2, v0
	ds_bpermute_b32 v0, v50, v38
	v_mov_b32_e32 v49, v18
	v_mov_b32_e32 v42, v22
	ds_bpermute_b32 v44, v50, v46
	ds_bpermute_b32 v45, v50, v47
	s_waitcnt lgkmcnt(0)
	v_mul_f32_e32 v43, v146, v0
	v_mul_f32_e32 v0, v18, v43
	v_pk_fma_f32 v[42:43], v[48:49], v[42:43], v[0:1] op_sel_hi:[1,1,0]
	ds_bpermute_b32 v0, v50, v39
	v_mov_b32_e32 v18, v39
	v_mov_b32_e32 v46, v23
	v_mov_b32_e32 v48, v40
	v_mov_b32_e32 v49, v20
	s_waitcnt lgkmcnt(0)
	v_mul_f32_e32 v47, v146, v0
	v_mul_f32_e32 v0, v39, v23
	v_pk_fma_f32 v[38:39], v[18:19], v[46:47], v[0:1] op_sel_hi:[1,1,0]
	ds_bpermute_b32 v0, v50, v36
	ds_bpermute_b32 v19, v50, v40
	v_mov_b32_e32 v46, v24
	v_mul_f32_e32 v18, v36, v28
	v_pk_mul_f32 v[44:45], v[146:147], v[44:45]
	s_waitcnt lgkmcnt(1)
	v_mul_f32_e32 v0, v146, v0
	s_waitcnt lgkmcnt(0)
	v_mul_f32_e32 v47, v146, v19
	v_mul_f32_e32 v22, v32, v0
	v_mul_f32_e32 v0, v20, v47
	v_pk_fma_f32 v[48:49], v[48:49], v[46:47], v[0:1] op_sel_hi:[1,1,0]
	ds_bpermute_b32 v0, v50, v37
	ds_bpermute_b32 v20, v50, v41
	v_mov_b32_e32 v32, v37
	v_mov_b32_e32 v46, v29
	v_mov_b32_e32 v38, v42
	s_waitcnt lgkmcnt(1)
	v_mul_f32_e32 v47, v146, v0
	v_pk_mul_f32 v[28:29], v[32:33], v[46:47]
	v_pk_fma_f32 v[46:47], v[30:31], v[44:45], v[26:27]
	v_mov_b32_e32 v19, v28
	v_mov_b32_e32 v23, v29
	v_pk_add_f32 v[36:37], v[18:19], v[22:23]
	s_waitcnt lgkmcnt(0)
	v_mul_f32_e32 v19, v146, v20
	v_mov_b32_e32 v20, v41
	v_mov_b32_e32 v18, v25
	v_mul_f32_e32 v0, v21, v19
	v_pk_fma_f32 v[18:19], v[20:21], v[18:19], v[0:1] op_sel_hi:[1,1,0]
	v_mov_b32_e32 v40, v48
	v_mov_b32_e32 v41, v18
; __device__ __forceinline__ unsigned cvtpk(float lo, float hi) { f32x2 v = {lo, hi}; bf16x2_t b = __builtin_convertvector(v, bf16x2_t); return __builtin_bit_cast(unsigned, b); }
; __device__ __forceinline__ void rope8(f32x4& v0, f32x4& v1, const float* cosr, const float* sinr, int fq) {
;     const int j0 = 8 * (fq & 1);
;     const f32x4 c0 = *(const f32x4*)(cosr + j0), c1 = *(const f32x4*)(cosr + j0 + 4), s0 = *(const f32x4*)(sinr + j0), s1 = *(const f32x4*)(sinr + j0 + 4);
;     const float sg = (fq < 2) ? -1.f : 1.f;
; #pragma unroll
;     for (int i = 0; i < 4; ++i) {
;         const float p0 = __shfl_xor(v0[i], 32), p1 = __shfl_xor(v1[i], 32);
;         v0[i] = v0[i] * c0[i] + sg * p0 * s0[i]; v1[i] = v1[i] * c1[i] + sg * p1 * s1[i];
;     }
;     __device__ __forceinline__ void operator()(AccRef acc, const Unit& u, int wr, int wc, int fr, int fq) const {
;     ...
;                 const int row = row0 + ai * 128 + m * 16;
;                 const float rs = rsqrtf(ssq_sum<NS>(ssq + (size_t)row * NS) * inv_n + EPS);
;                 bf16_t* rowp = O + (size_t)row * ldc + col0;
; #pragma unroll
;                 for (int bj = 0; bj < 2; ++bj) {
;                     f32x4 v0 = acc[ai][bj][m][0] * rs, v1 = acc[ai][bj][m][1] * rs;
;                     if (ROPE) { const int g32 = u.pn * 8 + bj * 4 + wc; if (g32 % 3 == 2) { const int pos = row & (SEQ - 1); rope8(v0, v1, cost + pos * 16, sint + pos * 16, fq); } }
;                     u32x4 w; w.x = cvtpk(v0[0], v0[1]); w.y = cvtpk(v0[2], v0[3]); w.z = cvtpk(v1[0], v1[1]); w.w = cvtpk(v1[2], v1[3]);
;                     st16_wt(rowp + bj * 128, w);
.LBB0_359:
	v_add_u32_e32 v26, 0xb0, v156
	v_cvt_pk_bf16_f32 v18, v46, v47
	v_cvt_pk_bf16_f32 v19, v36, v37
	v_cvt_pk_bf16_f32 v20, v38, v39
	v_cvt_pk_bf16_f32 v21, v40, v41
	v_ashrrev_i32_e32 v27, 31, v26
	global_store_dwordx4 v[34:35], v[18:21], off offset:256 sc0 sc1
	s_and_b64 vcc, exec, s[40:41]
	s_nop 0
	v_lshlrev_b64 v[18:19], 5, v[26:27]
	v_and_b32_e32 v22, 0x1fff, v18
	v_add_u32_e32 v22, 0x21400, v22
	ds_read_b128 v[18:21], v22
	s_nop 0
	ds_read_b128 v[22:25], v22 offset:16
	s_waitcnt lgkmcnt(0)
	v_mov_b32_e32 v28, v18
	v_mov_b32_e32 v29, v22
	v_mov_b32_e32 v22, v19
	v_mov_b32_e32 v18, v20
	v_mov_b32_e32 v19, v24
	v_mov_b32_e32 v24, v21
	v_pk_add_f32 v[20:21], v[28:29], v[22:23]
	v_pk_add_f32 v[18:19], v[18:19], v[24:25]
	s_nop 0
	v_pk_add_f32 v[18:19], v[20:21], v[18:19]
	s_nop 0
	v_add_f32_e32 v0, 0, v18
	v_add_f32_e32 v0, v0, v19
	v_fmamk_f32 v0, v0, 0x3b800000, v212
	v_mul_f32_e32 v18, 0x4b800000, v0
	v_cmp_gt_f32_e64 s[44:45], s69, v0
	s_nop 1
	v_cndmask_b32_e64 v0, v0, v18, s[44:45]
	v_rsq_f32_e32 v0, v0
	v_lshlrev_b32_e32 v18, 4, v26
	v_and_b32_e32 v18, 0x7ff0, v18
	v_mul_f32_e32 v19, 0x45800000, v0
	v_cndmask_b32_e64 v28, v0, v19, s[44:45]
	v_pk_mul_f32 v[32:33], v[16:17], v[28:29] op_sel_hi:[1,0]
	v_pk_mul_f32 v[38:39], v[14:15], v[28:29] op_sel_hi:[1,0]
	v_pk_mul_f32 v[34:35], v[12:13], v[28:29] op_sel_hi:[1,0]
	v_pk_mul_f32 v[30:31], v[10:11], v[28:29] op_sel_hi:[1,0]
	v_lshlrev_b32_e32 v0, 2, v18
	s_cbranch_vccnz .LBB0_361
	v_lshl_add_u64 v[10:11], v[148:149], 0, v[0:1]
	global_load_dwordx4 v[18:21], v[10:11], off
	global_load_dwordx4 v[14:17], v[10:11], off offset:16
	v_lshl_add_u64 v[10:11], v[150:151], 0, v[0:1]
	global_load_dwordx4 v[22:25], v[10:11], off
	s_nop 0
	global_load_dwordx4 v[10:13], v[10:11], off offset:16
	v_and_b32_e32 v29, 64, v213
	v_xor_b32_e32 v27, 32, v213
	v_add_u32_e32 v29, 64, v29
	v_cmp_lt_i32_e32 vcc, v27, v29
	v_mov_b32_e32 v42, v30
	s_waitcnt vmcnt(0)
	v_pk_mul_f32 v[18:19], v[38:39], v[18:19]
	v_cndmask_b32_e32 v27, v213, v27, vcc
	v_lshlrev_b32_e32 v27, 2, v27
	ds_bpermute_b32 v29, v27, v30
	v_mov_b32_e32 v43, v10
	v_mov_b32_e32 v36, v14
	ds_bpermute_b32 v40, v27, v38
	ds_bpermute_b32 v41, v27, v39
	s_waitcnt lgkmcnt(0)
	v_mul_f32_e32 v37, v146, v29
	v_mul_f32_e32 v10, v10, v37
	v_pk_fma_f32 v[36:37], v[42:43], v[36:37], v[10:11] op_sel_hi:[1,1,0]
	ds_bpermute_b32 v10, v27, v31
	v_pk_mul_f32 v[38:39], v[146:147], v[40:41]
	v_mov_b32_e32 v40, v15
	v_mul_f32_e32 v14, v31, v15
	v_mov_b32_e32 v42, v34
	s_waitcnt lgkmcnt(0)
	v_mul_f32_e32 v41, v146, v10
	v_mov_b32_e32 v10, v31
	v_pk_fma_f32 v[30:31], v[10:11], v[40:41], v[14:15] op_sel_hi:[1,1,0]
	ds_bpermute_b32 v11, v27, v32
	ds_bpermute_b32 v15, v27, v34
	v_mov_b32_e32 v43, v12
	v_mov_b32_e32 v40, v16
	v_mul_f32_e32 v10, v32, v20
	s_waitcnt lgkmcnt(1)
	v_mul_f32_e32 v11, v146, v11
	v_mul_f32_e32 v14, v24, v11
	ds_bpermute_b32 v11, v27, v33
	s_waitcnt lgkmcnt(1)
	v_mul_f32_e32 v41, v146, v15
	v_mul_f32_e32 v12, v12, v41
	v_pk_fma_f32 v[40:41], v[42:43], v[40:41], v[12:13] op_sel_hi:[1,1,0]
	ds_bpermute_b32 v12, v27, v35
	s_waitcnt lgkmcnt(1)
	v_mul_f32_e32 v43, v146, v11
	v_mov_b32_e32 v24, v33
	v_mov_b32_e32 v42, v21
	v_pk_mul_f32 v[20:21], v[24:25], v[42:43]
	v_pk_fma_f32 v[38:39], v[22:23], v[38:39], v[18:19]
	v_mov_b32_e32 v11, v20
	v_mov_b32_e32 v15, v21
	v_pk_add_f32 v[32:33], v[10:11], v[14:15]
	s_waitcnt lgkmcnt(0)
	v_mul_f32_e32 v11, v146, v12
	v_mov_b32_e32 v12, v35
	v_mov_b32_e32 v10, v17
	v_mul_f32_e32 v14, v13, v11
	v_pk_fma_f32 v[10:11], v[12:13], v[10:11], v[14:15] op_sel_hi:[1,1,0]
	v_mov_b32_e32 v30, v36
	v_mov_b32_e32 v34, v40
	v_mov_b32_e32 v35, v10
.LBB0_361:
	v_mov_b64_e32 v[10:11], s[92:93]
	v_mad_i64_i32 v[10:11], s[0:1], v26, s37, v[10:11]
	v_lshl_add_u64 v[18:19], v[130:131], 1, v[10:11]
	v_cvt_pk_bf16_f32 v10, v38, v39
	v_cvt_pk_bf16_f32 v11, v32, v33
	v_cvt_pk_bf16_f32 v12, v30, v31
	v_cvt_pk_bf16_f32 v13, v34, v35
	v_mov_b32_e32 v29, v28
	global_store_dwordx4 v[18:19], v[10:13], off sc0 sc1
	v_pk_mul_f32 v[30:31], v[6:7], v[28:29]
	s_and_b64 vcc, exec, s[42:43]
	v_mov_b32_e32 v10, v28
	v_mov_b32_e32 v11, v28
	v_pk_mul_f32 v[20:21], v[8:9], v[10:11]
	v_pk_mul_f32 v[24:25], v[4:5], v[10:11]
	v_pk_mul_f32 v[22:23], v[2:3], v[28:29]
	s_cbranch_vccnz .LBB0_363
	v_lshl_add_u64 v[2:3], v[148:149], 0, v[0:1]
	global_load_dwordx4 v[10:13], v[2:3], off
	global_load_dwordx4 v[6:9], v[2:3], off offset:16
	v_lshl_add_u64 v[2:3], v[150:151], 0, v[0:1]
	global_load_dwordx4 v[14:17], v[2:3], off
	s_nop 0
	global_load_dwordx4 v[2:5], v[2:3], off offset:16
	v_and_b32_e32 v26, 64, v213
	v_xor_b32_e32 v0, 32, v213
	v_add_u32_e32 v26, 64, v26
	v_cmp_lt_i32_e32 vcc, v0, v26
	v_mov_b32_e32 v32, v22
	s_waitcnt vmcnt(0)
	v_pk_mul_f32 v[10:11], v[30:31], v[10:11]
	v_cndmask_b32_e32 v0, v213, v0, vcc
	v_lshlrev_b32_e32 v34, 2, v0
	ds_bpermute_b32 v0, v34, v22
	v_mov_b32_e32 v33, v2
	v_mov_b32_e32 v26, v6
	ds_bpermute_b32 v28, v34, v30
	ds_bpermute_b32 v29, v34, v31
	s_waitcnt lgkmcnt(0)
	v_mul_f32_e32 v27, v146, v0
	v_mul_f32_e32 v0, v2, v27
	v_pk_fma_f32 v[26:27], v[32:33], v[26:27], v[0:1] op_sel_hi:[1,1,0]
	ds_bpermute_b32 v0, v34, v23
	v_mov_b32_e32 v2, v23
	v_mov_b32_e32 v30, v7
	v_mov_b32_e32 v32, v24
	v_mov_b32_e32 v33, v4
	s_waitcnt lgkmcnt(0)
	v_mul_f32_e32 v31, v146, v0
	v_mul_f32_e32 v0, v23, v7
	v_pk_fma_f32 v[22:23], v[2:3], v[30:31], v[0:1] op_sel_hi:[1,1,0]
	ds_bpermute_b32 v0, v34, v20
	ds_bpermute_b32 v3, v34, v24
	v_mov_b32_e32 v30, v8
	v_mul_f32_e32 v2, v20, v12
	v_pk_mul_f32 v[28:29], v[146:147], v[28:29]
	s_waitcnt lgkmcnt(1)
	v_mul_f32_e32 v0, v146, v0
	s_waitcnt lgkmcnt(0)
	v_mul_f32_e32 v31, v146, v3
	v_mul_f32_e32 v6, v16, v0
	v_mul_f32_e32 v0, v4, v31
	v_pk_fma_f32 v[32:33], v[32:33], v[30:31], v[0:1] op_sel_hi:[1,1,0]
	ds_bpermute_b32 v0, v34, v21
	ds_bpermute_b32 v4, v34, v25
	v_mov_b32_e32 v16, v21
	v_mov_b32_e32 v30, v13
	v_mov_b32_e32 v22, v26
	s_waitcnt lgkmcnt(1)
	v_mul_f32_e32 v31, v146, v0
	v_pk_mul_f32 v[12:13], v[16:17], v[30:31]
	v_pk_fma_f32 v[30:31], v[14:15], v[28:29], v[10:11]
	v_mov_b32_e32 v3, v12
	v_mov_b32_e32 v7, v13
	v_pk_add_f32 v[20:21], v[2:3], v[6:7]
	s_waitcnt lgkmcnt(0)
	v_mul_f32_e32 v3, v146, v4
	v_mov_b32_e32 v4, v25
	v_mov_b32_e32 v2, v9
	v_mul_f32_e32 v0, v5, v3
	v_pk_fma_f32 v[2:3], v[4:5], v[2:3], v[0:1] op_sel_hi:[1,1,0]
	v_mov_b32_e32 v24, v32
	v_mov_b32_e32 v25, v2
.LBB0_363:
	v_cvt_pk_bf16_f32 v2, v30, v31
	v_cvt_pk_bf16_f32 v3, v20, v21
	v_cvt_pk_bf16_f32 v4, v22, v23
	v_cvt_pk_bf16_f32 v5, v24, v25
	global_store_dwordx4 v[18:19], v[2:5], off offset:256 sc0 sc1
	s_and_b64 vcc, exec, s[38:39]
	s_mov_b64 s[0:1], -1
	s_cbranch_vccnz .LBB0_319
	s_andn2_b64 vcc, exec, s[62:63]
	s_cbranch_vccnz .LBB0_318
	s_barrier
	s_branch .LBB0_318

; __device__ __forceinline__ unsigned cvtpk(float lo, float hi) { f32x2 v = {lo, hi}; bf16x2_t b = __builtin_convertvector(v, bf16x2_t); return __builtin_bit_cast(unsigned, b); }
;     __device__ __forceinline__ void operator()(AccRef acc, const Unit& u, int wr, int wc, int fr, int fq) const {
;     ...
;                 const int row = row0 + ai * 128 + m * 16;
;                 const float rs = rsqrtf(ssq_sum<NS>(ssq + (size_t)row * NS) * inv_n + EPS);
;                 bf16_t* rowp = O + (size_t)row * ldc + col0;
; #pragma unroll
;                 for (int bj = 0; bj < 2; ++bj) {
;                     f32x4 v0 = acc[ai][bj][m][0] * rs, v1 = acc[ai][bj][m][1] * rs;
;                     if (ROPE) { const int g32 = u.pn * 8 + bj * 4 + wc; if (g32 % 3 == 2) { const int pos = row & (SEQ - 1); rope8(v0, v1, cost + pos * 16, sint + pos * 16, fq); } }
;                     u32x4 w; w.x = cvtpk(v0[0], v0[1]); w.y = cvtpk(v0[2], v0[3]); w.z = cvtpk(v1[0], v1[1]); w.w = cvtpk(v1[2], v1[3]);
;                     st16_wt(rowp + bj * 128, w);
.LBB0_388:
	v_lshl_add_u32 v144, s58, 8, v146
	v_ashrrev_i32_e32 v145, 31, v144
	v_and_b32_e32 v140, 0xff, v144
	v_lshlrev_b32_e32 v140, 4, v140
	v_add_u32_e32 v140, 0x21400, v140
	ds_read_b128 v[140:143], v140
	v_lshl_or_b32 v150, s55, 8, v148
	v_ashrrev_i32_e32 v151, 31, v150
	s_waitcnt lgkmcnt(0)
	v_mov_b32_e32 v152, v141
	v_mov_b32_e32 v153, v142
	v_mov_b32_e32 v141, v143
	v_pk_add_f32 v[140:141], v[152:153], v[140:141]
	v_lshlrev_b64 v[142:143], 1, v[150:151]
	v_add_f32_e32 v140, v140, v141
	v_add_f32_e32 v140, 0, v140
	v_fmamk_f32 v140, v140, 0x3c000000, v212
	v_cmp_gt_f32_e32 vcc, s69, v140
	v_mul_f32_e32 v141, 0x4b800000, v140
	s_nop 0
	v_cndmask_b32_e32 v140, v140, v141, vcc
	v_rsq_f32_e32 v140, v140
	s_nop 0
	v_mul_f32_e32 v141, 0x45800000, v140
	v_cndmask_b32_e32 v152, v140, v141, vcc
	v_mov_b64_e32 v[140:141], s[94:95]
	v_mad_i64_i32 v[154:155], s[20:21], v144, s33, v[140:141]
	v_pk_mul_f32 v[124:125], v[124:125], v[152:153] op_sel_hi:[1,0]
	v_pk_mul_f32 v[122:123], v[122:123], v[152:153] op_sel_hi:[1,0]
	v_pk_mul_f32 v[128:129], v[128:129], v[152:153] op_sel_hi:[1,0]
	v_pk_mul_f32 v[126:127], v[126:127], v[152:153] op_sel_hi:[1,0]
	v_lshl_add_u64 v[150:151], v[154:155], 0, v[142:143]
	v_cvt_pk_bf16_f32 v122, v122, v123
	v_cvt_pk_bf16_f32 v123, v124, v125
	v_cvt_pk_bf16_f32 v124, v126, v127
	v_cvt_pk_bf16_f32 v125, v128, v129
	global_store_dwordx4 v[150:151], v[122:125], off sc0 sc1
	v_pk_mul_f32 v[120:121], v[120:121], v[152:153] op_sel_hi:[1,0]
	v_pk_mul_f32 v[118:119], v[118:119], v[152:153] op_sel_hi:[1,0]
	v_pk_mul_f32 v[122:123], v[116:117], v[152:153] op_sel_hi:[1,0]
	v_pk_mul_f32 v[116:117], v[114:115], v[152:153] op_sel_hi:[1,0]
	v_cvt_pk_bf16_f32 v114, v118, v119
	v_cvt_pk_bf16_f32 v115, v120, v121
	v_cvt_pk_bf16_f32 v116, v116, v117
	v_cvt_pk_bf16_f32 v117, v122, v123
	v_or_b32_e32 v118, 16, v144
	global_store_dwordx4 v[150:151], v[114:117], off offset:256 sc0 sc1
	v_ashrrev_i32_e32 v119, 31, v118
	s_nop 0
	v_and_b32_e32 v114, 0xff, v118
	v_lshlrev_b32_e32 v114, 4, v114
	v_add_u32_e32 v114, 0x21400, v114
	ds_read_b128 v[114:117], v114
	s_waitcnt lgkmcnt(0)
	v_mov_b32_e32 v120, v115
	v_mov_b32_e32 v121, v116
	v_mov_b32_e32 v115, v117
	v_pk_add_f32 v[114:115], v[120:121], v[114:115]
	v_mad_i64_i32 v[116:117], s[20:21], v118, s33, v[140:141]
	v_add_f32_e32 v114, v114, v115
	v_add_f32_e32 v114, 0, v114
	v_fmamk_f32 v114, v114, 0x3c000000, v212
	v_cmp_gt_f32_e32 vcc, s69, v114
	v_mul_f32_e32 v115, 0x4b800000, v114
	v_lshl_add_u64 v[116:117], v[116:117], 0, v[142:143]
	v_cndmask_b32_e32 v114, v114, v115, vcc
	v_rsq_f32_e32 v114, v114
	s_nop 0
	v_mul_f32_e32 v115, 0x45800000, v114
	v_cndmask_b32_e32 v114, v114, v115, vcc
	v_pk_mul_f32 v[112:113], v[112:113], v[114:115] op_sel_hi:[1,0]
	v_pk_mul_f32 v[110:111], v[110:111], v[114:115] op_sel_hi:[1,0]
	v_pk_mul_f32 v[118:119], v[108:109], v[114:115] op_sel_hi:[1,0]
	v_pk_mul_f32 v[108:109], v[106:107], v[114:115] op_sel_hi:[1,0]
	v_cvt_pk_bf16_f32 v106, v110, v111
	v_cvt_pk_bf16_f32 v107, v112, v113
	v_cvt_pk_bf16_f32 v108, v108, v109
	v_cvt_pk_bf16_f32 v109, v118, v119
	global_store_dwordx4 v[116:117], v[106:109], off sc0 sc1
	v_pk_mul_f32 v[104:105], v[104:105], v[114:115] op_sel_hi:[1,0]
	v_pk_mul_f32 v[102:103], v[102:103], v[114:115] op_sel_hi:[1,0]
	v_pk_mul_f32 v[106:107], v[100:101], v[114:115] op_sel_hi:[1,0]
	v_pk_mul_f32 v[100:101], v[98:99], v[114:115] op_sel_hi:[1,0]
	v_cvt_pk_bf16_f32 v98, v102, v103
	v_cvt_pk_bf16_f32 v99, v104, v105
	v_cvt_pk_bf16_f32 v100, v100, v101
	v_cvt_pk_bf16_f32 v101, v106, v107
	v_or_b32_e32 v102, 32, v144
	global_store_dwordx4 v[116:117], v[98:101], off offset:256 sc0 sc1
	v_ashrrev_i32_e32 v103, 31, v102
	s_nop 0
	v_and_b32_e32 v98, 0xff, v102
	v_lshlrev_b32_e32 v98, 4, v98
	v_add_u32_e32 v98, 0x21400, v98
	ds_read_b128 v[98:101], v98
	s_waitcnt lgkmcnt(0)
	v_mov_b32_e32 v104, v99
	v_mov_b32_e32 v105, v100
	v_mov_b32_e32 v99, v101
	v_pk_add_f32 v[98:99], v[104:105], v[98:99]
	v_mad_i64_i32 v[100:101], s[20:21], v102, s33, v[140:141]
	v_add_f32_e32 v98, v98, v99
	v_add_f32_e32 v98, 0, v98
	v_fmamk_f32 v98, v98, 0x3c000000, v212
	v_cmp_gt_f32_e32 vcc, s69, v98
	v_mul_f32_e32 v99, 0x4b800000, v98
	v_lshl_add_u64 v[100:101], v[100:101], 0, v[142:143]
	v_cndmask_b32_e32 v98, v98, v99, vcc
	v_rsq_f32_e32 v98, v98
	s_nop 0
	v_mul_f32_e32 v99, 0x45800000, v98
	v_cndmask_b32_e32 v98, v98, v99, vcc
	v_pk_mul_f32 v[96:97], v[96:97], v[98:99] op_sel_hi:[1,0]
	v_pk_mul_f32 v[94:95], v[94:95], v[98:99] op_sel_hi:[1,0]
	v_pk_mul_f32 v[102:103], v[92:93], v[98:99] op_sel_hi:[1,0]
	v_pk_mul_f32 v[92:93], v[90:91], v[98:99] op_sel_hi:[1,0]
	v_cvt_pk_bf16_f32 v90, v94, v95
	v_cvt_pk_bf16_f32 v91, v96, v97
	v_cvt_pk_bf16_f32 v92, v92, v93
	v_cvt_pk_bf16_f32 v93, v102, v103
	global_store_dwordx4 v[100:101], v[90:93], off sc0 sc1
	v_pk_mul_f32 v[88:89], v[88:89], v[98:99] op_sel_hi:[1,0]
	v_pk_mul_f32 v[86:87], v[86:87], v[98:99] op_sel_hi:[1,0]
	v_pk_mul_f32 v[90:91], v[84:85], v[98:99] op_sel_hi:[1,0]
	v_pk_mul_f32 v[84:85], v[82:83], v[98:99] op_sel_hi:[1,0]
	v_cvt_pk_bf16_f32 v82, v86, v87
	v_cvt_pk_bf16_f32 v83, v88, v89
	v_cvt_pk_bf16_f32 v84, v84, v85
	v_cvt_pk_bf16_f32 v85, v90, v91
	v_or_b32_e32 v86, 48, v144
	global_store_dwordx4 v[100:101], v[82:85], off offset:256 sc0 sc1
	v_ashrrev_i32_e32 v87, 31, v86
	s_nop 0
	v_and_b32_e32 v82, 0xff, v86
	v_lshlrev_b32_e32 v82, 4, v82
	v_add_u32_e32 v82, 0x21400, v82
	ds_read_b128 v[82:85], v82
	s_waitcnt lgkmcnt(0)
; __device__ __forceinline__ unsigned cvtpk(float lo, float hi) { f32x2 v = {lo, hi}; bf16x2_t b = __builtin_convertvector(v, bf16x2_t); return __builtin_bit_cast(unsigned, b); }
;     __device__ __forceinline__ void operator()(AccRef acc, const Unit& u, int wr, int wc, int fr, int fq) const {
;     ...
;                 const int row = row0 + ai * 128 + m * 16;
;                 const float rs = rsqrtf(ssq_sum<NS>(ssq + (size_t)row * NS) * inv_n + EPS);
;                 bf16_t* rowp = O + (size_t)row * ldc + col0;
; #pragma unroll
;                 for (int bj = 0; bj < 2; ++bj) {
;                     f32x4 v0 = acc[ai][bj][m][0] * rs, v1 = acc[ai][bj][m][1] * rs;
;                     if (ROPE) { const int g32 = u.pn * 8 + bj * 4 + wc; if (g32 % 3 == 2) { const int pos = row & (SEQ - 1); rope8(v0, v1, cost + pos * 16, sint + pos * 16, fq); } }
;                     u32x4 w; w.x = cvtpk(v0[0], v0[1]); w.y = cvtpk(v0[2], v0[3]); w.z = cvtpk(v1[0], v1[1]); w.w = cvtpk(v1[2], v1[3]);
;                     st16_wt(rowp + bj * 128, w);
	v_mov_b32_e32 v88, v83
	v_mov_b32_e32 v89, v84
	v_mov_b32_e32 v83, v85
	v_pk_add_f32 v[82:83], v[88:89], v[82:83]
	v_mad_i64_i32 v[84:85], s[20:21], v86, s33, v[140:141]
	v_add_f32_e32 v82, v82, v83
	v_add_f32_e32 v82, 0, v82
	v_fmamk_f32 v82, v82, 0x3c000000, v212
	v_cmp_gt_f32_e32 vcc, s69, v82
	v_mul_f32_e32 v83, 0x4b800000, v82
	v_lshl_add_u64 v[84:85], v[84:85], 0, v[142:143]
	v_cndmask_b32_e32 v82, v82, v83, vcc
	v_rsq_f32_e32 v82, v82
	s_nop 0
	v_mul_f32_e32 v83, 0x45800000, v82
	v_cndmask_b32_e32 v82, v82, v83, vcc
	v_pk_mul_f32 v[80:81], v[80:81], v[82:83] op_sel_hi:[1,0]
	v_pk_mul_f32 v[78:79], v[78:79], v[82:83] op_sel_hi:[1,0]
	v_pk_mul_f32 v[86:87], v[76:77], v[82:83] op_sel_hi:[1,0]
	v_pk_mul_f32 v[76:77], v[74:75], v[82:83] op_sel_hi:[1,0]
	v_cvt_pk_bf16_f32 v74, v78, v79
	v_cvt_pk_bf16_f32 v75, v80, v81
	v_cvt_pk_bf16_f32 v76, v76, v77
	v_cvt_pk_bf16_f32 v77, v86, v87
	global_store_dwordx4 v[84:85], v[74:77], off sc0 sc1
	v_pk_mul_f32 v[72:73], v[72:73], v[82:83] op_sel_hi:[1,0]
	v_pk_mul_f32 v[70:71], v[70:71], v[82:83] op_sel_hi:[1,0]
	v_pk_mul_f32 v[74:75], v[68:69], v[82:83] op_sel_hi:[1,0]
	v_pk_mul_f32 v[68:69], v[66:67], v[82:83] op_sel_hi:[1,0]
	v_cvt_pk_bf16_f32 v66, v70, v71
	v_cvt_pk_bf16_f32 v67, v72, v73
	v_cvt_pk_bf16_f32 v68, v68, v69
	v_cvt_pk_bf16_f32 v69, v74, v75
	v_add_u32_e32 v70, 0x80, v144
	global_store_dwordx4 v[84:85], v[66:69], off offset:256 sc0 sc1
	v_ashrrev_i32_e32 v71, 31, v70
	s_nop 0
	v_and_b32_e32 v66, 0xff, v70
	v_lshlrev_b32_e32 v66, 4, v66
	v_add_u32_e32 v66, 0x21400, v66
	ds_read_b128 v[66:69], v66
	s_waitcnt lgkmcnt(0)
	v_mov_b32_e32 v72, v67
	v_mov_b32_e32 v73, v68
	v_mov_b32_e32 v67, v69
	v_pk_add_f32 v[66:67], v[72:73], v[66:67]
	v_mad_i64_i32 v[68:69], s[20:21], v70, s33, v[140:141]
	v_add_f32_e32 v66, v66, v67
	v_add_f32_e32 v66, 0, v66
	v_fmamk_f32 v66, v66, 0x3c000000, v212
	v_cmp_gt_f32_e32 vcc, s69, v66
	v_mul_f32_e32 v67, 0x4b800000, v66
	v_lshl_add_u64 v[68:69], v[68:69], 0, v[142:143]
	v_cndmask_b32_e32 v66, v66, v67, vcc
	v_rsq_f32_e32 v66, v66
	s_nop 0
	v_mul_f32_e32 v67, 0x45800000, v66
	v_cndmask_b32_e32 v66, v66, v67, vcc
	v_pk_mul_f32 v[64:65], v[64:65], v[66:67] op_sel_hi:[1,0]
	v_pk_mul_f32 v[62:63], v[62:63], v[66:67] op_sel_hi:[1,0]
	v_pk_mul_f32 v[70:71], v[60:61], v[66:67] op_sel_hi:[1,0]
	v_pk_mul_f32 v[60:61], v[58:59], v[66:67] op_sel_hi:[1,0]
	v_cvt_pk_bf16_f32 v58, v62, v63
	v_cvt_pk_bf16_f32 v59, v64, v65
	v_cvt_pk_bf16_f32 v60, v60, v61
	v_cvt_pk_bf16_f32 v61, v70, v71
	global_store_dwordx4 v[68:69], v[58:61], off sc0 sc1
	v_pk_mul_f32 v[56:57], v[56:57], v[66:67] op_sel_hi:[1,0]
	v_pk_mul_f32 v[54:55], v[54:55], v[66:67] op_sel_hi:[1,0]
	v_pk_mul_f32 v[58:59], v[52:53], v[66:67] op_sel_hi:[1,0]
	v_pk_mul_f32 v[52:53], v[50:51], v[66:67] op_sel_hi:[1,0]
	v_cvt_pk_bf16_f32 v50, v54, v55
	v_cvt_pk_bf16_f32 v51, v56, v57
	v_cvt_pk_bf16_f32 v52, v52, v53
	v_cvt_pk_bf16_f32 v53, v58, v59
	v_add_u32_e32 v54, 0x90, v144
	global_store_dwordx4 v[68:69], v[50:53], off offset:256 sc0 sc1
	v_ashrrev_i32_e32 v55, 31, v54
	s_nop 0
	v_and_b32_e32 v50, 0xff, v54
	v_lshlrev_b32_e32 v50, 4, v50
	v_add_u32_e32 v50, 0x21400, v50
	ds_read_b128 v[50:53], v50
	s_waitcnt lgkmcnt(0)
; __device__ __forceinline__ unsigned cvtpk(float lo, float hi) { f32x2 v = {lo, hi}; bf16x2_t b = __builtin_convertvector(v, bf16x2_t); return __builtin_bit_cast(unsigned, b); }
;     __device__ __forceinline__ void operator()(AccRef acc, const Unit& u, int wr, int wc, int fr, int fq) const {
;     ...
;                 const int row = row0 + ai * 128 + m * 16;
;                 const float rs = rsqrtf(ssq_sum<NS>(ssq + (size_t)row * NS) * inv_n + EPS);
;                 bf16_t* rowp = O + (size_t)row * ldc + col0;
; #pragma unroll
;                 for (int bj = 0; bj < 2; ++bj) {
;                     f32x4 v0 = acc[ai][bj][m][0] * rs, v1 = acc[ai][bj][m][1] * rs;
;                     if (ROPE) { const int g32 = u.pn * 8 + bj * 4 + wc; if (g32 % 3 == 2) { const int pos = row & (SEQ - 1); rope8(v0, v1, cost + pos * 16, sint + pos * 16, fq); } }
;                     u32x4 w; w.x = cvtpk(v0[0], v0[1]); w.y = cvtpk(v0[2], v0[3]); w.z = cvtpk(v1[0], v1[1]); w.w = cvtpk(v1[2], v1[3]);
;                     st16_wt(rowp + bj * 128, w);
	v_mov_b32_e32 v56, v51
	v_mov_b32_e32 v57, v52
	v_mov_b32_e32 v51, v53
	v_pk_add_f32 v[50:51], v[56:57], v[50:51]
	v_mad_i64_i32 v[52:53], s[20:21], v54, s33, v[140:141]
	v_add_f32_e32 v50, v50, v51
	v_add_f32_e32 v50, 0, v50
	v_fmamk_f32 v50, v50, 0x3c000000, v212
	v_cmp_gt_f32_e32 vcc, s69, v50
	v_mul_f32_e32 v51, 0x4b800000, v50
	v_lshl_add_u64 v[52:53], v[52:53], 0, v[142:143]
	v_cndmask_b32_e32 v50, v50, v51, vcc
	v_rsq_f32_e32 v50, v50
	s_nop 0
	v_mul_f32_e32 v51, 0x45800000, v50
	v_cndmask_b32_e32 v50, v50, v51, vcc
	v_pk_mul_f32 v[48:49], v[48:49], v[50:51] op_sel_hi:[1,0]
	v_pk_mul_f32 v[46:47], v[46:47], v[50:51] op_sel_hi:[1,0]
	v_pk_mul_f32 v[54:55], v[44:45], v[50:51] op_sel_hi:[1,0]
	v_pk_mul_f32 v[44:45], v[42:43], v[50:51] op_sel_hi:[1,0]
	v_cvt_pk_bf16_f32 v42, v46, v47
	v_cvt_pk_bf16_f32 v43, v48, v49
	v_cvt_pk_bf16_f32 v44, v44, v45
	v_cvt_pk_bf16_f32 v45, v54, v55
	global_store_dwordx4 v[52:53], v[42:45], off sc0 sc1
	v_pk_mul_f32 v[40:41], v[40:41], v[50:51] op_sel_hi:[1,0]
	v_pk_mul_f32 v[38:39], v[38:39], v[50:51] op_sel_hi:[1,0]
	v_pk_mul_f32 v[42:43], v[36:37], v[50:51] op_sel_hi:[1,0]
	v_pk_mul_f32 v[36:37], v[34:35], v[50:51] op_sel_hi:[1,0]
	v_cvt_pk_bf16_f32 v34, v38, v39
	v_cvt_pk_bf16_f32 v35, v40, v41
	v_cvt_pk_bf16_f32 v36, v36, v37
	v_cvt_pk_bf16_f32 v37, v42, v43
	v_add_u32_e32 v38, 0xa0, v144
	global_store_dwordx4 v[52:53], v[34:37], off offset:256 sc0 sc1
	v_ashrrev_i32_e32 v39, 31, v38
	s_nop 0
	v_and_b32_e32 v34, 0xff, v38
	v_lshlrev_b32_e32 v34, 4, v34
	v_add_u32_e32 v34, 0x21400, v34
	ds_read_b128 v[34:37], v34
	s_waitcnt lgkmcnt(0)
	v_mov_b32_e32 v40, v35
	v_mov_b32_e32 v41, v36
	v_mov_b32_e32 v35, v37
	v_pk_add_f32 v[34:35], v[40:41], v[34:35]
	v_mad_i64_i32 v[36:37], s[20:21], v38, s33, v[140:141]
	v_add_f32_e32 v34, v34, v35
	v_add_f32_e32 v34, 0, v34
	v_fmamk_f32 v34, v34, 0x3c000000, v212
	v_cmp_gt_f32_e32 vcc, s69, v34
	v_mul_f32_e32 v35, 0x4b800000, v34
	v_lshl_add_u64 v[36:37], v[36:37], 0, v[142:143]
	v_cndmask_b32_e32 v34, v34, v35, vcc
	v_rsq_f32_e32 v34, v34
	s_nop 0
	v_mul_f32_e32 v35, 0x45800000, v34
	v_cndmask_b32_e32 v34, v34, v35, vcc
	v_pk_mul_f32 v[32:33], v[32:33], v[34:35] op_sel_hi:[1,0]
	v_pk_mul_f32 v[30:31], v[30:31], v[34:35] op_sel_hi:[1,0]
	v_pk_mul_f32 v[38:39], v[28:29], v[34:35] op_sel_hi:[1,0]
	v_pk_mul_f32 v[28:29], v[26:27], v[34:35] op_sel_hi:[1,0]
	v_cvt_pk_bf16_f32 v26, v30, v31
	v_cvt_pk_bf16_f32 v27, v32, v33
	v_cvt_pk_bf16_f32 v28, v28, v29
	v_cvt_pk_bf16_f32 v29, v38, v39
	global_store_dwordx4 v[36:37], v[26:29], off sc0 sc1
	v_pk_mul_f32 v[24:25], v[24:25], v[34:35] op_sel_hi:[1,0]
	v_pk_mul_f32 v[22:23], v[22:23], v[34:35] op_sel_hi:[1,0]
	v_pk_mul_f32 v[26:27], v[20:21], v[34:35] op_sel_hi:[1,0]
	v_pk_mul_f32 v[20:21], v[18:19], v[34:35] op_sel_hi:[1,0]
	v_cvt_pk_bf16_f32 v18, v22, v23
	v_cvt_pk_bf16_f32 v19, v24, v25
	v_cvt_pk_bf16_f32 v20, v20, v21
	v_cvt_pk_bf16_f32 v21, v26, v27
	v_add_u32_e32 v22, 0xb0, v144
	global_store_dwordx4 v[36:37], v[18:21], off offset:256 sc0 sc1
	v_ashrrev_i32_e32 v23, 31, v22
	s_nop 0
	v_and_b32_e32 v18, 0xff, v22
	v_lshlrev_b32_e32 v18, 4, v18
	v_add_u32_e32 v18, 0x21400, v18
	ds_read_b128 v[18:21], v18
	s_waitcnt lgkmcnt(0)
	v_mov_b32_e32 v24, v19
	v_mov_b32_e32 v25, v20
	v_mov_b32_e32 v19, v21
	v_pk_add_f32 v[18:19], v[24:25], v[18:19]
	v_mad_i64_i32 v[20:21], s[20:21], v22, s33, v[140:141]
	v_add_f32_e32 v18, v18, v19
	v_add_f32_e32 v18, 0, v18
	v_fmamk_f32 v18, v18, 0x3c000000, v212
	v_cmp_gt_f32_e32 vcc, s69, v18
	v_mul_f32_e32 v19, 0x4b800000, v18
	v_lshl_add_u64 v[20:21], v[20:21], 0, v[142:143]
	v_cndmask_b32_e32 v18, v18, v19, vcc
	v_rsq_f32_e32 v18, v18
	s_mov_b64 s[20:21], -1
	v_mul_f32_e32 v19, 0x45800000, v18
	v_cndmask_b32_e32 v18, v18, v19, vcc
	v_pk_mul_f32 v[16:17], v[16:17], v[18:19] op_sel_hi:[1,0]
	v_pk_mul_f32 v[14:15], v[14:15], v[18:19] op_sel_hi:[1,0]
	v_pk_mul_f32 v[22:23], v[12:13], v[18:19] op_sel_hi:[1,0]
	v_pk_mul_f32 v[12:13], v[10:11], v[18:19] op_sel_hi:[1,0]
	v_cvt_pk_bf16_f32 v10, v14, v15
	v_cvt_pk_bf16_f32 v11, v16, v17
	v_cvt_pk_bf16_f32 v12, v12, v13
	v_cvt_pk_bf16_f32 v13, v22, v23
	global_store_dwordx4 v[20:21], v[10:13], off sc0 sc1
	v_pk_mul_f32 v[8:9], v[8:9], v[18:19] op_sel_hi:[1,0]
	v_pk_mul_f32 v[6:7], v[6:7], v[18:19] op_sel_hi:[1,0]
	v_pk_mul_f32 v[10:11], v[4:5], v[18:19] op_sel_hi:[1,0]
	v_pk_mul_f32 v[4:5], v[2:3], v[18:19] op_sel_hi:[1,0]
	v_cvt_pk_bf16_f32 v2, v6, v7
	v_cvt_pk_bf16_f32 v3, v8, v9
	v_cvt_pk_bf16_f32 v4, v4, v5
	v_cvt_pk_bf16_f32 v5, v10, v11
	global_store_dwordx4 v[20:21], v[2:5], off offset:256 sc0 sc1
	s_and_b64 vcc, exec, s[40:41]
	s_cbranch_vccnz .LBB0_372
	s_andn2_b64 vcc, exec, s[22:23]
	s_cbranch_vccnz .LBB0_371
	s_barrier
	s_branch .LBB0_371

; __device__ __forceinline__ float xsum(float a) { auto rr = __builtin_amdgcn_permlane32_swap(__float_as_uint(a), __float_as_uint(a), false, false); return __uint_as_float(rr[0]) + __uint_as_float(rr[1]); }
; template <int MODE, int NQ>
; __device__ __forceinline__ void attn_unit(LAS unsigned char* lds, const Params& P, int layer, int b, int h, int qb) {
;     ...
;         bf16_t* orow = mix + (rowbase + qpos0) * DM + ocol + 8 * hi;
;         const float lam = __hip_atomic_load((const float*)(P.ws + WS_LAM) + layer, __ATOMIC_RELAXED, __HIP_MEMORY_SCOPE_AGENT);
;         const float lam_init = 0.8f - 0.6f * expf(-0.3f * (float)layer);
;         const float i1 = 1.f / lrun[0], i2 = lam / lrun[NC - 1];
;         float ss = 0.f;
; #pragma unroll
;         for (int d = 0; d < 2; ++d)
; #pragma unroll
;             for (int r = 0; r < 16; ++r) { const float v = o[0][d][r] * i1 - o[NC - 1][d][r] * i2; o[0][d][r] = v; ss += v * v; }
;         ss = xsum(ss);
;         const float sc_ = rsqrtf(ss * (1.0f / 64.0f) + EPS) * (1.f - lam_init);
;         const float* gn = P.a_subln + layer * 64 + 4 * hi;
.LBB0_394:
	s_barrier
	s_setprio 0
	global_load_dword v0, v1, s[44:45] sc1
	v_div_scale_f32 v4, s[0:1], v188, v188, 1.0
	v_rcp_f32_e32 v5, v4
	v_lshlrev_b64 v[2:3], 11, v[176:177]
	v_lshl_add_u64 v[2:3], s[12:13], 0, v[2:3]
	s_lshl_b32 s72, s4, 1
	v_fma_f32 v6, -v4, v5, 1.0
	v_fmac_f32_e32 v5, v6, v5
	v_div_scale_f32 v6, vcc, 1.0, v188, 1.0
	v_mul_f32_e32 v7, v6, v5
	v_fma_f32 v8, -v4, v7, v6
	v_fmac_f32_e32 v7, v8, v5
	v_fma_f32 v4, -v4, v7, v6
	v_div_fmas_f32 v4, v4, v5, v7
	v_div_fixup_f32 v80, v4, v188, 1.0
	v_lshl_add_u64 v[2:3], v[2:3], 0, s[72:73]
	v_lshlrev_b32_e32 v81, 2, v185
	s_add_i32 s21, s21, s86
	s_add_i32 s20, s20, 1
	s_cmpk_lt_i32 s21, 0x200
	s_waitcnt vmcnt(0)
	v_div_scale_f32 v4, s[0:1], v187, v187, v0
	v_rcp_f32_e32 v5, v4
	s_nop 0
	v_fma_f32 v6, -v4, v5, 1.0
	v_fmac_f32_e32 v5, v6, v5
	v_div_scale_f32 v6, vcc, v0, v187, v0
	v_mul_f32_e32 v7, v6, v5
	v_fma_f32 v8, -v4, v7, v6
	v_fmac_f32_e32 v7, v8, v5
	v_fma_f32 v4, -v4, v7, v6
	v_div_fmas_f32 v4, v4, v5, v7
	v_div_fixup_f32 v82, v4, v187, v0
	v_lshlrev_b32_e32 v0, 1, v186
	v_lshl_add_u64 v[10:11], v[2:3], 0, v[0:1]
	global_load_dwordx4 v[6:9], v81, s[46:47]
	global_load_dwordx4 v[2:5], v81, s[46:47] offset:32
	global_load_dwordx4 v[128:131], v81, s[46:47] offset:64
	global_load_dwordx4 v[132:135], v81, s[46:47] offset:96
	global_load_dwordx4 v[136:139], v81, s[46:47] offset:128
	global_load_dwordx4 v[140:143], v81, s[46:47] offset:160
	global_load_dwordx4 v[144:147], v81, s[46:47] offset:192
	global_load_dwordx4 v[148:151], v81, s[46:47] offset:224
	v_pk_mul_f32 v[14:15], v[52:53], v[82:83] op_sel_hi:[1,0]
	v_pk_mul_f32 v[12:13], v[54:55], v[82:83] op_sel_hi:[1,0]
	v_pk_fma_f32 v[52:53], v[80:81], v[68:69], v[14:15] op_sel_hi:[0,1,1] neg_lo:[0,0,1] neg_hi:[0,0,1]
	v_pk_mul_f32 v[14:15], v[50:51], v[82:83] op_sel_hi:[1,0]
	v_pk_fma_f32 v[12:13], v[80:81], v[70:71], v[12:13] op_sel_hi:[0,1,1] neg_lo:[0,0,1] neg_hi:[0,0,1]
	v_pk_fma_f32 v[50:51], v[80:81], v[66:67], v[14:15] op_sel_hi:[0,1,1] neg_lo:[0,0,1] neg_hi:[0,0,1]
	v_pk_mul_f32 v[14:15], v[48:49], v[82:83] op_sel_hi:[1,0]
	v_pk_mul_f32 v[56:57], v[56:57], v[82:83] op_sel_hi:[1,0]
	v_pk_fma_f32 v[54:55], v[80:81], v[64:65], v[14:15] op_sel_hi:[0,1,1] neg_lo:[0,0,1] neg_hi:[0,0,1]
	v_mul_f32_e32 v0, v55, v55
	v_pk_fma_f32 v[14:15], v[54:55], v[54:55], v[0:1] op_sel_hi:[1,1,0]
	v_mul_f32_e32 v0, v51, v51
	v_pk_fma_f32 v[14:15], v[50:51], v[50:51], v[14:15]
	v_pk_fma_f32 v[56:57], v[80:81], v[72:73], v[56:57] op_sel_hi:[0,1,1] neg_lo:[0,0,1] neg_hi:[0,0,1]
	v_pk_add_f32 v[14:15], v[0:1], v[14:15] op_sel_hi:[0,1]
	v_pk_fma_f32 v[14:15], v[52:53], v[52:53], v[14:15]
	v_mul_f32_e32 v0, v53, v53
	v_pk_add_f32 v[14:15], v[0:1], v[14:15] op_sel_hi:[0,1]
	v_pk_fma_f32 v[14:15], v[12:13], v[12:13], v[14:15]
	v_mul_f32_e32 v0, v13, v13
	v_pk_add_f32 v[64:65], v[0:1], v[14:15] op_sel_hi:[0,1]
	v_pk_mul_f32 v[48:49], v[60:61], v[82:83] op_sel_hi:[1,0]
	v_pk_mul_f32 v[58:59], v[58:59], v[82:83] op_sel_hi:[1,0]
	v_pk_fma_f32 v[60:61], v[56:57], v[56:57], v[64:65]
	v_mul_f32_e32 v0, v57, v57
	v_pk_fma_f32 v[58:59], v[80:81], v[74:75], v[58:59] op_sel_hi:[0,1,1] neg_lo:[0,0,1] neg_hi:[0,0,1]
	v_pk_add_f32 v[60:61], v[0:1], v[60:61] op_sel_hi:[0,1]
	v_pk_fma_f32 v[60:61], v[58:59], v[58:59], v[60:61]
	v_mul_f32_e32 v0, v59, v59
	v_pk_fma_f32 v[48:49], v[80:81], v[76:77], v[48:49] op_sel_hi:[0,1,1] neg_lo:[0,0,1] neg_hi:[0,0,1]
	v_pk_add_f32 v[60:61], v[0:1], v[60:61] op_sel_hi:[0,1]
	v_pk_mul_f32 v[14:15], v[62:63], v[82:83] op_sel_hi:[1,0]
	v_pk_fma_f32 v[60:61], v[48:49], v[48:49], v[60:61]
	v_mul_f32_e32 v0, v49, v49
	v_pk_fma_f32 v[14:15], v[80:81], v[78:79], v[14:15] op_sel_hi:[0,1,1] neg_lo:[0,0,1] neg_hi:[0,0,1]
	v_pk_add_f32 v[60:61], v[0:1], v[60:61] op_sel_hi:[0,1]
	v_pk_mul_f32 v[34:35], v[34:35], v[82:83] op_sel_hi:[1,0]
	v_pk_fma_f32 v[60:61], v[14:15], v[14:15], v[60:61]
	v_mul_f32_e32 v0, v15, v15
	v_pk_fma_f32 v[34:35], v[80:81], v[18:19], v[34:35] op_sel_hi:[0,1,1] neg_lo:[0,0,1] neg_hi:[0,0,1]
	v_pk_mul_f32 v[18:19], v[32:33], v[82:83] op_sel_hi:[1,0]
	v_pk_add_f32 v[60:61], v[0:1], v[60:61] op_sel_hi:[0,1]
	v_pk_fma_f32 v[32:33], v[80:81], v[16:17], v[18:19] op_sel_hi:[0,1,1] neg_lo:[0,0,1] neg_hi:[0,0,1]
	v_pk_fma_f32 v[16:17], v[32:33], v[32:33], v[60:61]
	v_mul_f32_e32 v0, v33, v33
	v_pk_add_f32 v[16:17], v[0:1], v[16:17] op_sel_hi:[0,1]
	v_pk_mul_f32 v[36:37], v[36:37], v[82:83] op_sel_hi:[1,0]
	v_pk_fma_f32 v[16:17], v[34:35], v[34:35], v[16:17]
	v_mul_f32_e32 v0, v35, v35
	v_pk_fma_f32 v[20:21], v[80:81], v[20:21], v[36:37] op_sel_hi:[0,1,1] neg_lo:[0,0,1] neg_hi:[0,0,1]
	v_pk_add_f32 v[16:17], v[0:1], v[16:17] op_sel_hi:[0,1]
	v_pk_mul_f32 v[38:39], v[38:39], v[82:83] op_sel_hi:[1,0]
	v_pk_fma_f32 v[16:17], v[20:21], v[20:21], v[16:17]
	v_mul_f32_e32 v0, v21, v21
	v_pk_mul_f32 v[18:19], v[44:45], v[82:83] op_sel_hi:[1,0]
	v_pk_fma_f32 v[22:23], v[80:81], v[22:23], v[38:39] op_sel_hi:[0,1,1] neg_lo:[0,0,1] neg_hi:[0,0,1]
	v_pk_add_f32 v[16:17], v[0:1], v[16:17] op_sel_hi:[0,1]
	v_pk_fma_f32 v[18:19], v[80:81], v[28:29], v[18:19] op_sel_hi:[0,1,1] neg_lo:[0,0,1] neg_hi:[0,0,1]
	v_pk_mul_f32 v[28:29], v[42:43], v[82:83] op_sel_hi:[1,0]
	v_pk_fma_f32 v[16:17], v[22:23], v[22:23], v[16:17]
	v_mul_f32_e32 v0, v23, v23
	v_pk_fma_f32 v[26:27], v[80:81], v[26:27], v[28:29] op_sel_hi:[0,1,1] neg_lo:[0,0,1] neg_hi:[0,0,1]
	v_pk_mul_f32 v[28:29], v[40:41], v[82:83] op_sel_hi:[1,0]
	v_pk_add_f32 v[36:37], v[0:1], v[16:17] op_sel_hi:[0,1]
	v_pk_fma_f32 v[24:25], v[80:81], v[24:25], v[28:29] op_sel_hi:[0,1,1] neg_lo:[0,0,1] neg_hi:[0,0,1]
	v_pk_fma_f32 v[28:29], v[24:25], v[24:25], v[36:37]
	v_mul_f32_e32 v0, v25, v25
	v_pk_add_f32 v[28:29], v[0:1], v[28:29] op_sel_hi:[0,1]
	v_pk_fma_f32 v[28:29], v[26:27], v[26:27], v[28:29]
	v_mul_f32_e32 v0, v27, v27
	v_pk_add_f32 v[28:29], v[0:1], v[28:29] op_sel_hi:[0,1]
	v_pk_mul_f32 v[16:17], v[46:47], v[82:83] op_sel_hi:[1,0]
	v_pk_fma_f32 v[28:29], v[18:19], v[18:19], v[28:29]
	v_mul_f32_e32 v0, v19, v19
	v_pk_fma_f32 v[16:17], v[80:81], v[30:31], v[16:17] op_sel_hi:[0,1,1] neg_lo:[0,0,1] neg_hi:[0,0,1]
	v_pk_add_f32 v[28:29], v[0:1], v[28:29] op_sel_hi:[0,1]
	v_pk_fma_f32 v[28:29], v[16:17], v[16:17], v[28:29]
	v_mul_f32_e32 v0, v17, v17
	v_pk_add_f32 v[28:29], v[0:1], v[28:29] op_sel_hi:[0,1]
	v_mov_b32_e32 v0, v28
	s_nop 1
	v_permlane32_swap_b32_e32 v28, v0
	v_add_f32_e32 v0, v28, v0
	v_fmamk_f32 v0, v0, 0x3c800000, v212
	v_cmp_gt_f32_e32 vcc, s69, v0
	v_mul_f32_e32 v28, 0x4b800000, v0
	s_nop 0
	v_cndmask_b32_e32 v0, v0, v28, vcc
	v_rsq_f32_e32 v0, v0
	s_nop 0
	v_mul_f32_e32 v28, 0x45800000, v0
	v_cndmask_b32_e32 v0, v0, v28, vcc
	v_mul_f32_e32 v0, v184, v0
	v_pk_mul_f32 v[28:29], v[54:55], v[0:1] op_sel_hi:[1,0]
	s_waitcnt vmcnt(7)
; __device__ __forceinline__ unsigned cvtpk(float lo, float hi) { f32x2 v = {lo, hi}; bf16x2_t b = __builtin_convertvector(v, bf16x2_t); return __builtin_bit_cast(unsigned, b); }
; template <int MODE, int NQ>
; __device__ __forceinline__ void attn_unit(LAS unsigned char* lds, const Params& P, int layer, int b, int h, int qb) {
;     ...
; #pragma unroll
;         for (int d = 0; d < 2; ++d)
; #pragma unroll
;             for (int gp = 0; gp < 2; ++gp) {
;                 u32x2 ab[2];
; #pragma unroll
;                 for (int e = 0; e < 2; ++e) { const int g = 2 * gp + e;
;                     const f32x4 gv = *(const f32x4*)(gn + 32 * d + 8 * g);
;                     ab[e].x = cvtpk(o[0][d][4 * g] * sc_ * gv[0], o[0][d][4 * g + 1] * sc_ * gv[1]); ab[e].y = cvtpk(o[0][d][4 * g + 2] * sc_ * gv[2], o[0][d][4 * g + 3] * sc_ * gv[3]); }
;                 *(u32x4*)(orow + 32 * d + 16 * gp) = pair_swap(ab[0], ab[1]);
;             }
	v_pk_mul_f32 v[6:7], v[6:7], v[28:29]
	v_pk_mul_f32 v[28:29], v[50:51], v[0:1] op_sel_hi:[1,0]
	v_cvt_pk_bf16_f32 v6, v6, v7
	v_pk_mul_f32 v[8:9], v[8:9], v[28:29]
	s_nop 0
	v_cvt_pk_bf16_f32 v7, v8, v9
	v_pk_mul_f32 v[8:9], v[52:53], v[0:1] op_sel_hi:[1,0]
	s_waitcnt vmcnt(0)
	v_pk_mul_f32 v[2:3], v[2:3], v[8:9]
	s_nop 0
	v_cvt_pk_bf16_f32 v8, v2, v3
	v_pk_mul_f32 v[2:3], v[12:13], v[0:1] op_sel_hi:[1,0]
	s_nop 0
	v_permlane32_swap_b32_e32 v6, v8
	v_pk_mul_f32 v[2:3], v[4:5], v[2:3]
	s_nop 0
	v_cvt_pk_bf16_f32 v9, v2, v3
	s_nop 1
	v_permlane32_swap_b32_e32 v7, v9
	global_store_dwordx4 v[10:11], v[6:9], off sc0 sc1
	s_nop 1
	v_mov_b64_e32 v[2:3], v[128:129]
	v_mov_b64_e32 v[4:5], v[130:131]
	s_nop 0
	v_pk_mul_f32 v[6:7], v[56:57], v[0:1] op_sel_hi:[1,0]
	v_pk_mul_f32 v[8:9], v[48:49], v[0:1] op_sel_hi:[1,0]
	s_nop 0
	v_pk_mul_f32 v[2:3], v[2:3], v[6:7]
	v_pk_mul_f32 v[6:7], v[58:59], v[0:1] op_sel_hi:[1,0]
	v_cvt_pk_bf16_f32 v2, v2, v3
	v_pk_mul_f32 v[4:5], v[4:5], v[6:7]
	s_nop 0
	v_cvt_pk_bf16_f32 v3, v4, v5
	s_nop 1
	v_mov_b64_e32 v[4:5], v[132:133]
	v_mov_b64_e32 v[6:7], v[134:135]
	s_nop 0
	v_pk_mul_f32 v[4:5], v[4:5], v[8:9]
	v_pk_mul_f32 v[8:9], v[14:15], v[0:1] op_sel_hi:[1,0]
	v_cvt_pk_bf16_f32 v4, v4, v5
	v_pk_mul_f32 v[6:7], v[6:7], v[8:9]
	s_nop 0
	v_permlane32_swap_b32_e32 v2, v4
	v_cvt_pk_bf16_f32 v5, v6, v7
	s_nop 1
	v_permlane32_swap_b32_e32 v3, v5
	global_store_dwordx4 v[10:11], v[2:5], off offset:32 sc0 sc1
	s_nop 1
	v_mov_b64_e32 v[2:3], v[136:137]
	v_mov_b64_e32 v[4:5], v[138:139]
	v_pk_mul_f32 v[6:7], v[32:33], v[0:1] op_sel_hi:[1,0]
	v_pk_mul_f32 v[8:9], v[20:21], v[0:1] op_sel_hi:[1,0]
	s_nop 0
	v_pk_mul_f32 v[2:3], v[2:3], v[6:7]
	v_pk_mul_f32 v[6:7], v[34:35], v[0:1] op_sel_hi:[1,0]
	v_cvt_pk_bf16_f32 v2, v2, v3
	v_pk_mul_f32 v[4:5], v[4:5], v[6:7]
	s_nop 0
	v_cvt_pk_bf16_f32 v3, v4, v5
	s_nop 1
	v_mov_b64_e32 v[4:5], v[140:141]
	v_mov_b64_e32 v[6:7], v[142:143]
	s_nop 0
	v_pk_mul_f32 v[4:5], v[8:9], v[4:5]
	v_pk_mul_f32 v[8:9], v[22:23], v[0:1] op_sel_hi:[1,0]
	v_cvt_pk_bf16_f32 v4, v4, v5
	v_pk_mul_f32 v[6:7], v[8:9], v[6:7]
	s_nop 0
	v_permlane32_swap_b32_e32 v2, v4
	v_cvt_pk_bf16_f32 v5, v6, v7
	s_nop 1
	v_permlane32_swap_b32_e32 v3, v5
	global_store_dwordx4 v[10:11], v[2:5], off offset:64 sc0 sc1
	s_nop 1
	v_mov_b64_e32 v[2:3], v[144:145]
	v_mov_b64_e32 v[4:5], v[146:147]
	v_pk_mul_f32 v[6:7], v[24:25], v[0:1] op_sel_hi:[1,0]
	v_pk_mul_f32 v[8:9], v[18:19], v[0:1] op_sel_hi:[1,0]
	s_nop 0
	v_pk_mul_f32 v[2:3], v[6:7], v[2:3]
	v_pk_mul_f32 v[6:7], v[26:27], v[0:1] op_sel_hi:[1,0]
	v_cvt_pk_bf16_f32 v2, v2, v3
	v_pk_mul_f32 v[4:5], v[6:7], v[4:5]
	s_nop 0
	v_cvt_pk_bf16_f32 v3, v4, v5
	s_nop 1
	v_mov_b64_e32 v[4:5], v[148:149]
	v_mov_b64_e32 v[6:7], v[150:151]
	s_nop 0
	v_pk_mul_f32 v[4:5], v[8:9], v[4:5]
	v_pk_mul_f32 v[8:9], v[16:17], v[0:1] op_sel_hi:[1,0]
	v_cvt_pk_bf16_f32 v4, v4, v5
	v_pk_mul_f32 v[6:7], v[8:9], v[6:7]
	s_nop 0
	v_permlane32_swap_b32_e32 v2, v4
	v_cvt_pk_bf16_f32 v5, v6, v7
	s_nop 1
	v_permlane32_swap_b32_e32 v3, v5
	global_store_dwordx4 v[10:11], v[2:5], off offset:96 sc0 sc1
	s_cbranch_scc0 .LBB0_482

; __device__ __forceinline__ unsigned cvtpk(float lo, float hi) { f32x2 v = {lo, hi}; bf16x2_t b = __builtin_convertvector(v, bf16x2_t); return __builtin_bit_cast(unsigned, b); }
; template <int MODE, int NQ>
; __device__ __forceinline__ void attn_unit(LAS unsigned char* lds, const Params& P, int layer, int b, int h, int qb) {
;     ...
;         for (int jq = 0; jq < NQ; ++jq) {
;             bf16_t* orow = mix + (rowbase + qpos0 + 32 * jq) * DM + ocol + 8 * hi;
;             const float inv = 1.f / lrun[jq];
; #pragma unroll
;             for (int d = 0; d < 2; ++d)
; #pragma unroll
;                 for (int gp = 0; gp < 2; ++gp) {
;                     u32x2 a, b; const int g0 = 2 * gp, g1 = 2 * gp + 1;
;                     a.x = cvtpk(o[jq][d][4 * g0] * inv, o[jq][d][4 * g0 + 1] * inv); a.y = cvtpk(o[jq][d][4 * g0 + 2] * inv, o[jq][d][4 * g0 + 3] * inv);
;                     b.x = cvtpk(o[jq][d][4 * g1] * inv, o[jq][d][4 * g1 + 1] * inv); b.y = cvtpk(o[jq][d][4 * g1 + 2] * inv, o[jq][d][4 * g1 + 3] * inv);
;                     *(u32x4*)(orow + 32 * d + 16 * gp) = pair_swap(a, b);
;                 }
.LBB0_483:
	s_setprio 0
	s_lshl_b32 s0, s9, 1
	s_add_u32 s0, s84, s0
	s_addc_u32 s1, s85, 0
	v_lshlrev_b64 v[2:3], 11, v[116:117]
	v_lshl_add_u64 v[2:3], s[0:1], 0, v[2:3]
	v_div_scale_f32 v4, s[0:1], v132, v132, 1.0
	v_rcp_f32_e32 v5, v4
	v_lshlrev_b32_e32 v0, 1, v129
	v_lshl_add_u64 v[6:7], v[2:3], 0, v[0:1]
	s_mov_b64 s[0:1], 0x19a00200
	v_fma_f32 v0, -v4, v5, 1.0
	v_fmac_f32_e32 v5, v0, v5
	v_div_scale_f32 v0, vcc, 1.0, v132, 1.0
	v_mul_f32_e32 v2, v0, v5
	v_fma_f32 v3, -v4, v2, v0
	v_fmac_f32_e32 v2, v3, v5
	v_fma_f32 v0, -v4, v2, v0
	v_div_fmas_f32 v0, v0, v5, v2
	v_div_fixup_f32 v0, v0, v132, 1.0
	v_pk_mul_f32 v[2:3], v[0:1], v[32:33] op_sel_hi:[0,1]
	v_pk_mul_f32 v[4:5], v[0:1], v[34:35] op_sel_hi:[0,1]
	v_lshl_add_u64 v[8:9], v[6:7], 0, s[0:1]
	v_cvt_pk_bf16_f32 v2, v2, v3
	v_cvt_pk_bf16_f32 v3, v4, v5
	v_pk_mul_f32 v[4:5], v[0:1], v[36:37] op_sel_hi:[0,1]
	v_pk_mul_f32 v[10:11], v[0:1], v[38:39] op_sel_hi:[0,1]
	s_mov_b32 s0, 0x19a00000
	v_cvt_pk_bf16_f32 v4, v4, v5
	v_cvt_pk_bf16_f32 v5, v10, v11
	v_add_co_u32_e32 v6, vcc, s0, v6
	v_permlane32_swap_b32_e32 v2, v4
	v_permlane32_swap_b32_e32 v3, v5
	v_addc_co_u32_e32 v7, vcc, 0, v7, vcc
	global_store_dwordx4 v[6:7], v[2:5], off offset:512 sc0 sc1
	v_pk_mul_f32 v[6:7], v[0:1], v[46:47] op_sel_hi:[0,1]
	s_add_i32 s5, s5, s86
	v_pk_mul_f32 v[2:3], v[0:1], v[40:41] op_sel_hi:[0,1]
	v_pk_mul_f32 v[4:5], v[0:1], v[42:43] op_sel_hi:[0,1]
	v_cvt_pk_bf16_f32 v2, v2, v3
	v_cvt_pk_bf16_f32 v3, v4, v5
	v_pk_mul_f32 v[4:5], v[0:1], v[44:45] op_sel_hi:[0,1]
	v_cvt_pk_bf16_f32 v4, v4, v5
	v_cvt_pk_bf16_f32 v5, v6, v7
	s_nop 0
	v_permlane32_swap_b32_e32 v2, v4
	v_permlane32_swap_b32_e32 v3, v5
	global_store_dwordx4 v[8:9], v[2:5], off offset:32 sc0 sc1
	v_pk_mul_f32 v[6:7], v[0:1], v[22:23] op_sel_hi:[0,1]
	s_add_i32 s4, s4, 1
	v_pk_mul_f32 v[2:3], v[0:1], v[16:17] op_sel_hi:[0,1]
	v_pk_mul_f32 v[4:5], v[0:1], v[18:19] op_sel_hi:[0,1]
	v_cvt_pk_bf16_f32 v2, v2, v3
	v_cvt_pk_bf16_f32 v3, v4, v5
	v_pk_mul_f32 v[4:5], v[0:1], v[20:21] op_sel_hi:[0,1]
	v_cvt_pk_bf16_f32 v4, v4, v5
	v_cvt_pk_bf16_f32 v5, v6, v7
	s_nop 0
	v_permlane32_swap_b32_e32 v2, v4
	v_permlane32_swap_b32_e32 v3, v5
	global_store_dwordx4 v[8:9], v[2:5], off offset:64 sc0 sc1
	v_pk_mul_f32 v[6:7], v[0:1], v[30:31] op_sel_hi:[0,1]
	s_cmpk_gt_i32 s5, 0x1ff
	v_pk_mul_f32 v[2:3], v[0:1], v[24:25] op_sel_hi:[0,1]
	v_pk_mul_f32 v[4:5], v[0:1], v[26:27] op_sel_hi:[0,1]
	v_cvt_pk_bf16_f32 v2, v2, v3
	v_cvt_pk_bf16_f32 v3, v4, v5
	v_pk_mul_f32 v[4:5], v[0:1], v[28:29] op_sel_hi:[0,1]
	v_cvt_pk_bf16_f32 v4, v4, v5
	v_cvt_pk_bf16_f32 v5, v6, v7
	s_nop 0
	v_permlane32_swap_b32_e32 v2, v4
	v_permlane32_swap_b32_e32 v3, v5
	global_store_dwordx4 v[8:9], v[2:5], off offset:96 sc0 sc1
	s_cbranch_scc1 .LBB0_525

; __device__ __forceinline__ unsigned cvtpk(float lo, float hi) { f32x2 v = {lo, hi}; bf16x2_t b = __builtin_convertvector(v, bf16x2_t); return __builtin_bit_cast(unsigned, b); }
; __device__ __forceinline__ float fast_exp2(float x) { return __builtin_amdgcn_exp2f(x); }
; template <int MODE, int NQ>
; __device__ __forceinline__ void attn_unit(LAS unsigned char* lds, const Params& P, int layer, int b, int h, int qb) {
;     ...
;                         for (int r = 0; r < 16; ++r) s0[r] = fast_exp2(s0[r] - mn);
;                     } else {
;                         const float nm = -mn;
; #pragma unroll
;                         for (int r = 0; r < 16; ++r) s0[r] = fast_exp2(__builtin_fmaf(s0[r], c, nm));
;                     }
;                     u32x4 w;
;                     w.x = cvtpk(s0[0], s0[1]); w.y = cvtpk(s0[2], s0[3]); w.z = cvtpk(s0[4], s0[5]); w.w = cvtpk(s0[6], s0[7]); pw[cc][0] = __builtin_bit_cast(bf16x8, w);
;                     w.x = cvtpk(s0[8], s0[9]); w.y = cvtpk(s0[10], s0[11]); w.z = cvtpk(s0[12], s0[13]); w.w = cvtpk(s0[14], s0[15]); pw[cc][1] = __builtin_bit_cast(bf16x8, w);
;                     f32x16 t = __builtin_amdgcn_mfma_f32_32x32x16_bf16(ones8, pw[cc][0], f32x16{}, 0, 0, 0);
;                     t = __builtin_amdgcn_mfma_f32_32x32x16_bf16(ones8, pw[cc][1], t, 0, 0, 0);
;                     lrun[cc] += t[0];
.LBB0_579:
	v_fmamk_f32 v14, v80, 0x3e16c740, v196
	v_fmamk_f32 v15, v81, 0x3e16c740, v196
	v_fmamk_f32 v80, v82, 0x3e16c740, v196
	v_fmamk_f32 v81, v83, 0x3e16c740, v196
	v_fmamk_f32 v82, v84, 0x3e16c740, v196
	v_fmamk_f32 v83, v85, 0x3e16c740, v196
	v_fmamk_f32 v84, v86, 0x3e16c740, v196
	v_fmamk_f32 v85, v87, 0x3e16c740, v196
	v_mov_b64_e32 v[108:109], s[62:63]
	v_exp_f32_e32 v14, v14
	v_exp_f32_e32 v15, v15
	v_exp_f32_e32 v80, v80
	v_exp_f32_e32 v81, v81
	v_exp_f32_e32 v82, v82
	v_exp_f32_e32 v83, v83
	v_exp_f32_e32 v84, v84
	v_exp_f32_e32 v85, v85
	v_fmamk_f32 v86, v88, 0x3e16c740, v196
	v_fmamk_f32 v87, v89, 0x3e16c740, v196
	v_fmamk_f32 v88, v90, 0x3e16c740, v196
	v_fmamk_f32 v89, v91, 0x3e16c740, v196
	v_fmamk_f32 v90, v92, 0x3e16c740, v196
	v_fmamk_f32 v91, v93, 0x3e16c740, v196
	v_fmamk_f32 v92, v94, 0x3e16c740, v196
	v_fmac_f32_e32 v196, 0x3e16c740, v95
	v_mov_b64_e32 v[106:107], s[60:61]
	v_exp_f32_e32 v86, v86
	v_exp_f32_e32 v87, v87
	v_exp_f32_e32 v88, v88
	v_exp_f32_e32 v89, v89
	v_exp_f32_e32 v90, v90
	v_exp_f32_e32 v91, v91
	v_exp_f32_e32 v92, v92
	v_exp_f32_e32 v93, v196
	v_cvt_pk_bf16_f32 v98, v14, v15
	v_cvt_pk_bf16_f32 v99, v80, v81
	v_cvt_pk_bf16_f32 v100, v82, v83
	v_cvt_pk_bf16_f32 v101, v84, v85
	v_cvt_pk_bf16_f32 v102, v86, v87
	v_cvt_pk_bf16_f32 v103, v88, v89
	v_cvt_pk_bf16_f32 v104, v90, v91
	v_cvt_pk_bf16_f32 v105, v92, v93
	v_mfma_f32_32x32x16_bf16 v[80:95], v[106:109], v[98:101], 0
	s_waitcnt lgkmcnt(0)
	s_barrier
; __device__ __forceinline__ unsigned cvtpk(float lo, float hi) { f32x2 v = {lo, hi}; bf16x2_t b = __builtin_convertvector(v, bf16x2_t); return __builtin_bit_cast(unsigned, b); }
; template <int MODE, int NQ>
; __device__ __forceinline__ void attn_unit(LAS unsigned char* lds, const Params& P, int layer, int b, int h, int qb) {
;     ...
;                     f32x16 t = __builtin_amdgcn_mfma_f32_32x32x16_bf16(ones8, pw[cc][0], f32x16{}, 0, 0, 0);
;                     t = __builtin_amdgcn_mfma_f32_32x32x16_bf16(ones8, pw[cc][1], t, 0, 0, 0);
;                     lrun[cc] += t[0];
;                 }
;             }
;             if (alive)
; #pragma unroll
;             for (int dv = 0; dv < 2; ++dv)
; #pragma unroll
;                 for (int k2 = 0; k2 < 2; ++k2) {
;                     const s16x4 lo = vlo[dv * 2 + k2], hh = vhi[dv * 2 + k2];
;                     const bf16x8 vf = (bf16x8){lo[0], lo[1], lo[2], lo[3], hh[0], hh[1], hh[2], hh[3]};
; #pragma unroll
;                     for (int cc = 0; cc < NC; ++cc) o[cc][dv] = __builtin_amdgcn_mfma_f32_32x32x16_bf16(vf, pw[cc][k2], o[cc][dv], 0, 0, 0);
;     ...
;         for (int jq = 0; jq < NQ; ++jq) {
;             bf16_t* orow = mix + (rowbase + qpos0 + 32 * jq) * DM + ocol + 8 * hi;
;             const float inv = 1.f / lrun[jq];
; #pragma unroll
;             for (int d = 0; d < 2; ++d)
; #pragma unroll
;                 for (int gp = 0; gp < 2; ++gp) {
;                     u32x2 a, b; const int g0 = 2 * gp, g1 = 2 * gp + 1;
;                     a.x = cvtpk(o[jq][d][4 * g0] * inv, o[jq][d][4 * g0 + 1] * inv); a.y = cvtpk(o[jq][d][4 * g0 + 2] * inv, o[jq][d][4 * g0 + 3] * inv);
;                     b.x = cvtpk(o[jq][d][4 * g1] * inv, o[jq][d][4 * g1 + 1] * inv); b.y = cvtpk(o[jq][d][4 * g1 + 2] * inv, o[jq][d][4 * g1 + 3] * inv);
;                     *(u32x4*)(orow + 32 * d + 16 * gp) = pair_swap(a, b);
;                 }
	v_mfma_f32_32x32x16_bf16 v[80:95], v[106:109], v[102:105], v[80:95]
	v_mfma_f32_32x32x16_bf16 v[64:79], v[114:117], v[122:125], v[64:79]
	v_mfma_f32_32x32x16_bf16 v[32:47], v[114:117], v[98:101], v[32:47]
	v_mfma_f32_32x32x16_bf16 v[48:63], v[6:9], v[122:125], v[48:63]
	v_mfma_f32_32x32x16_bf16 v[16:31], v[6:9], v[98:101], v[16:31]
	v_mfma_f32_32x32x16_bf16 v[64:79], v[10:13], v[118:121], v[64:79]
	v_mfma_f32_32x32x16_bf16 v[32:47], v[10:13], v[102:105], v[32:47]
	s_nop 5
	v_add_f32_e32 v13, v126, v80
	v_mfma_f32_32x32x16_bf16 v[48:63], v[2:5], v[118:121], v[48:63]
	v_mfma_f32_32x32x16_bf16 v[16:31], v[2:5], v[102:105], v[16:31]
	v_add_f32_e32 v4, v0, v96
	s_setprio 0
	s_lshl_b32 s0, s6, 7
	v_div_scale_f32 v5, s[6:7], v4, v4, 1.0
	v_rcp_f32_e32 v12, v5
	s_add_u32 s0, s84, s0
	s_addc_u32 s1, s85, 0
	v_lshlrev_b64 v[6:7], 11, v[224:225]
	v_lshl_add_u64 v[2:3], s[0:1], 0, v[6:7]
	v_lshlrev_b32_e32 v0, 1, v232
	v_lshl_add_u64 v[8:9], v[2:3], 0, v[0:1]
	v_fma_f32 v2, -v5, v12, 1.0
	v_fmac_f32_e32 v12, v2, v12
	v_div_scale_f32 v2, vcc, 1.0, v4, 1.0
	v_mul_f32_e32 v3, v2, v12
	v_fma_f32 v14, -v5, v3, v2
	v_fmac_f32_e32 v3, v14, v12
	v_fma_f32 v2, -v5, v3, v2
	v_div_fmas_f32 v2, v2, v12, v3
	v_div_fixup_f32 v12, v2, v4, 1.0
	v_pk_mul_f32 v[2:3], v[12:13], v[64:65] op_sel_hi:[0,1]
	v_pk_mul_f32 v[4:5], v[12:13], v[66:67] op_sel_hi:[0,1]
	s_mov_b64 s[10:11], 0x19a00400
	v_cvt_pk_bf16_f32 v2, v2, v3
	v_cvt_pk_bf16_f32 v3, v4, v5
	v_pk_mul_f32 v[4:5], v[12:13], v[68:69] op_sel_hi:[0,1]
	v_pk_mul_f32 v[14:15], v[12:13], v[70:71] op_sel_hi:[0,1]
	s_mov_b32 s8, 0x19a00000
	v_lshl_add_u64 v[10:11], v[8:9], 0, s[10:11]
	v_cvt_pk_bf16_f32 v4, v4, v5
	v_cvt_pk_bf16_f32 v5, v14, v15
	v_add_co_u32_e32 v8, vcc, s8, v8
	v_permlane32_swap_b32_e32 v2, v4
	v_permlane32_swap_b32_e32 v3, v5
	v_addc_co_u32_e32 v9, vcc, 0, v9, vcc
	global_store_dwordx4 v[8:9], v[2:5], off offset:1024 sc0 sc1
	v_pk_mul_f32 v[8:9], v[12:13], v[78:79] op_sel_hi:[0,1]
	v_or_b32_e32 v6, 0x10000, v6
	v_pk_mul_f32 v[2:3], v[12:13], v[72:73] op_sel_hi:[0,1]
	v_pk_mul_f32 v[4:5], v[12:13], v[74:75] op_sel_hi:[0,1]
	v_cvt_pk_bf16_f32 v2, v2, v3
	v_cvt_pk_bf16_f32 v3, v4, v5
	v_pk_mul_f32 v[4:5], v[12:13], v[76:77] op_sel_hi:[0,1]
	v_cvt_pk_bf16_f32 v4, v4, v5
	v_cvt_pk_bf16_f32 v5, v8, v9
	s_nop 0
	v_permlane32_swap_b32_e32 v2, v4
	v_permlane32_swap_b32_e32 v3, v5
	global_store_dwordx4 v[10:11], v[2:5], off offset:32 sc0 sc1
	v_pk_mul_f32 v[8:9], v[12:13], v[54:55] op_sel_hi:[0,1]
	s_add_i32 s5, s5, s86
	v_pk_mul_f32 v[2:3], v[12:13], v[48:49] op_sel_hi:[0,1]
	v_pk_mul_f32 v[4:5], v[12:13], v[50:51] op_sel_hi:[0,1]
	v_cvt_pk_bf16_f32 v2, v2, v3
	v_cvt_pk_bf16_f32 v3, v4, v5
	v_pk_mul_f32 v[4:5], v[12:13], v[52:53] op_sel_hi:[0,1]
	v_cvt_pk_bf16_f32 v4, v4, v5
	v_cvt_pk_bf16_f32 v5, v8, v9
	s_nop 0
	v_permlane32_swap_b32_e32 v2, v4
	v_permlane32_swap_b32_e32 v3, v5
	global_store_dwordx4 v[10:11], v[2:5], off offset:64 sc0 sc1
	v_pk_mul_f32 v[8:9], v[12:13], v[62:63] op_sel_hi:[0,1]
	s_add_i32 s4, s4, 1
	v_pk_mul_f32 v[2:3], v[12:13], v[56:57] op_sel_hi:[0,1]
	v_pk_mul_f32 v[4:5], v[12:13], v[58:59] op_sel_hi:[0,1]
	v_cvt_pk_bf16_f32 v2, v2, v3
	v_cvt_pk_bf16_f32 v3, v4, v5
	v_pk_mul_f32 v[4:5], v[12:13], v[60:61] op_sel_hi:[0,1]
	v_cvt_pk_bf16_f32 v4, v4, v5
	v_cvt_pk_bf16_f32 v5, v8, v9
	s_nop 0
	v_permlane32_swap_b32_e32 v2, v4
	v_permlane32_swap_b32_e32 v3, v5
	global_store_dwordx4 v[10:11], v[2:5], off offset:96 sc0 sc1
	s_cmpk_gt_i32 s5, 0x1ff
	s_nop 0
	v_div_scale_f32 v4, s[6:7], v13, v13, 1.0
	v_rcp_f32_e32 v5, v4
	v_lshl_add_u64 v[2:3], s[0:1], 0, v[6:7]
	v_lshl_add_u64 v[6:7], v[2:3], 0, v[0:1]
	v_lshl_add_u64 v[8:9], v[6:7], 0, s[10:11]
	v_fma_f32 v0, -v4, v5, 1.0
	v_fmac_f32_e32 v5, v0, v5
	v_div_scale_f32 v0, vcc, 1.0, v13, 1.0
	v_mul_f32_e32 v2, v0, v5
	v_fma_f32 v3, -v4, v2, v0
	v_fmac_f32_e32 v2, v3, v5
	v_fma_f32 v0, -v4, v2, v0
	v_div_fmas_f32 v0, v0, v5, v2
	v_div_fixup_f32 v0, v0, v13, 1.0
	v_pk_mul_f32 v[2:3], v[0:1], v[32:33] op_sel_hi:[0,1]
	v_pk_mul_f32 v[4:5], v[0:1], v[34:35] op_sel_hi:[0,1]
	v_cvt_pk_bf16_f32 v2, v2, v3
	v_cvt_pk_bf16_f32 v3, v4, v5
	v_pk_mul_f32 v[4:5], v[0:1], v[36:37] op_sel_hi:[0,1]
	v_pk_mul_f32 v[10:11], v[0:1], v[38:39] op_sel_hi:[0,1]
	v_cvt_pk_bf16_f32 v4, v4, v5
	v_cvt_pk_bf16_f32 v5, v10, v11
	v_add_co_u32_e32 v6, vcc, s8, v6
	v_permlane32_swap_b32_e32 v2, v4
	v_permlane32_swap_b32_e32 v3, v5
	v_addc_co_u32_e32 v7, vcc, 0, v7, vcc
	global_store_dwordx4 v[6:7], v[2:5], off offset:1024 sc0 sc1
	v_pk_mul_f32 v[6:7], v[0:1], v[46:47] op_sel_hi:[0,1]
	s_nop 0
	v_pk_mul_f32 v[2:3], v[0:1], v[40:41] op_sel_hi:[0,1]
	v_pk_mul_f32 v[4:5], v[0:1], v[42:43] op_sel_hi:[0,1]
	v_cvt_pk_bf16_f32 v2, v2, v3
	v_cvt_pk_bf16_f32 v3, v4, v5
	v_pk_mul_f32 v[4:5], v[0:1], v[44:45] op_sel_hi:[0,1]
	v_cvt_pk_bf16_f32 v4, v4, v5
	v_cvt_pk_bf16_f32 v5, v6, v7
	s_nop 0
	v_permlane32_swap_b32_e32 v2, v4
	v_permlane32_swap_b32_e32 v3, v5
	global_store_dwordx4 v[8:9], v[2:5], off offset:32 sc0 sc1
	v_pk_mul_f32 v[6:7], v[0:1], v[22:23] op_sel_hi:[0,1]
	s_nop 0
	v_pk_mul_f32 v[2:3], v[0:1], v[16:17] op_sel_hi:[0,1]
	v_pk_mul_f32 v[4:5], v[0:1], v[18:19] op_sel_hi:[0,1]
	v_cvt_pk_bf16_f32 v2, v2, v3
	v_cvt_pk_bf16_f32 v3, v4, v5
	v_pk_mul_f32 v[4:5], v[0:1], v[20:21] op_sel_hi:[0,1]
	v_cvt_pk_bf16_f32 v4, v4, v5
	v_cvt_pk_bf16_f32 v5, v6, v7
	s_nop 0
	v_permlane32_swap_b32_e32 v2, v4
	v_permlane32_swap_b32_e32 v3, v5
	global_store_dwordx4 v[8:9], v[2:5], off offset:64 sc0 sc1
	v_pk_mul_f32 v[6:7], v[0:1], v[30:31] op_sel_hi:[0,1]
	s_nop 0
	v_pk_mul_f32 v[2:3], v[0:1], v[24:25] op_sel_hi:[0,1]
	v_pk_mul_f32 v[4:5], v[0:1], v[26:27] op_sel_hi:[0,1]
	v_cvt_pk_bf16_f32 v2, v2, v3
	v_cvt_pk_bf16_f32 v3, v4, v5
	v_pk_mul_f32 v[4:5], v[0:1], v[28:29] op_sel_hi:[0,1]
	v_cvt_pk_bf16_f32 v4, v4, v5
	v_cvt_pk_bf16_f32 v5, v6, v7
	s_nop 0
	v_permlane32_swap_b32_e32 v2, v4
	v_permlane32_swap_b32_e32 v3, v5
	global_store_dwordx4 v[8:9], v[2:5], off offset:96 sc0 sc1
	s_cbranch_scc1 .LBB0_631

; __device__ __forceinline__ unsigned cvtpk(float lo, float hi) { f32x2 v = {lo, hi}; bf16x2_t b = __builtin_convertvector(v, bf16x2_t); return __builtin_bit_cast(unsigned, b); }
;     __device__ __forceinline__ void operator()(AccRef acc, const Unit& u, int wr, int wc, int fr, int fq) const {
;     ...
;                 const int row = row0 + ai * 128 + m * 16; bf16_t* rowp = XB + (size_t)row * DM + col0; float s = 0.f;
; #pragma unroll
;                 for (int bj = 0; bj < 2; ++bj) {
;                     const u32x4 xo = *(const u32x4*)(rowp + bj * 128);
;                     float v[8];
; #pragma unroll
;                     for (int k = 0; k < 4; ++k) { v[2 * k] = __uint_as_float(xo[k] << 16) + acc[ai][bj][m][k >> 1][(2 * k) & 3]; v[2 * k + 1] = __uint_as_float(xo[k] & 0xffff0000u) + acc[ai][bj][m][k >> 1][(2 * k + 1) & 3]; }
; #pragma unroll
;                     for (int k = 0; k < 8; ++k) s += v[k] * v[k];
;                     u32x4 w; w.x = cvtpk(v[0], v[1]); w.y = cvtpk(v[2], v[3]); w.z = cvtpk(v[4], v[5]); w.w = cvtpk(v[6], v[7]);
;                     st16_wt(rowp + bj * 128, w);
;                 }
;                 s += __shfl_xor(s, 16); s += __shfl_xor(s, 32);
;                 if (fq == 0) red[(ai * 128 + wr * 64 + m * 16 + fr) * 4 + wc] = s;
.LBB0_704:
	v_and_b32_e32 v144, 64, v213
	v_xor_b32_e32 v143, 16, v213
	v_add_u32_e32 v144, 64, v144
	v_cmp_lt_i32_e32 vcc, v143, v144
	s_lshl_b32 s51, s51, 8
	v_add_u32_e32 v142, s51, v146
	v_cndmask_b32_e32 v143, v213, v143, vcc
	v_lshlrev_b32_e32 v154, 2, v143
	v_xor_b32_e32 v143, 32, v213
	v_cmp_lt_i32_e32 vcc, v143, v144
	v_lshl_or_b32 v140, s50, 8, v148
	v_ashrrev_i32_e32 v141, 31, v140
	v_cndmask_b32_e32 v143, v213, v143, vcc
	v_lshlrev_b32_e32 v153, 2, v143
	v_ashrrev_i32_e32 v143, 31, v142
	v_lshlrev_b64 v[144:145], 11, v[142:143]
	v_lshl_add_u64 v[144:145], s[66:67], 0, v[144:145]
	v_lshl_add_u64 v[144:145], v[140:141], 1, v[144:145]
	v_mov_b64_e32 v[226:227], v[144:145]
	global_load_dwordx4 v[168:171], v[226:227], off
	global_load_dwordx4 v[172:175], v[226:227], off offset:256
	s_mov_b64 s[20:21], 0x8000
	s_nop 0
	v_lshl_add_u64 v[224:225], v[226:227], 0, s[20:21]
	global_load_dwordx4 v[176:179], v[224:225], off
	global_load_dwordx4 v[180:183], v[224:225], off offset:256
	s_mov_b64 s[20:21], 0x10000
	s_nop 0
	v_lshl_add_u64 v[224:225], v[226:227], 0, s[20:21]
	global_load_dwordx4 v[184:187], v[224:225], off
	global_load_dwordx4 v[188:191], v[224:225], off offset:256
	s_mov_b64 s[20:21], 0x18000
	s_nop 0
	v_lshl_add_u64 v[224:225], v[226:227], 0, s[20:21]
	global_load_dwordx4 v[192:195], v[224:225], off
	global_load_dwordx4 v[196:199], v[224:225], off offset:256
	s_mov_b64 s[20:21], 0x40000
	s_nop 0
	v_lshl_add_u64 v[224:225], v[226:227], 0, s[20:21]
	global_load_dwordx4 v[200:203], v[224:225], off
	global_load_dwordx4 v[204:207], v[224:225], off offset:256
	s_waitcnt vmcnt(9)
	v_lshlrev_b32_e32 v160, 16, v168
	v_and_b32_e32 v161, 0xffff0000, v168
	v_pk_add_f32 v[160:161], v[126:127], v[160:161]
	v_lshlrev_b32_e32 v126, 16, v169
	v_and_b32_e32 v127, 0xffff0000, v169
	v_pk_add_f32 v[162:163], v[128:129], v[126:127]
	v_lshlrev_b32_e32 v126, 16, v170
	v_and_b32_e32 v127, 0xffff0000, v170
	v_pk_add_f32 v[164:165], v[122:123], v[126:127]
	v_lshlrev_b32_e32 v122, 16, v171
	v_and_b32_e32 v123, 0xffff0000, v171
	v_pk_add_f32 v[166:167], v[124:125], v[122:123]
	v_cvt_pk_bf16_f32 v156, v160, v161
	v_cvt_pk_bf16_f32 v157, v162, v163
	v_cvt_pk_bf16_f32 v158, v164, v165
	v_cvt_pk_bf16_f32 v159, v166, v167
	global_store_dwordx4 v[144:145], v[156:159], off sc0 sc1
	v_pk_mul_f32 v[128:129], v[160:161], v[160:161]
	v_pk_mul_f32 v[126:127], v[162:163], v[162:163]
	v_add_f32_e32 v128, v128, v129
	v_add_f32_e32 v126, v126, v128
	v_pk_mul_f32 v[124:125], v[164:165], v[164:165]
	v_add_f32_e32 v126, v127, v126
	v_add_f32_e32 v124, v124, v126
	v_pk_mul_f32 v[122:123], v[166:167], v[166:167]
	v_add_f32_e32 v124, v125, v124
	v_add_f32_e32 v122, v122, v124
	v_add_f32_e32 v122, v123, v122
	s_waitcnt vmcnt(9)
	v_lshlrev_b32_e32 v160, 16, v172
	v_and_b32_e32 v161, 0xffff0000, v172
	v_lshlrev_b32_e32 v156, 16, v173
	v_and_b32_e32 v157, 0xffff0000, v173
	v_pk_add_f32 v[120:121], v[120:121], v[156:157]
	v_lshlrev_b32_e32 v156, 16, v174
	v_and_b32_e32 v157, 0xffff0000, v174
	v_pk_add_f32 v[118:119], v[118:119], v[160:161]
	v_pk_add_f32 v[156:157], v[114:115], v[156:157]
	v_lshlrev_b32_e32 v114, 16, v175
	v_and_b32_e32 v115, 0xffff0000, v175
	v_pk_add_f32 v[158:159], v[116:117], v[114:115]
	v_pk_mul_f32 v[114:115], v[118:119], v[118:119]
	v_pk_mul_f32 v[116:117], v[120:121], v[120:121]
	v_add_f32_e32 v114, v114, v122
	v_add_f32_e32 v114, v115, v114
	v_add_f32_e32 v114, v116, v114
	v_pk_mul_f32 v[160:161], v[156:157], v[156:157]
	v_add_f32_e32 v114, v117, v114
	v_add_f32_e32 v114, v160, v114
	v_pk_mul_f32 v[162:163], v[158:159], v[158:159]
	v_add_f32_e32 v114, v161, v114
	v_add_f32_e32 v114, v162, v114
	v_add_f32_e32 v122, v163, v114
	v_cvt_pk_bf16_f32 v114, v118, v119
	v_cvt_pk_bf16_f32 v115, v120, v121
	v_cvt_pk_bf16_f32 v116, v156, v157
	v_cvt_pk_bf16_f32 v117, v158, v159
	global_store_dwordx4 v[144:145], v[114:117], off offset:256 sc0 sc1
	s_mov_b64 s[20:21], 0x48000
	s_nop 0
	v_lshl_add_u64 v[224:225], v[226:227], 0, s[20:21]
	global_load_dwordx4 v[168:171], v[224:225], off
	global_load_dwordx4 v[172:175], v[224:225], off offset:256
	ds_bpermute_b32 v114, v154, v122
	s_waitcnt lgkmcnt(0)
	v_add_f32_e32 v114, v122, v114
	ds_bpermute_b32 v115, v153, v114
	s_and_saveexec_b64 s[20:21], s[40:41]
	s_cbranch_execz .LBB0_706
	s_waitcnt lgkmcnt(0)
	v_add_f32_e32 v114, v114, v115
	ds_write_b32 v150, v114
; __device__ __forceinline__ unsigned cvtpk(float lo, float hi) { f32x2 v = {lo, hi}; bf16x2_t b = __builtin_convertvector(v, bf16x2_t); return __builtin_bit_cast(unsigned, b); }
;     __device__ __forceinline__ void operator()(AccRef acc, const Unit& u, int wr, int wc, int fr, int fq) const {
;     ...
;                 const int row = row0 + ai * 128 + m * 16; bf16_t* rowp = XB + (size_t)row * DM + col0; float s = 0.f;
; #pragma unroll
;                 for (int bj = 0; bj < 2; ++bj) {
;                     const u32x4 xo = *(const u32x4*)(rowp + bj * 128);
;                     float v[8];
; #pragma unroll
;                     for (int k = 0; k < 4; ++k) { v[2 * k] = __uint_as_float(xo[k] << 16) + acc[ai][bj][m][k >> 1][(2 * k) & 3]; v[2 * k + 1] = __uint_as_float(xo[k] & 0xffff0000u) + acc[ai][bj][m][k >> 1][(2 * k + 1) & 3]; }
; #pragma unroll
;                     for (int k = 0; k < 8; ++k) s += v[k] * v[k];
;                     u32x4 w; w.x = cvtpk(v[0], v[1]); w.y = cvtpk(v[2], v[3]); w.z = cvtpk(v[4], v[5]); w.w = cvtpk(v[6], v[7]);
;                     st16_wt(rowp + bj * 128, w);
;                 }
;                 s += __shfl_xor(s, 16); s += __shfl_xor(s, 32);
;                 if (fq == 0) red[(ai * 128 + wr * 64 + m * 16 + fr) * 4 + wc] = s;
.LBB0_706:
	s_or_b64 exec, exec, s[20:21]
	v_or_b32_e32 v114, 16, v142
	s_waitcnt lgkmcnt(0)
	v_ashrrev_i32_e32 v115, 31, v114
	v_lshlrev_b64 v[114:115], 11, v[114:115]
	v_lshl_add_u64 v[114:115], s[66:67], 0, v[114:115]
	v_lshl_add_u64 v[114:115], v[140:141], 1, v[114:115]
	s_waitcnt vmcnt(11)
	v_lshlrev_b32_e32 v120, 16, v176
	v_and_b32_e32 v121, 0xffff0000, v176
	v_lshlrev_b32_e32 v116, 16, v177
	v_and_b32_e32 v117, 0xffff0000, v177
	v_pk_add_f32 v[112:113], v[112:113], v[116:117]
	v_lshlrev_b32_e32 v116, 16, v178
	v_and_b32_e32 v117, 0xffff0000, v178
	v_pk_add_f32 v[116:117], v[106:107], v[116:117]
	v_lshlrev_b32_e32 v106, 16, v179
	v_and_b32_e32 v107, 0xffff0000, v179
	v_pk_add_f32 v[110:111], v[110:111], v[120:121]
	v_pk_add_f32 v[118:119], v[108:109], v[106:107]
	v_cvt_pk_bf16_f32 v106, v110, v111
	v_cvt_pk_bf16_f32 v107, v112, v113
	v_cvt_pk_bf16_f32 v108, v116, v117
	v_cvt_pk_bf16_f32 v109, v118, v119
	global_store_dwordx4 v[114:115], v[106:109], off sc0 sc1
	v_pk_mul_f32 v[120:121], v[110:111], v[110:111]
	v_pk_mul_f32 v[122:123], v[112:113], v[112:113]
	v_pk_mul_f32 v[124:125], v[116:117], v[116:117]
	v_add_f32_e32 v116, v120, v121
	v_add_f32_e32 v116, v122, v116
	v_add_f32_e32 v116, v123, v116
	v_add_f32_e32 v116, v124, v116
	v_pk_mul_f32 v[126:127], v[118:119], v[118:119]
	v_add_f32_e32 v116, v125, v116
	v_add_f32_e32 v116, v126, v116
	v_add_f32_e32 v116, v127, v116
	s_waitcnt vmcnt(11)
	v_lshlrev_b32_e32 v110, 16, v180
	v_and_b32_e32 v111, 0xffff0000, v180
	v_lshlrev_b32_e32 v106, 16, v181
	v_and_b32_e32 v107, 0xffff0000, v181
	v_pk_add_f32 v[104:105], v[104:105], v[106:107]
	v_lshlrev_b32_e32 v106, 16, v182
	v_and_b32_e32 v107, 0xffff0000, v182
	v_pk_add_f32 v[102:103], v[102:103], v[110:111]
	v_pk_add_f32 v[106:107], v[98:99], v[106:107]
	v_lshlrev_b32_e32 v98, 16, v183
	v_and_b32_e32 v99, 0xffff0000, v183
	v_pk_add_f32 v[108:109], v[100:101], v[98:99]
	v_pk_mul_f32 v[98:99], v[102:103], v[102:103]
	v_pk_mul_f32 v[100:101], v[104:105], v[104:105]
	v_add_f32_e32 v98, v98, v116
	v_add_f32_e32 v98, v99, v98
	v_add_f32_e32 v98, v100, v98
	v_pk_mul_f32 v[110:111], v[106:107], v[106:107]
	v_add_f32_e32 v98, v101, v98
	v_add_f32_e32 v98, v110, v98
	v_pk_mul_f32 v[112:113], v[108:109], v[108:109]
	v_add_f32_e32 v98, v111, v98
	v_add_f32_e32 v98, v112, v98
	v_add_f32_e32 v110, v113, v98
	v_cvt_pk_bf16_f32 v98, v102, v103
	v_cvt_pk_bf16_f32 v99, v104, v105
	v_cvt_pk_bf16_f32 v100, v106, v107
	v_cvt_pk_bf16_f32 v101, v108, v109
	global_store_dwordx4 v[114:115], v[98:101], off offset:256 sc0 sc1
	s_mov_b64 s[20:21], 0x50000
	s_nop 0
	v_lshl_add_u64 v[224:225], v[226:227], 0, s[20:21]
	global_load_dwordx4 v[176:179], v[224:225], off
	global_load_dwordx4 v[180:183], v[224:225], off offset:256
	ds_bpermute_b32 v98, v154, v110
	s_waitcnt lgkmcnt(0)
	v_add_f32_e32 v98, v110, v98
	ds_bpermute_b32 v99, v153, v98
	s_and_saveexec_b64 s[20:21], s[40:41]
	s_cbranch_execz .LBB0_708
	s_waitcnt lgkmcnt(0)
	v_add_f32_e32 v98, v98, v99
	ds_write_b32 v150, v98 offset:256
.LBB0_708:
	s_or_b64 exec, exec, s[20:21]
	v_or_b32_e32 v98, 32, v142
	s_waitcnt lgkmcnt(0)
	v_ashrrev_i32_e32 v99, 31, v98
	v_lshlrev_b64 v[98:99], 11, v[98:99]
	v_lshl_add_u64 v[98:99], s[66:67], 0, v[98:99]
	v_lshl_add_u64 v[98:99], v[140:141], 1, v[98:99]
	s_waitcnt vmcnt(13)
	v_lshlrev_b32_e32 v104, 16, v184
	v_and_b32_e32 v105, 0xffff0000, v184
	v_lshlrev_b32_e32 v100, 16, v185
	v_and_b32_e32 v101, 0xffff0000, v185
	v_pk_add_f32 v[96:97], v[96:97], v[100:101]
	v_lshlrev_b32_e32 v100, 16, v186
	v_and_b32_e32 v101, 0xffff0000, v186
	v_pk_add_f32 v[100:101], v[90:91], v[100:101]
	v_lshlrev_b32_e32 v90, 16, v187
	v_and_b32_e32 v91, 0xffff0000, v187
	v_pk_add_f32 v[94:95], v[94:95], v[104:105]
	v_pk_add_f32 v[102:103], v[92:93], v[90:91]
	v_cvt_pk_bf16_f32 v90, v94, v95
	v_cvt_pk_bf16_f32 v91, v96, v97
	v_cvt_pk_bf16_f32 v92, v100, v101
	v_cvt_pk_bf16_f32 v93, v102, v103
	global_store_dwordx4 v[98:99], v[90:93], off sc0 sc1
	v_pk_mul_f32 v[104:105], v[94:95], v[94:95]
	v_pk_mul_f32 v[106:107], v[96:97], v[96:97]
	v_pk_mul_f32 v[108:109], v[100:101], v[100:101]
	v_add_f32_e32 v100, v104, v105
	v_add_f32_e32 v100, v106, v100
	v_add_f32_e32 v100, v107, v100
	v_add_f32_e32 v100, v108, v100
	v_pk_mul_f32 v[110:111], v[102:103], v[102:103]
	v_add_f32_e32 v100, v109, v100
	v_add_f32_e32 v100, v110, v100
	v_add_f32_e32 v100, v111, v100
	s_waitcnt vmcnt(13)
	v_lshlrev_b32_e32 v94, 16, v188
	v_and_b32_e32 v95, 0xffff0000, v188
	v_lshlrev_b32_e32 v90, 16, v189
	v_and_b32_e32 v91, 0xffff0000, v189
	v_pk_add_f32 v[88:89], v[88:89], v[90:91]
	v_lshlrev_b32_e32 v90, 16, v190
	v_and_b32_e32 v91, 0xffff0000, v190
	v_pk_add_f32 v[86:87], v[86:87], v[94:95]
	v_pk_add_f32 v[90:91], v[82:83], v[90:91]
	v_lshlrev_b32_e32 v82, 16, v191
	v_and_b32_e32 v83, 0xffff0000, v191
	v_pk_add_f32 v[92:93], v[84:85], v[82:83]
	v_pk_mul_f32 v[82:83], v[86:87], v[86:87]
	v_pk_mul_f32 v[84:85], v[88:89], v[88:89]
	v_add_f32_e32 v82, v82, v100
	v_add_f32_e32 v82, v83, v82
	v_add_f32_e32 v82, v84, v82
	v_pk_mul_f32 v[94:95], v[90:91], v[90:91]
	v_add_f32_e32 v82, v85, v82
	v_add_f32_e32 v82, v94, v82
	v_pk_mul_f32 v[96:97], v[92:93], v[92:93]
	v_add_f32_e32 v82, v95, v82
	v_add_f32_e32 v82, v96, v82
	v_add_f32_e32 v94, v97, v82
	v_cvt_pk_bf16_f32 v82, v86, v87
	v_cvt_pk_bf16_f32 v83, v88, v89
	v_cvt_pk_bf16_f32 v84, v90, v91
	v_cvt_pk_bf16_f32 v85, v92, v93
	global_store_dwordx4 v[98:99], v[82:85], off offset:256 sc0 sc1
	s_mov_b64 s[20:21], 0x58000
	s_nop 0
	v_lshl_add_u64 v[224:225], v[226:227], 0, s[20:21]
	global_load_dwordx4 v[184:187], v[224:225], off
	global_load_dwordx4 v[188:191], v[224:225], off offset:256
	ds_bpermute_b32 v82, v154, v94
	s_waitcnt lgkmcnt(0)
	v_add_f32_e32 v82, v94, v82
	ds_bpermute_b32 v83, v153, v82
	s_and_saveexec_b64 s[20:21], s[40:41]
	s_cbranch_execz .LBB0_710
	s_waitcnt lgkmcnt(0)
	v_add_f32_e32 v82, v82, v83
	ds_write_b32 v150, v82 offset:512
; __device__ __forceinline__ unsigned cvtpk(float lo, float hi) { f32x2 v = {lo, hi}; bf16x2_t b = __builtin_convertvector(v, bf16x2_t); return __builtin_bit_cast(unsigned, b); }
;     __device__ __forceinline__ void operator()(AccRef acc, const Unit& u, int wr, int wc, int fr, int fq) const {
;     ...
;                 const int row = row0 + ai * 128 + m * 16; bf16_t* rowp = XB + (size_t)row * DM + col0; float s = 0.f;
; #pragma unroll
;                 for (int bj = 0; bj < 2; ++bj) {
;                     const u32x4 xo = *(const u32x4*)(rowp + bj * 128);
;                     float v[8];
; #pragma unroll
;                     for (int k = 0; k < 4; ++k) { v[2 * k] = __uint_as_float(xo[k] << 16) + acc[ai][bj][m][k >> 1][(2 * k) & 3]; v[2 * k + 1] = __uint_as_float(xo[k] & 0xffff0000u) + acc[ai][bj][m][k >> 1][(2 * k + 1) & 3]; }
; #pragma unroll
;                     for (int k = 0; k < 8; ++k) s += v[k] * v[k];
;                     u32x4 w; w.x = cvtpk(v[0], v[1]); w.y = cvtpk(v[2], v[3]); w.z = cvtpk(v[4], v[5]); w.w = cvtpk(v[6], v[7]);
;                     st16_wt(rowp + bj * 128, w);
;                 }
;                 s += __shfl_xor(s, 16); s += __shfl_xor(s, 32);
;                 if (fq == 0) red[(ai * 128 + wr * 64 + m * 16 + fr) * 4 + wc] = s;
.LBB0_710:
	s_or_b64 exec, exec, s[20:21]
	v_or_b32_e32 v82, 48, v142
	s_waitcnt lgkmcnt(0)
	v_ashrrev_i32_e32 v83, 31, v82
	v_lshlrev_b64 v[82:83], 11, v[82:83]
	v_lshl_add_u64 v[82:83], s[66:67], 0, v[82:83]
	v_lshl_add_u64 v[82:83], v[140:141], 1, v[82:83]
	s_waitcnt vmcnt(15)
	v_lshlrev_b32_e32 v88, 16, v192
	v_and_b32_e32 v89, 0xffff0000, v192
	v_lshlrev_b32_e32 v84, 16, v193
	v_and_b32_e32 v85, 0xffff0000, v193
	v_pk_add_f32 v[80:81], v[80:81], v[84:85]
	v_lshlrev_b32_e32 v84, 16, v194
	v_and_b32_e32 v85, 0xffff0000, v194
	v_pk_add_f32 v[84:85], v[74:75], v[84:85]
	v_lshlrev_b32_e32 v74, 16, v195
	v_and_b32_e32 v75, 0xffff0000, v195
	v_pk_add_f32 v[78:79], v[78:79], v[88:89]
	v_pk_add_f32 v[86:87], v[76:77], v[74:75]
	v_cvt_pk_bf16_f32 v74, v78, v79
	v_cvt_pk_bf16_f32 v75, v80, v81
	v_cvt_pk_bf16_f32 v76, v84, v85
	v_cvt_pk_bf16_f32 v77, v86, v87
	global_store_dwordx4 v[82:83], v[74:77], off sc0 sc1
	v_pk_mul_f32 v[88:89], v[78:79], v[78:79]
	v_pk_mul_f32 v[90:91], v[80:81], v[80:81]
	v_pk_mul_f32 v[92:93], v[84:85], v[84:85]
	v_add_f32_e32 v84, v88, v89
	v_add_f32_e32 v84, v90, v84
	v_add_f32_e32 v84, v91, v84
	v_add_f32_e32 v84, v92, v84
	v_pk_mul_f32 v[94:95], v[86:87], v[86:87]
	v_add_f32_e32 v84, v93, v84
	v_add_f32_e32 v84, v94, v84
	v_add_f32_e32 v84, v95, v84
	s_waitcnt vmcnt(15)
	v_lshlrev_b32_e32 v78, 16, v196
	v_and_b32_e32 v79, 0xffff0000, v196
	v_lshlrev_b32_e32 v74, 16, v197
	v_and_b32_e32 v75, 0xffff0000, v197
	v_pk_add_f32 v[72:73], v[72:73], v[74:75]
	v_lshlrev_b32_e32 v74, 16, v198
	v_and_b32_e32 v75, 0xffff0000, v198
	v_pk_add_f32 v[70:71], v[70:71], v[78:79]
	v_pk_add_f32 v[74:75], v[66:67], v[74:75]
	v_lshlrev_b32_e32 v66, 16, v199
	v_and_b32_e32 v67, 0xffff0000, v199
	v_pk_add_f32 v[76:77], v[68:69], v[66:67]
	v_pk_mul_f32 v[66:67], v[70:71], v[70:71]
	v_pk_mul_f32 v[68:69], v[72:73], v[72:73]
	v_add_f32_e32 v66, v66, v84
	v_add_f32_e32 v66, v67, v66
	v_add_f32_e32 v66, v68, v66
	v_pk_mul_f32 v[78:79], v[74:75], v[74:75]
	v_add_f32_e32 v66, v69, v66
	v_add_f32_e32 v66, v78, v66
	v_pk_mul_f32 v[80:81], v[76:77], v[76:77]
	v_add_f32_e32 v66, v79, v66
	v_add_f32_e32 v66, v80, v66
	v_add_f32_e32 v78, v81, v66
	v_cvt_pk_bf16_f32 v66, v70, v71
	v_cvt_pk_bf16_f32 v67, v72, v73
	v_cvt_pk_bf16_f32 v68, v74, v75
	v_cvt_pk_bf16_f32 v69, v76, v77
	global_store_dwordx4 v[82:83], v[66:69], off offset:256 sc0 sc1
	ds_bpermute_b32 v66, v154, v78
	s_waitcnt lgkmcnt(0)
	v_add_f32_e32 v66, v78, v66
	ds_bpermute_b32 v67, v153, v66
	s_and_saveexec_b64 s[20:21], s[40:41]
	s_cbranch_execz .LBB0_712
	s_waitcnt lgkmcnt(0)
	v_add_f32_e32 v66, v66, v67
	ds_write_b32 v150, v66 offset:768
.LBB0_712:
	s_or_b64 exec, exec, s[20:21]
	s_waitcnt lgkmcnt(0)
	v_lshlrev_b64 v[66:67], 11, v[142:143]
	v_lshl_add_u64 v[66:67], s[66:67], 0, v[66:67]
	v_lshl_add_u64 v[66:67], v[140:141], 1, v[66:67]
	v_add_co_u32_e32 v74, vcc, 0x40000, v66
	s_mov_b64 s[20:21], 0x40000
	s_nop 0
	v_addc_co_u32_e32 v75, vcc, 0, v67, vcc
	v_lshl_add_u64 v[68:69], v[66:67], 0, s[20:21]
	s_waitcnt vmcnt(15)
	v_lshlrev_b32_e32 v76, 16, v200
	v_and_b32_e32 v77, 0xffff0000, v200
	v_pk_add_f32 v[76:77], v[62:63], v[76:77]
	v_lshlrev_b32_e32 v62, 16, v201
	v_and_b32_e32 v63, 0xffff0000, v201
	v_pk_add_f32 v[78:79], v[64:65], v[62:63]
	v_lshlrev_b32_e32 v62, 16, v202
	v_and_b32_e32 v63, 0xffff0000, v202
	v_pk_add_f32 v[80:81], v[58:59], v[62:63]
	v_lshlrev_b32_e32 v58, 16, v203
	v_and_b32_e32 v59, 0xffff0000, v203
	v_pk_add_f32 v[82:83], v[60:61], v[58:59]
	v_cvt_pk_bf16_f32 v70, v76, v77
	v_cvt_pk_bf16_f32 v71, v78, v79
	v_cvt_pk_bf16_f32 v72, v80, v81
	v_cvt_pk_bf16_f32 v73, v82, v83
	global_store_dwordx4 v[74:75], v[70:73], off sc0 sc1
	v_pk_mul_f32 v[64:65], v[76:77], v[76:77]
	v_pk_mul_f32 v[62:63], v[78:79], v[78:79]
	v_add_f32_e32 v64, v64, v65
	v_add_f32_e32 v62, v62, v64
	v_pk_mul_f32 v[60:61], v[80:81], v[80:81]
	v_add_f32_e32 v62, v63, v62
	v_add_f32_e32 v60, v60, v62
	v_pk_mul_f32 v[58:59], v[82:83], v[82:83]
	v_add_f32_e32 v60, v61, v60
	v_add_f32_e32 v58, v58, v60
	v_add_f32_e32 v58, v59, v58
	s_waitcnt vmcnt(15)
	v_lshlrev_b32_e32 v74, 16, v204
	v_and_b32_e32 v75, 0xffff0000, v204
	v_lshlrev_b32_e32 v70, 16, v205
	v_and_b32_e32 v71, 0xffff0000, v205
	v_pk_add_f32 v[56:57], v[56:57], v[70:71]
	v_lshlrev_b32_e32 v70, 16, v206
	v_and_b32_e32 v71, 0xffff0000, v206
	v_pk_add_f32 v[54:55], v[54:55], v[74:75]
	v_pk_add_f32 v[70:71], v[50:51], v[70:71]
	v_lshlrev_b32_e32 v50, 16, v207
	v_and_b32_e32 v51, 0xffff0000, v207
	v_pk_add_f32 v[72:73], v[52:53], v[50:51]
	v_pk_mul_f32 v[50:51], v[54:55], v[54:55]
	v_pk_mul_f32 v[52:53], v[56:57], v[56:57]
	v_add_f32_e32 v50, v50, v58
	v_add_f32_e32 v50, v51, v50
	v_add_f32_e32 v50, v52, v50
	v_pk_mul_f32 v[74:75], v[70:71], v[70:71]
	v_add_f32_e32 v50, v53, v50
	v_add_f32_e32 v50, v74, v50
	v_pk_mul_f32 v[76:77], v[72:73], v[72:73]
	v_add_f32_e32 v50, v75, v50
	v_add_f32_e32 v50, v76, v50
	v_add_f32_e32 v58, v77, v50
	v_cvt_pk_bf16_f32 v50, v54, v55
	v_cvt_pk_bf16_f32 v51, v56, v57
	v_cvt_pk_bf16_f32 v52, v70, v71
	v_cvt_pk_bf16_f32 v53, v72, v73
	global_store_dwordx4 v[68:69], v[50:53], off offset:256 sc0 sc1
	ds_bpermute_b32 v50, v154, v58
	s_waitcnt lgkmcnt(0)
	v_add_f32_e32 v50, v58, v50
	ds_bpermute_b32 v51, v153, v50
	s_and_saveexec_b64 s[20:21], s[40:41]
	s_cbranch_execz .LBB0_714
	s_waitcnt lgkmcnt(0)
	v_add_f32_e32 v50, v50, v51
	ds_write_b32 v150, v50 offset:2048
; __device__ __forceinline__ unsigned cvtpk(float lo, float hi) { f32x2 v = {lo, hi}; bf16x2_t b = __builtin_convertvector(v, bf16x2_t); return __builtin_bit_cast(unsigned, b); }
;     __device__ __forceinline__ void operator()(AccRef acc, const Unit& u, int wr, int wc, int fr, int fq) const {
;     ...
;                 const int row = row0 + ai * 128 + m * 16; bf16_t* rowp = XB + (size_t)row * DM + col0; float s = 0.f;
; #pragma unroll
;                 for (int bj = 0; bj < 2; ++bj) {
;                     const u32x4 xo = *(const u32x4*)(rowp + bj * 128);
;                     float v[8];
; #pragma unroll
;                     for (int k = 0; k < 4; ++k) { v[2 * k] = __uint_as_float(xo[k] << 16) + acc[ai][bj][m][k >> 1][(2 * k) & 3]; v[2 * k + 1] = __uint_as_float(xo[k] & 0xffff0000u) + acc[ai][bj][m][k >> 1][(2 * k + 1) & 3]; }
; #pragma unroll
;                     for (int k = 0; k < 8; ++k) s += v[k] * v[k];
;                     u32x4 w; w.x = cvtpk(v[0], v[1]); w.y = cvtpk(v[2], v[3]); w.z = cvtpk(v[4], v[5]); w.w = cvtpk(v[6], v[7]);
;                     st16_wt(rowp + bj * 128, w);
;                 }
;                 s += __shfl_xor(s, 16); s += __shfl_xor(s, 32);
;                 if (fq == 0) red[(ai * 128 + wr * 64 + m * 16 + fr) * 4 + wc] = s;
.LBB0_714:
	s_or_b64 exec, exec, s[20:21]
	v_add_co_u32_e32 v56, vcc, 0x48000, v66
	s_mov_b64 s[20:21], 0x48000
	s_nop 0
	v_addc_co_u32_e32 v57, vcc, 0, v67, vcc
	s_waitcnt lgkmcnt(0)
	v_lshl_add_u64 v[50:51], v[66:67], 0, s[20:21]
	s_waitcnt vmcnt(13)
	v_lshlrev_b32_e32 v58, 16, v168
	v_and_b32_e32 v59, 0xffff0000, v168
	v_pk_add_f32 v[58:59], v[46:47], v[58:59]
	v_lshlrev_b32_e32 v46, 16, v169
	v_and_b32_e32 v47, 0xffff0000, v169
	v_pk_add_f32 v[60:61], v[48:49], v[46:47]
	v_lshlrev_b32_e32 v46, 16, v170
	v_and_b32_e32 v47, 0xffff0000, v170
	v_pk_add_f32 v[62:63], v[42:43], v[46:47]
	v_lshlrev_b32_e32 v42, 16, v171
	v_and_b32_e32 v43, 0xffff0000, v171
	v_pk_add_f32 v[64:65], v[44:45], v[42:43]
	v_cvt_pk_bf16_f32 v52, v58, v59
	v_cvt_pk_bf16_f32 v53, v60, v61
	v_cvt_pk_bf16_f32 v54, v62, v63
	v_cvt_pk_bf16_f32 v55, v64, v65
	global_store_dwordx4 v[56:57], v[52:55], off sc0 sc1
	v_pk_mul_f32 v[48:49], v[58:59], v[58:59]
	v_pk_mul_f32 v[46:47], v[60:61], v[60:61]
	v_add_f32_e32 v48, v48, v49
	v_add_f32_e32 v46, v46, v48
	v_pk_mul_f32 v[44:45], v[62:63], v[62:63]
	v_add_f32_e32 v46, v47, v46
	v_add_f32_e32 v44, v44, v46
	v_pk_mul_f32 v[42:43], v[64:65], v[64:65]
	v_add_f32_e32 v44, v45, v44
	v_add_f32_e32 v42, v42, v44
	v_add_f32_e32 v42, v43, v42
	s_waitcnt vmcnt(13)
	v_lshlrev_b32_e32 v56, 16, v172
	v_and_b32_e32 v57, 0xffff0000, v172
	v_lshlrev_b32_e32 v52, 16, v173
	v_and_b32_e32 v53, 0xffff0000, v173
	v_pk_add_f32 v[40:41], v[40:41], v[52:53]
	v_lshlrev_b32_e32 v52, 16, v174
	v_and_b32_e32 v53, 0xffff0000, v174
	v_pk_add_f32 v[38:39], v[38:39], v[56:57]
	v_pk_add_f32 v[52:53], v[34:35], v[52:53]
	v_lshlrev_b32_e32 v34, 16, v175
	v_and_b32_e32 v35, 0xffff0000, v175
	v_pk_add_f32 v[54:55], v[36:37], v[34:35]
	v_pk_mul_f32 v[34:35], v[38:39], v[38:39]
	v_pk_mul_f32 v[36:37], v[40:41], v[40:41]
	v_add_f32_e32 v34, v34, v42
	v_add_f32_e32 v34, v35, v34
	v_add_f32_e32 v34, v36, v34
	v_pk_mul_f32 v[56:57], v[52:53], v[52:53]
	v_add_f32_e32 v34, v37, v34
	v_add_f32_e32 v34, v56, v34
	v_pk_mul_f32 v[58:59], v[54:55], v[54:55]
	v_add_f32_e32 v34, v57, v34
	v_add_f32_e32 v34, v58, v34
	v_add_f32_e32 v42, v59, v34
	v_cvt_pk_bf16_f32 v34, v38, v39
	v_cvt_pk_bf16_f32 v35, v40, v41
	v_cvt_pk_bf16_f32 v36, v52, v53
	v_cvt_pk_bf16_f32 v37, v54, v55
	global_store_dwordx4 v[50:51], v[34:37], off offset:256 sc0 sc1
	ds_bpermute_b32 v34, v154, v42
	s_waitcnt lgkmcnt(0)
	v_add_f32_e32 v34, v42, v34
	ds_bpermute_b32 v35, v153, v34
	s_and_saveexec_b64 s[20:21], s[40:41]
	s_cbranch_execz .LBB0_716
	s_waitcnt lgkmcnt(0)
	v_add_f32_e32 v34, v34, v35
	ds_write_b32 v150, v34 offset:2304
; __device__ __forceinline__ unsigned cvtpk(float lo, float hi) { f32x2 v = {lo, hi}; bf16x2_t b = __builtin_convertvector(v, bf16x2_t); return __builtin_bit_cast(unsigned, b); }
;     __device__ __forceinline__ void operator()(AccRef acc, const Unit& u, int wr, int wc, int fr, int fq) const {
;     ...
;                 const int row = row0 + ai * 128 + m * 16; bf16_t* rowp = XB + (size_t)row * DM + col0; float s = 0.f;
; #pragma unroll
;                 for (int bj = 0; bj < 2; ++bj) {
;                     const u32x4 xo = *(const u32x4*)(rowp + bj * 128);
;                     float v[8];
; #pragma unroll
;                     for (int k = 0; k < 4; ++k) { v[2 * k] = __uint_as_float(xo[k] << 16) + acc[ai][bj][m][k >> 1][(2 * k) & 3]; v[2 * k + 1] = __uint_as_float(xo[k] & 0xffff0000u) + acc[ai][bj][m][k >> 1][(2 * k + 1) & 3]; }
; #pragma unroll
;                     for (int k = 0; k < 8; ++k) s += v[k] * v[k];
;                     u32x4 w; w.x = cvtpk(v[0], v[1]); w.y = cvtpk(v[2], v[3]); w.z = cvtpk(v[4], v[5]); w.w = cvtpk(v[6], v[7]);
;                     st16_wt(rowp + bj * 128, w);
;                 }
;                 s += __shfl_xor(s, 16); s += __shfl_xor(s, 32);
;                 if (fq == 0) red[(ai * 128 + wr * 64 + m * 16 + fr) * 4 + wc] = s;
.LBB0_716:
	s_or_b64 exec, exec, s[20:21]
	s_waitcnt lgkmcnt(0)
	v_lshlrev_b64 v[34:35], 11, v[142:143]
	v_lshl_add_u64 v[34:35], s[66:67], 0, v[34:35]
	v_lshl_add_u64 v[34:35], v[140:141], 1, v[34:35]
	v_add_co_u32_e32 v42, vcc, 0x50000, v34
	s_mov_b64 s[20:21], 0x50000
	s_nop 0
	v_addc_co_u32_e32 v43, vcc, 0, v35, vcc
	v_lshl_add_u64 v[36:37], v[34:35], 0, s[20:21]
	s_waitcnt vmcnt(11)
	v_lshlrev_b32_e32 v44, 16, v176
	v_and_b32_e32 v45, 0xffff0000, v176
	v_pk_add_f32 v[44:45], v[30:31], v[44:45]
	v_lshlrev_b32_e32 v30, 16, v177
	v_and_b32_e32 v31, 0xffff0000, v177
	v_pk_add_f32 v[46:47], v[32:33], v[30:31]
	v_lshlrev_b32_e32 v30, 16, v178
	v_and_b32_e32 v31, 0xffff0000, v178
	v_pk_add_f32 v[48:49], v[26:27], v[30:31]
	v_lshlrev_b32_e32 v26, 16, v179
	v_and_b32_e32 v27, 0xffff0000, v179
	v_pk_add_f32 v[50:51], v[28:29], v[26:27]
	v_cvt_pk_bf16_f32 v38, v44, v45
	v_cvt_pk_bf16_f32 v39, v46, v47
	v_cvt_pk_bf16_f32 v40, v48, v49
	v_cvt_pk_bf16_f32 v41, v50, v51
	global_store_dwordx4 v[42:43], v[38:41], off sc0 sc1
	v_pk_mul_f32 v[32:33], v[44:45], v[44:45]
	v_pk_mul_f32 v[30:31], v[46:47], v[46:47]
	v_add_f32_e32 v32, v32, v33
	v_add_f32_e32 v30, v30, v32
	v_pk_mul_f32 v[28:29], v[48:49], v[48:49]
	v_add_f32_e32 v30, v31, v30
	v_add_f32_e32 v28, v28, v30
	v_pk_mul_f32 v[26:27], v[50:51], v[50:51]
	v_add_f32_e32 v28, v29, v28
	v_add_f32_e32 v26, v26, v28
	v_add_f32_e32 v26, v27, v26
	s_waitcnt vmcnt(11)
	v_lshlrev_b32_e32 v42, 16, v180
	v_and_b32_e32 v43, 0xffff0000, v180
	v_lshlrev_b32_e32 v38, 16, v181
	v_and_b32_e32 v39, 0xffff0000, v181
	v_pk_add_f32 v[24:25], v[24:25], v[38:39]
	v_lshlrev_b32_e32 v38, 16, v182
	v_and_b32_e32 v39, 0xffff0000, v182
	v_pk_add_f32 v[22:23], v[22:23], v[42:43]
	v_pk_add_f32 v[38:39], v[18:19], v[38:39]
	v_lshlrev_b32_e32 v18, 16, v183
	v_and_b32_e32 v19, 0xffff0000, v183
	v_pk_add_f32 v[40:41], v[20:21], v[18:19]
	v_pk_mul_f32 v[18:19], v[22:23], v[22:23]
	v_pk_mul_f32 v[20:21], v[24:25], v[24:25]
	v_add_f32_e32 v18, v18, v26
	v_add_f32_e32 v18, v19, v18
	v_add_f32_e32 v18, v20, v18
	v_pk_mul_f32 v[42:43], v[38:39], v[38:39]
	v_add_f32_e32 v18, v21, v18
	v_add_f32_e32 v18, v42, v18
	v_pk_mul_f32 v[44:45], v[40:41], v[40:41]
	v_add_f32_e32 v18, v43, v18
	v_add_f32_e32 v18, v44, v18
	v_add_f32_e32 v26, v45, v18
	v_cvt_pk_bf16_f32 v18, v22, v23
	v_cvt_pk_bf16_f32 v19, v24, v25
	v_cvt_pk_bf16_f32 v20, v38, v39
	v_cvt_pk_bf16_f32 v21, v40, v41
	global_store_dwordx4 v[36:37], v[18:21], off offset:256 sc0 sc1
	ds_bpermute_b32 v18, v154, v26
	s_waitcnt lgkmcnt(0)
	v_add_f32_e32 v18, v26, v18
	ds_bpermute_b32 v19, v153, v18
	s_and_saveexec_b64 s[20:21], s[40:41]
	s_cbranch_execz .LBB0_718
	s_waitcnt lgkmcnt(0)
	v_add_f32_e32 v18, v18, v19
	ds_write_b32 v150, v18 offset:2560
.LBB0_718:
	s_or_b64 exec, exec, s[20:21]
	v_add_co_u32_e32 v24, vcc, 0x58000, v34
	s_mov_b64 s[20:21], 0x58000
	s_nop 0
	v_addc_co_u32_e32 v25, vcc, 0, v35, vcc
	s_waitcnt lgkmcnt(0)
	v_lshl_add_u64 v[18:19], v[34:35], 0, s[20:21]
	s_waitcnt vmcnt(9)
	v_lshlrev_b32_e32 v26, 16, v184
	v_and_b32_e32 v27, 0xffff0000, v184
	v_pk_add_f32 v[26:27], v[14:15], v[26:27]
	v_lshlrev_b32_e32 v14, 16, v185
	v_and_b32_e32 v15, 0xffff0000, v185
	v_pk_add_f32 v[28:29], v[16:17], v[14:15]
	v_lshlrev_b32_e32 v14, 16, v186
	v_and_b32_e32 v15, 0xffff0000, v186
	v_pk_add_f32 v[30:31], v[10:11], v[14:15]
	v_lshlrev_b32_e32 v10, 16, v187
	v_and_b32_e32 v11, 0xffff0000, v187
	v_pk_add_f32 v[32:33], v[12:13], v[10:11]
	v_cvt_pk_bf16_f32 v20, v26, v27
	v_cvt_pk_bf16_f32 v21, v28, v29
	v_cvt_pk_bf16_f32 v22, v30, v31
	v_cvt_pk_bf16_f32 v23, v32, v33
	global_store_dwordx4 v[24:25], v[20:23], off sc0 sc1
	v_pk_mul_f32 v[16:17], v[26:27], v[26:27]
	v_pk_mul_f32 v[14:15], v[28:29], v[28:29]
	v_add_f32_e32 v16, v16, v17
	v_add_f32_e32 v14, v14, v16
	v_pk_mul_f32 v[12:13], v[30:31], v[30:31]
	v_add_f32_e32 v14, v15, v14
	v_add_f32_e32 v12, v12, v14
	v_pk_mul_f32 v[10:11], v[32:33], v[32:33]
	v_add_f32_e32 v12, v13, v12
	v_add_f32_e32 v10, v10, v12
	v_add_f32_e32 v10, v11, v10
	s_waitcnt vmcnt(9)
	v_lshlrev_b32_e32 v24, 16, v188
	v_and_b32_e32 v25, 0xffff0000, v188
	v_lshlrev_b32_e32 v20, 16, v189
	v_and_b32_e32 v21, 0xffff0000, v189
	v_pk_add_f32 v[8:9], v[8:9], v[20:21]
	v_lshlrev_b32_e32 v20, 16, v190
	v_and_b32_e32 v21, 0xffff0000, v190
	v_pk_add_f32 v[6:7], v[6:7], v[24:25]
	v_pk_add_f32 v[20:21], v[2:3], v[20:21]
	v_lshlrev_b32_e32 v2, 16, v191
	v_and_b32_e32 v3, 0xffff0000, v191
	v_pk_add_f32 v[22:23], v[4:5], v[2:3]
	v_pk_mul_f32 v[2:3], v[6:7], v[6:7]
	v_pk_mul_f32 v[4:5], v[8:9], v[8:9]
	v_add_f32_e32 v2, v2, v10
	v_add_f32_e32 v2, v3, v2
	v_add_f32_e32 v2, v4, v2
	v_pk_mul_f32 v[24:25], v[20:21], v[20:21]
	v_add_f32_e32 v2, v5, v2
	v_add_f32_e32 v2, v24, v2
	v_pk_mul_f32 v[26:27], v[22:23], v[22:23]
	v_add_f32_e32 v2, v25, v2
	v_add_f32_e32 v2, v26, v2
	v_add_f32_e32 v10, v27, v2
	v_cvt_pk_bf16_f32 v2, v6, v7
	v_cvt_pk_bf16_f32 v3, v8, v9
	v_cvt_pk_bf16_f32 v4, v20, v21
	v_cvt_pk_bf16_f32 v5, v22, v23
	global_store_dwordx4 v[18:19], v[2:5], off offset:256 sc0 sc1
	ds_bpermute_b32 v2, v154, v10
	s_waitcnt lgkmcnt(0)
	v_add_f32_e32 v2, v10, v2
	ds_bpermute_b32 v3, v153, v2
	s_and_saveexec_b64 s[20:21], s[40:41]
	s_cbranch_execz .LBB0_720
	s_waitcnt lgkmcnt(0)
	v_add_f32_e32 v2, v2, v3
	ds_write_b32 v150, v2 offset:2816

; __device__ __forceinline__ unsigned cvtpk(float lo, float hi) { f32x2 v = {lo, hi}; bf16x2_t b = __builtin_convertvector(v, bf16x2_t); return __builtin_bit_cast(unsigned, b); }
;     __device__ __forceinline__ void operator()(AccRef acc, const Unit& u, int wr, int wc, int fr, int fq) const {
;     ...
;                 const float rs = rsqrtf(ssq_sum<4>(ssqx + (size_t)(row0 + ai * 128 + m * 16) * 4) * (1.0f / DM) + EPS);
; #pragma unroll
;                 for (int bj = 0; bj < 2; ++bj) { acc[ai][bj][m][0] = acc[ai][bj][m][0] * rs; acc[ai][bj][m][1] = acc[ai][bj][m][1] * rs; }
;             }
;             asm volatile("" ::: "memory");
;             const int chunk = u.pm * 4 + ai * 2 + wr;
; #pragma unroll
;             for (int e = 0; e < 2; ++e) {
;                 const int m = e ? 3 : 0;
;                 const bool mine = e ? (fr >= 14) : (fr <= 1);
;                 const int slot = e ? (fr - 12) : fr;
;                 if (mine) {
; #pragma unroll
;                     for (int bj = 0; bj < 2; ++bj) {
;                         const f32x4 v0 = acc[ai][bj][m][0], v1 = acc[ai][bj][m][1];
;                         u32x4 w; w.x = cvtpk(v0[0], v0[1]); w.y = cvtpk(v0[2], v0[3]); w.z = cvtpk(v1[0], v1[1]); w.w = cvtpk(v1[2], v1[3]);
;                         *(u32x4*)(UB + ((size_t)chunk * 4 + slot) * NUP + bj * DFF + gcol) = w;
;                     }
;                 }
;             }
.LBB0_795:
	v_lshl_add_u32 v146, s21, 8, v137
	v_ashrrev_i32_e32 v147, 31, v146
	v_and_b32_e32 v148, 0xff, v146
	v_lshlrev_b32_e32 v148, 4, v148
	v_add_u32_e32 v148, 0x21400, v148
	ds_read_b128 v[148:151], v148
	s_mov_b32 s12, 0x3a800000
	v_lshl_or_b32 v144, s20, 7, v242
	s_lshl_b32 s20, s21, 2
	s_add_i32 s52, s20, s54
	s_ashr_i32 s53, s52, 31
	v_ashrrev_i32_e32 v145, 31, v144
	s_lshl_b64 s[50:51], s[52:53], 2
	s_waitcnt lgkmcnt(0)
	v_mov_b32_e32 v152, v149
	v_mov_b32_e32 v153, v150
	v_mov_b32_e32 v149, v151
	v_pk_add_f32 v[154:155], v[152:153], v[148:149]
	v_or_b32_e32 v148, 16, v146
	v_ashrrev_i32_e32 v149, 31, v148
	v_and_b32_e32 v150, 0xff, v148
	v_lshlrev_b32_e32 v150, 4, v150
	v_add_u32_e32 v150, 0x21400, v150
	ds_read_b128 v[150:153], v150
	s_waitcnt lgkmcnt(0)
	v_mov_b32_e32 v156, v151
	v_mov_b32_e32 v157, v152
	v_mov_b32_e32 v151, v153
	v_pk_add_f32 v[150:151], v[156:157], v[150:151]
	v_mov_b32_e32 v153, v154
	v_mov_b32_e32 v152, v150
	v_mov_b32_e32 v154, v151
	v_pk_add_f32 v[150:151], v[152:153], v[154:155]
	v_or_b32_e32 v152, 48, v146
	v_pk_add_f32 v[150:151], v[150:151], 0 op_sel_hi:[1,0]
	v_ashrrev_i32_e32 v153, 31, v152
	v_pk_fma_f32 v[180:181], v[150:151], s[12:13], v[212:213] op_sel_hi:[1,0,0]
	s_nop 0
	v_mul_f32_e32 v147, 0x4b800000, v181
	v_cmp_gt_f32_e32 vcc, s69, v181
	v_cmp_gt_f32_e64 s[46:47], s69, v180
	s_nop 0
	v_cndmask_b32_e32 v147, v181, v147, vcc
	v_rsq_f32_e32 v147, v147
	s_nop 0
	v_mul_f32_e32 v149, 0x45800000, v147
	v_cndmask_b32_e32 v150, v147, v149, vcc
	v_pk_mul_f32 v[158:159], v[124:125], v[150:151] op_sel_hi:[1,0]
	v_pk_mul_f32 v[182:183], v[122:123], v[150:151] op_sel_hi:[1,0]
	v_pk_mul_f32 v[122:123], v[128:129], v[150:151] op_sel_hi:[1,0]
	v_pk_mul_f32 v[126:127], v[126:127], v[150:151] op_sel_hi:[1,0]
	v_pk_mul_f32 v[160:161], v[120:121], v[150:151] op_sel_hi:[1,0]
	v_pk_mul_f32 v[184:185], v[118:119], v[150:151] op_sel_hi:[1,0]
	v_pk_mul_f32 v[124:125], v[116:117], v[150:151] op_sel_hi:[1,0]
	v_pk_mul_f32 v[128:129], v[114:115], v[150:151] op_sel_hi:[1,0]
	v_or_b32_e32 v150, 32, v146
	v_ashrrev_i32_e32 v151, 31, v150
	v_and_b32_e32 v114, 0xff, v150
	v_lshlrev_b32_e32 v114, 4, v114
	v_add_u32_e32 v114, 0x21400, v114
	v_and_b32_e32 v118, 0xff, v152
	v_lshlrev_b32_e32 v118, 4, v118
	v_add_u32_e32 v118, 0x21400, v118
	ds_read_b128 v[114:117], v114
	s_nop 0
	ds_read_b128 v[118:121], v118
	s_and_saveexec_b64 s[20:21], s[42:43]
	s_cbranch_execz .LBB0_797
	v_or_b32_e32 v147, s50, v136
	v_mov_b64_e32 v[162:163], s[94:95]
	s_movk_i32 s12, 0x2c00
	v_mad_u64_u32 v[162:163], s[24:25], v147, s12, v[162:163]
	v_mad_i32_i24 v163, s51, v240, v163
	v_cvt_pk_bf16_f32 v154, v182, v183
	v_cvt_pk_bf16_f32 v155, v158, v159
	v_cvt_pk_bf16_f32 v156, v126, v127
	v_cvt_pk_bf16_f32 v157, v122, v123
	v_lshl_add_u64 v[162:163], v[144:145], 1, v[162:163]
	global_store_dwordx4 v[162:163], v[154:157], off sc0 sc1
	v_add_co_u32_e32 v162, vcc, 0x1000, v162
	s_nop 0
	v_cvt_pk_bf16_f32 v154, v184, v185
	v_cvt_pk_bf16_f32 v155, v160, v161
	v_cvt_pk_bf16_f32 v156, v128, v129
	v_cvt_pk_bf16_f32 v157, v124, v125
	v_addc_co_u32_e32 v163, vcc, 0, v163, vcc
	global_store_dwordx4 v[162:163], v[154:157], off offset:1536 sc0 sc1
.LBB0_797:
	s_or_b64 exec, exec, s[20:21]
	s_waitcnt lgkmcnt(0)
	v_mov_b32_e32 v154, v115
	v_mov_b32_e32 v155, v116
	v_mov_b32_e32 v115, v117
	v_mov_b32_e32 v116, v119
	v_mov_b32_e32 v117, v120
	v_mov_b32_e32 v119, v121
	v_pk_add_f32 v[114:115], v[154:155], v[114:115]
	v_pk_add_f32 v[116:117], v[116:117], v[118:119]
	v_mov_b32_e32 v119, v114
	v_mov_b32_e32 v118, v116
	v_mov_b32_e32 v114, v117
	v_pk_add_f32 v[114:115], v[118:119], v[114:115]
	s_mov_b32 s12, 0x3a800000
	v_pk_add_f32 v[114:115], v[114:115], 0 op_sel_hi:[1,0]
	s_nop 0
	v_pk_fma_f32 v[192:193], v[114:115], s[12:13], v[212:213] op_sel_hi:[1,0,0]
	s_nop 0
	v_mul_f32_e32 v114, 0x4b800000, v192
	v_cmp_gt_f32_e32 vcc, s69, v192
	v_cmp_gt_f32_e64 s[48:49], s69, v193
	s_nop 0
	v_cndmask_b32_e32 v114, v192, v114, vcc
	v_rsq_f32_e32 v114, v114
	s_nop 0
	v_mul_f32_e32 v115, 0x45800000, v114
	v_cndmask_b32_e32 v114, v114, v115, vcc
	v_pk_mul_f32 v[166:167], v[112:113], v[114:115] op_sel_hi:[1,0]
	v_pk_mul_f32 v[186:187], v[110:111], v[114:115] op_sel_hi:[1,0]
	v_pk_mul_f32 v[108:109], v[108:109], v[114:115] op_sel_hi:[1,0]
	v_pk_mul_f32 v[106:107], v[106:107], v[114:115] op_sel_hi:[1,0]
	v_pk_mul_f32 v[170:171], v[104:105], v[114:115] op_sel_hi:[1,0]
	v_pk_mul_f32 v[188:189], v[102:103], v[114:115] op_sel_hi:[1,0]
	v_pk_mul_f32 v[100:101], v[100:101], v[114:115] op_sel_hi:[1,0]
	v_pk_mul_f32 v[98:99], v[98:99], v[114:115] op_sel_hi:[1,0]
	s_and_saveexec_b64 s[20:21], s[40:41]
	s_cbranch_execz .LBB0_799
	v_lshl_add_u64 v[110:111], s[50:51], 0, v[138:139]
	v_mov_b64_e32 v[112:113], s[94:95]
	s_movk_i32 s12, 0x2c00
	v_mad_u64_u32 v[112:113], s[24:25], v110, s12, v[112:113]
	v_mad_i32_i24 v113, v111, s12, v113
	v_cvt_pk_bf16_f32 v102, v186, v187
	v_cvt_pk_bf16_f32 v103, v166, v167
	v_cvt_pk_bf16_f32 v104, v106, v107
	v_cvt_pk_bf16_f32 v105, v108, v109
	v_lshl_add_u64 v[110:111], v[144:145], 1, v[112:113]
	global_store_dwordx4 v[110:111], v[102:105], off sc0 sc1
	v_add_co_u32_e32 v110, vcc, 0x1000, v110
	s_nop 0
	v_cvt_pk_bf16_f32 v102, v188, v189
	v_cvt_pk_bf16_f32 v103, v170, v171
	v_cvt_pk_bf16_f32 v104, v98, v99
	v_cvt_pk_bf16_f32 v105, v100, v101
	v_addc_co_u32_e32 v111, vcc, 0, v111, vcc
	global_store_dwordx4 v[110:111], v[102:105], off offset:1536 sc0 sc1
; __device__ __forceinline__ unsigned cvtpk(float lo, float hi) { f32x2 v = {lo, hi}; bf16x2_t b = __builtin_convertvector(v, bf16x2_t); return __builtin_bit_cast(unsigned, b); }
;     __device__ __forceinline__ void operator()(AccRef acc, const Unit& u, int wr, int wc, int fr, int fq) const {
;     ...
;                 const float rs = rsqrtf(ssq_sum<4>(ssqx + (size_t)(row0 + ai * 128 + m * 16) * 4) * (1.0f / DM) + EPS);
; #pragma unroll
;                 for (int bj = 0; bj < 2; ++bj) { acc[ai][bj][m][0] = acc[ai][bj][m][0] * rs; acc[ai][bj][m][1] = acc[ai][bj][m][1] * rs; }
;             }
;             asm volatile("" ::: "memory");
;             const int chunk = u.pm * 4 + ai * 2 + wr;
; #pragma unroll
;             for (int e = 0; e < 2; ++e) {
;                 const int m = e ? 3 : 0;
;                 const bool mine = e ? (fr >= 14) : (fr <= 1);
;                 const int slot = e ? (fr - 12) : fr;
;                 if (mine) {
; #pragma unroll
;                     for (int bj = 0; bj < 2; ++bj) {
;                         const f32x4 v0 = acc[ai][bj][m][0], v1 = acc[ai][bj][m][1];
;                         u32x4 w; w.x = cvtpk(v0[0], v0[1]); w.y = cvtpk(v0[2], v0[3]); w.z = cvtpk(v1[0], v1[1]); w.w = cvtpk(v1[2], v1[3]);
;                         *(u32x4*)(UB + ((size_t)chunk * 4 + slot) * NUP + bj * DFF + gcol) = w;
;                     }
;                 }
;             }
.LBB0_799:
	s_or_b64 exec, exec, s[20:21]
	s_nop 0
	v_add_u32_e32 v102, 0x80, v146
	v_ashrrev_i32_e32 v103, 31, v102
	v_and_b32_e32 v104, 0xff, v102
	v_lshlrev_b32_e32 v104, 4, v104
	v_add_u32_e32 v104, 0x21400, v104
	ds_read_b128 v[110:113], v104
	s_mov_b32 s12, 0x3a800000
	s_add_i32 s52, s52, 2
	s_ashr_i32 s53, s52, 31
	s_lshl_b64 s[20:21], s[52:53], 2
	s_waitcnt lgkmcnt(0)
	v_mov_b32_e32 v104, v111
	v_mov_b32_e32 v105, v112
	v_mov_b32_e32 v111, v113
	v_pk_add_f32 v[114:115], v[104:105], v[110:111]
	v_add_u32_e32 v104, 0x90, v146
	v_ashrrev_i32_e32 v105, 31, v104
	v_and_b32_e32 v110, 0xff, v104
	v_lshlrev_b32_e32 v110, 4, v110
	v_add_u32_e32 v110, 0x21400, v110
	ds_read_b128 v[110:113], v110
	s_waitcnt lgkmcnt(0)
	v_mov_b32_e32 v116, v111
	v_mov_b32_e32 v117, v112
	v_mov_b32_e32 v111, v113
	v_pk_add_f32 v[110:111], v[116:117], v[110:111]
	v_mov_b32_e32 v113, v114
	v_mov_b32_e32 v112, v110
	v_mov_b32_e32 v114, v111
	v_pk_add_f32 v[110:111], v[112:113], v[114:115]
	v_add_u32_e32 v112, 0xb0, v146
	v_pk_add_f32 v[110:111], v[110:111], 0 op_sel_hi:[1,0]
	v_ashrrev_i32_e32 v113, 31, v112
	v_pk_fma_f32 v[118:119], v[110:111], s[12:13], v[212:213] op_sel_hi:[1,0,0]
	s_nop 0
	v_mul_f32_e32 v103, 0x4b800000, v119
	v_cmp_gt_f32_e32 vcc, s69, v119
	v_cmp_gt_f32_e64 s[50:51], s69, v118
	s_nop 0
	v_cndmask_b32_e32 v103, v119, v103, vcc
	v_rsq_f32_e32 v103, v103
	s_nop 0
	v_mul_f32_e32 v105, 0x45800000, v103
	v_cndmask_b32_e32 v110, v103, v105, vcc
	v_pk_mul_f32 v[114:115], v[96:97], v[110:111] op_sel_hi:[1,0]
	v_pk_mul_f32 v[162:163], v[94:95], v[110:111] op_sel_hi:[1,0]
	v_pk_mul_f32 v[92:93], v[92:93], v[110:111] op_sel_hi:[1,0]
	v_pk_mul_f32 v[94:95], v[90:91], v[110:111] op_sel_hi:[1,0]
	v_pk_mul_f32 v[116:117], v[88:89], v[110:111] op_sel_hi:[1,0]
	v_pk_mul_f32 v[164:165], v[86:87], v[110:111] op_sel_hi:[1,0]
	v_pk_mul_f32 v[90:91], v[84:85], v[110:111] op_sel_hi:[1,0]
	v_pk_mul_f32 v[96:97], v[82:83], v[110:111] op_sel_hi:[1,0]
	v_add_u32_e32 v110, 0xa0, v146
	v_ashrrev_i32_e32 v111, 31, v110
	v_and_b32_e32 v82, 0xff, v110
	v_lshlrev_b32_e32 v82, 4, v82
	v_add_u32_e32 v82, 0x21400, v82
	v_and_b32_e32 v86, 0xff, v112
	v_lshlrev_b32_e32 v86, 4, v86
	v_add_u32_e32 v86, 0x21400, v86
	ds_read_b128 v[82:85], v82
	s_nop 0
	ds_read_b128 v[86:89], v86
	s_and_saveexec_b64 s[52:53], s[42:43]
	s_cbranch_execz .LBB0_801
	v_or_b32_e32 v103, s20, v136
	v_mov_b64_e32 v[120:121], s[94:95]
	s_movk_i32 s12, 0x2c00
	v_mad_u64_u32 v[120:121], s[24:25], v103, s12, v[120:121]
	v_mad_i32_i24 v121, s21, v240, v121
	v_cvt_pk_bf16_f32 v154, v162, v163
	v_cvt_pk_bf16_f32 v155, v114, v115
	v_cvt_pk_bf16_f32 v156, v94, v95
	v_cvt_pk_bf16_f32 v157, v92, v93
	v_lshl_add_u64 v[120:121], v[144:145], 1, v[120:121]
	global_store_dwordx4 v[120:121], v[154:157], off sc0 sc1
	v_add_co_u32_e32 v120, vcc, 0x1000, v120
	s_nop 0
	v_cvt_pk_bf16_f32 v154, v164, v165
	v_cvt_pk_bf16_f32 v155, v116, v117
	v_cvt_pk_bf16_f32 v156, v96, v97
	v_cvt_pk_bf16_f32 v157, v90, v91
	v_addc_co_u32_e32 v121, vcc, 0, v121, vcc
	global_store_dwordx4 v[120:121], v[154:157], off offset:1536 sc0 sc1
.LBB0_801:
	s_or_b64 exec, exec, s[52:53]
	s_waitcnt lgkmcnt(0)
	v_mov_b32_e32 v120, v83
	v_mov_b32_e32 v121, v84
	v_mov_b32_e32 v83, v85
	v_mov_b32_e32 v84, v87
	v_mov_b32_e32 v85, v88
	v_mov_b32_e32 v87, v89
	v_pk_add_f32 v[82:83], v[120:121], v[82:83]
	v_pk_add_f32 v[84:85], v[84:85], v[86:87]
	v_mov_b32_e32 v87, v82
	v_mov_b32_e32 v86, v84
	v_mov_b32_e32 v82, v85
	v_pk_add_f32 v[82:83], v[86:87], v[82:83]
	s_mov_b32 s12, 0x3a800000
	v_pk_add_f32 v[82:83], v[82:83], 0 op_sel_hi:[1,0]
	s_nop 0
	v_pk_fma_f32 v[84:85], v[82:83], s[12:13], v[212:213] op_sel_hi:[1,0,0]
	s_nop 0
	v_mul_f32_e32 v82, 0x4b800000, v84
	v_cmp_gt_f32_e32 vcc, s69, v84
	v_cmp_gt_f32_e64 s[52:53], s69, v85
	s_nop 0
	v_cndmask_b32_e32 v82, v84, v82, vcc
	v_rsq_f32_e32 v82, v82
	s_nop 0
	v_mul_f32_e32 v83, 0x45800000, v82
	v_cndmask_b32_e32 v84, v82, v83, vcc
	v_pk_mul_f32 v[80:81], v[80:81], v[84:85] op_sel_hi:[1,0]
	v_pk_mul_f32 v[168:169], v[78:79], v[84:85] op_sel_hi:[1,0]
	v_pk_mul_f32 v[76:77], v[76:77], v[84:85] op_sel_hi:[1,0]
	v_pk_mul_f32 v[74:75], v[74:75], v[84:85] op_sel_hi:[1,0]
	v_pk_mul_f32 v[82:83], v[72:73], v[84:85] op_sel_hi:[1,0]
	v_pk_mul_f32 v[172:173], v[70:71], v[84:85] op_sel_hi:[1,0]
	v_pk_mul_f32 v[68:69], v[68:69], v[84:85] op_sel_hi:[1,0]
	v_pk_mul_f32 v[66:67], v[66:67], v[84:85] op_sel_hi:[1,0]
	s_and_saveexec_b64 s[24:25], s[40:41]
	s_cbranch_execz .LBB0_803
	v_lshl_add_u64 v[78:79], s[20:21], 0, v[138:139]
	v_mov_b64_e32 v[86:87], s[94:95]
	s_movk_i32 s12, 0x2c00
	v_mad_u64_u32 v[86:87], s[20:21], v78, s12, v[86:87]
	v_mad_i32_i24 v87, v79, s12, v87
	v_cvt_pk_bf16_f32 v70, v168, v169
	v_cvt_pk_bf16_f32 v71, v80, v81
	v_cvt_pk_bf16_f32 v72, v74, v75
	v_cvt_pk_bf16_f32 v73, v76, v77
	v_lshl_add_u64 v[78:79], v[144:145], 1, v[86:87]
	global_store_dwordx4 v[78:79], v[70:73], off sc0 sc1
	v_add_co_u32_e32 v78, vcc, 0x1000, v78
	s_nop 0
	v_cvt_pk_bf16_f32 v70, v172, v173
	v_cvt_pk_bf16_f32 v71, v82, v83
	v_cvt_pk_bf16_f32 v72, v66, v67
	v_cvt_pk_bf16_f32 v73, v68, v69
	v_addc_co_u32_e32 v79, vcc, 0, v79, vcc
	global_store_dwordx4 v[78:79], v[70:73], off offset:1536 sc0 sc1

; __device__ __forceinline__ float bf2f(unsigned short b) { return __uint_as_float((unsigned)b << 16); }
; __device__ __forceinline__ void ffn_fixup(const Params& P, int layer) {
;     ...
;     for (int it = blockIdx.x * 512 + threadIdx.x; it < 512 * 2 * CG; it += gridDim.x * 512) {
;         const int cgi = it % CG, e = (it / CG) & 1, chunk = it / (2 * CG), col = cgi * 8;
;         const bf16_t *up, *mid, *dn; bool zu = false, zd = false;
;         if (e == 0) { zu = (chunk % 32) == 0; up = UB + ((size_t)(zu ? chunk : chunk - 1) * 4 + 3) * NUP; mid = UB + ((size_t)chunk * 4 + 0) * NUP; dn = UB + ((size_t)chunk * 4 + 1) * NUP; }
;         else { zd = (chunk % 32) == 31; up = UB + ((size_t)chunk * 4 + 2) * NUP; mid = UB + ((size_t)chunk * 4 + 3) * NUP; dn = UB + ((size_t)(zd ? chunk : chunk + 1) * 4 + 0) * NUP; }
;         const float fu = zu ? 0.f : 1.f, fd = zd ? 0.f : 1.f;
;         float res[8];
;         bf16_t ug[8], mg[8], dg[8], uv[8], mv[8], dv[8];
;         *(u32x4*)ug = *(const u32x4*)(up + col); *(u32x4*)mg = *(const u32x4*)(mid + col); *(u32x4*)dg = *(const u32x4*)(dn + col);
;         *(u32x4*)uv = *(const u32x4*)(up + DFF + col); *(u32x4*)mv = *(const u32x4*)(mid + DFF + col); *(u32x4*)dv = *(const u32x4*)(dn + DFF + col);
; #pragma unroll
;         for (int k = 0; k < 8; ++k) {
;             const int cg_ = col + k, cv_ = DFF + col + k;
;             const float gt = cw[cg_] * bf2f(ug[k]) * fu + cw[NUP + cg_] * bf2f(mg[k]) + cw[2 * NUP + cg_] * bf2f(dg[k]) * fd + cb[cg_];
;             const float vl = cw[cv_] * bf2f(uv[k]) * fu + cw[NUP + cv_] * bf2f(mv[k]) + cw[2 * NUP + cv_] * bf2f(dv[k]) * fd + cb[cv_];
.LBB0_861:
	s_or_b64 exec, exec, s[14:15]
	v_mul_i32_i24_e32 v0, 0x160, v0
	v_lshlrev_b32_e32 v0, 3, v0
	v_sub_u32_e32 v62, v59, v0
	v_ashrrev_i32_e32 v63, 31, v62
	v_lshlrev_b64 v[56:57], 1, v[62:63]
	v_lshl_add_u64 v[2:3], v[2:3], 0, v[56:57]
	s_movk_i32 s4, 0x1000
	global_load_dwordx4 v[22:25], v[2:3], off
	v_add_co_u32_e32 v2, vcc, s4, v2
	v_lshl_add_u64 v[4:5], v[4:5], 0, v[56:57]
	s_nop 0
	v_addc_co_u32_e32 v3, vcc, 0, v3, vcc
	global_load_dwordx4 v[10:13], v[2:3], off offset:1536
	v_add_co_u32_e32 v2, vcc, s4, v4
	v_lshl_add_u64 v[26:27], v[6:7], 0, v[56:57]
	s_nop 0
	v_addc_co_u32_e32 v3, vcc, 0, v5, vcc
	global_load_dwordx4 v[18:21], v[4:5], off
	global_load_dwordx4 v[6:9], v[2:3], off offset:1536
	v_add_co_u32_e32 v2, vcc, s4, v26
	global_load_dwordx4 v[14:17], v[26:27], off
	s_nop 0
	v_addc_co_u32_e32 v3, vcc, 0, v27, vcc
	global_load_dwordx4 v[2:5], v[2:3], off offset:1536
	v_add_u32_e32 v0, 0xb00, v62
	v_lshlrev_b64 v[26:27], 2, v[62:63]
	v_lshl_add_u64 v[34:35], s[62:63], 0, v[26:27]
	v_lshl_add_u64 v[42:43], s[76:77], 0, v[26:27]
	v_lshlrev_b64 v[26:27], 2, v[0:1]
	v_lshl_add_u64 v[44:45], s[62:63], 0, v[26:27]
	v_lshl_add_u64 v[64:65], s[76:77], 0, v[26:27]
	global_load_dwordx4 v[26:29], v[34:35], off offset:16
	global_load_dwordx4 v[48:51], v[34:35], off
	s_mov_b64 s[4:5], 0x5800
	v_lshl_add_u64 v[30:31], v[34:35], 0, s[4:5]
	s_mov_b64 s[4:5], 0xb000
	v_lshl_add_u64 v[36:37], v[34:35], 0, s[4:5]
	s_movk_i32 s4, 0x5000
	s_mov_b32 s5, 0xb000
	s_waitcnt vmcnt(7)
	v_and_b32_e32 v33, 0xffff0000, v22
	v_lshlrev_b32_e32 v32, 16, v22
	s_waitcnt vmcnt(5)
	v_and_b32_e32 v41, 0xffff0000, v18
	v_lshlrev_b32_e32 v40, 16, v18
	s_waitcnt vmcnt(0)
	v_pk_mul_f32 v[38:39], v[48:49], v[32:33]
	v_add_co_u32_e32 v32, vcc, s4, v34
	s_nop 1
	v_addc_co_u32_e32 v33, vcc, 0, v35, vcc
	global_load_dwordx4 v[52:55], v[32:33], off offset:2048
	s_nop 0
	global_load_dwordx4 v[30:33], v[30:31], off offset:16
	v_add_co_u32_e32 v34, vcc, s5, v34
	s_waitcnt vmcnt(1)
	v_pk_mul_f32 v[40:41], v[52:53], v[40:41]
	v_addc_co_u32_e32 v35, vcc, 0, v35, vcc
	global_load_dwordx4 v[68:71], v[34:35], off
	s_nop 0
	global_load_dwordx4 v[34:37], v[36:37], off offset:16
	v_pk_fma_f32 v[38:39], v[60:61], v[38:39], v[40:41] op_sel_hi:[0,1,1]
	v_and_b32_e32 v41, 0xffff0000, v14
	v_lshlrev_b32_e32 v40, 16, v14
	s_waitcnt vmcnt(1)
	v_pk_mul_f32 v[40:41], v[68:69], v[40:41]
	s_nop 0
	v_pk_fma_f32 v[46:47], v[58:59], v[40:41], v[38:39] op_sel_hi:[0,1,1]
	global_load_dwordx4 v[38:41], v[42:43], off offset:16
	global_load_dwordx4 v[72:75], v[42:43], off
	v_and_b32_e32 v43, 0xffff0000, v10
	v_lshlrev_b32_e32 v42, 16, v10
	s_waitcnt vmcnt(0)
	v_pk_add_f32 v[52:53], v[72:73], v[46:47]
	v_add_co_u32_e32 v72, vcc, s4, v44
	global_load_dwordx4 v[46:49], v[44:45], off offset:16
	global_load_dwordx4 v[76:79], v[44:45], off
	v_addc_co_u32_e32 v73, vcc, 0, v45, vcc
	global_load_dwordx2 v[72:73], v[72:73], off offset:2048
	v_add_co_u32_e32 v44, vcc, s5, v44
	v_mul_f32_e32 v0, 0xbfb8aa3b, v52
	s_nop 0
	v_addc_co_u32_e32 v45, vcc, 0, v45, vcc
	global_load_dwordx2 v[44:45], v[44:45], off
	v_exp_f32_e32 v0, v0
	s_waitcnt vmcnt(2)
	v_pk_mul_f32 v[42:43], v[76:77], v[42:43]
	v_and_b32_e32 v77, 0xffff0000, v6
	v_lshlrev_b32_e32 v76, 16, v6
	s_waitcnt vmcnt(1)
	v_pk_mul_f32 v[72:73], v[72:73], v[76:77]
	v_add_f32_e32 v0, 1.0, v0
	v_pk_fma_f32 v[42:43], v[60:61], v[42:43], v[72:73] op_sel_hi:[0,1,1]
	v_and_b32_e32 v73, 0xffff0000, v2
	v_lshlrev_b32_e32 v72, 16, v2
	v_rcp_f32_e32 v68, v0
	s_waitcnt vmcnt(0)
	v_pk_mul_f32 v[44:45], v[44:45], v[72:73]
	v_mul_f32_e32 v0, 0xbfb8aa3b, v53
	v_pk_fma_f32 v[72:73], v[58:59], v[44:45], v[42:43] op_sel_hi:[0,1,1]
	global_load_dwordx4 v[42:45], v[64:65], off offset:16
	global_load_dwordx4 v[80:83], v[64:65], off
	v_exp_f32_e32 v0, v0
	s_waitcnt vmcnt(0)
	v_pk_add_f32 v[64:65], v[80:81], v[72:73]
	v_add_f32_e32 v0, 1.0, v0
	v_rcp_f32_e32 v69, v0
	v_add_u32_e32 v0, 0xb02, v62
	v_pk_mul_f32 v[52:53], v[52:53], v[68:69]
	v_and_b32_e32 v69, 0xffff0000, v23
	v_lshlrev_b32_e32 v68, 16, v23
	v_pk_mul_f32 v[22:23], v[50:51], v[68:69]
	v_and_b32_e32 v51, 0xffff0000, v19
	v_lshlrev_b32_e32 v50, 16, v19
	v_pk_mul_f32 v[18:19], v[54:55], v[50:51]
	v_pk_mul_f32 v[52:53], v[64:65], v[52:53]
	v_pk_fma_f32 v[18:19], v[60:61], v[22:23], v[18:19] op_sel_hi:[0,1,1]
	v_and_b32_e32 v23, 0xffff0000, v15
	v_lshlrev_b32_e32 v22, 16, v15
	v_pk_mul_f32 v[14:15], v[70:71], v[22:23]
	v_lshl_add_u64 v[64:65], v[0:1], 2, s[62:63]
	v_pk_fma_f32 v[14:15], v[58:59], v[14:15], v[18:19] op_sel_hi:[0,1,1]
	v_and_b32_e32 v19, 0xffff0000, v11
	v_lshlrev_b32_e32 v18, 16, v11
	v_pk_mul_f32 v[10:11], v[78:79], v[18:19]
	v_add_co_u32_e32 v18, vcc, s4, v64
	v_and_b32_e32 v23, 0xffff0000, v7
	s_nop 0
	v_addc_co_u32_e32 v19, vcc, 0, v65, vcc
	global_load_dwordx2 v[18:19], v[18:19], off offset:2048
	v_lshlrev_b32_e32 v22, 16, v7
	v_pk_add_f32 v[14:15], v[74:75], v[14:15]
	s_waitcnt vmcnt(0)
; __device__ __forceinline__ unsigned cvtpk(float lo, float hi) { f32x2 v = {lo, hi}; bf16x2_t b = __builtin_convertvector(v, bf16x2_t); return __builtin_bit_cast(unsigned, b); }
; __device__ __forceinline__ float bf2f(unsigned short b) { return __uint_as_float((unsigned)b << 16); }
; __device__ __forceinline__ float fast_exp2(float x) { return __builtin_amdgcn_exp2f(x); }
; __device__ __forceinline__ float fast_rcp(float x) { return __builtin_amdgcn_rcpf(x); }
; __device__ __forceinline__ void ffn_fixup(const Params& P, int layer) {
;     ...
;         for (int k = 0; k < 8; ++k) {
;             const int cg_ = col + k, cv_ = DFF + col + k;
;             const float gt = cw[cg_] * bf2f(ug[k]) * fu + cw[NUP + cg_] * bf2f(mg[k]) + cw[2 * NUP + cg_] * bf2f(dg[k]) * fd + cb[cg_];
;             const float vl = cw[cv_] * bf2f(uv[k]) * fu + cw[NUP + cv_] * bf2f(mv[k]) + cw[2 * NUP + cv_] * bf2f(dv[k]) * fd + cb[cv_];
;             res[k] = gt * fast_rcp(1.f + fast_exp2(-LOG2E * gt)) * vl;
;         }
;         u32x4 w; w.x = cvtpk(res[0], res[1]); w.y = cvtpk(res[2], res[3]); w.z = cvtpk(res[4], res[5]); w.w = cvtpk(res[6], res[7]);
;         *(u32x4*)(ACT + (size_t)(chunk * 64 + (e ? 63 : 0)) * DFF + col) = w;
	v_pk_mul_f32 v[6:7], v[18:19], v[22:23]
	s_nop 0
	v_pk_fma_f32 v[6:7], v[60:61], v[10:11], v[6:7] op_sel_hi:[0,1,1]
	v_add_co_u32_e32 v10, vcc, s5, v64
	v_mul_f32_e32 v0, 0xbfb8aa3b, v14
	s_nop 0
	v_addc_co_u32_e32 v11, vcc, 0, v65, vcc
	global_load_dwordx2 v[10:11], v[10:11], off
	v_exp_f32_e32 v0, v0
	v_and_b32_e32 v19, 0xffff0000, v3
	v_lshlrev_b32_e32 v18, 16, v3
	v_add_f32_e32 v0, 1.0, v0
	v_rcp_f32_e32 v2, v0
	v_mul_f32_e32 v0, 0xbfb8aa3b, v15
	v_exp_f32_e32 v0, v0
	s_waitcnt vmcnt(0)
	v_pk_mul_f32 v[10:11], v[10:11], v[18:19]
	v_add_f32_e32 v0, 1.0, v0
	v_rcp_f32_e32 v3, v0
	v_pk_fma_f32 v[6:7], v[58:59], v[10:11], v[6:7] op_sel_hi:[0,1,1]
	v_pk_add_f32 v[6:7], v[82:83], v[6:7]
	v_add_u32_e32 v0, 0xb04, v62
	v_pk_mul_f32 v[2:3], v[14:15], v[2:3]
	v_and_b32_e32 v11, 0xffff0000, v24
	v_pk_mul_f32 v[2:3], v[6:7], v[2:3]
	v_lshl_add_u64 v[6:7], v[0:1], 2, s[62:63]
	v_add_co_u32_e32 v22, vcc, s4, v6
	v_lshlrev_b32_e32 v10, 16, v24
	s_nop 0
	v_addc_co_u32_e32 v23, vcc, 0, v7, vcc
	global_load_dwordx2 v[22:23], v[22:23], off offset:2048
	v_add_co_u32_e32 v6, vcc, s5, v6
	v_and_b32_e32 v15, 0xffff0000, v20
	s_nop 0
	v_addc_co_u32_e32 v7, vcc, 0, v7, vcc
	global_load_dwordx2 v[6:7], v[6:7], off
	v_lshlrev_b32_e32 v14, 16, v20
	v_pk_mul_f32 v[10:11], v[26:27], v[10:11]
	v_pk_mul_f32 v[14:15], v[30:31], v[14:15]
	v_and_b32_e32 v19, 0xffff0000, v12
	v_pk_fma_f32 v[10:11], v[60:61], v[10:11], v[14:15] op_sel_hi:[0,1,1]
	v_and_b32_e32 v15, 0xffff0000, v16
	v_lshlrev_b32_e32 v14, 16, v16
	v_pk_mul_f32 v[14:15], v[34:35], v[14:15]
	v_lshlrev_b32_e32 v18, 16, v12
	v_pk_fma_f32 v[10:11], v[58:59], v[14:15], v[10:11] op_sel_hi:[0,1,1]
	v_pk_add_f32 v[10:11], v[38:39], v[10:11]
	v_and_b32_e32 v27, 0xffff0000, v8
	v_mul_f32_e32 v0, 0xbfb8aa3b, v10
	v_exp_f32_e32 v0, v0
	v_lshlrev_b32_e32 v26, 16, v8
	v_pk_mul_f32 v[18:19], v[46:47], v[18:19]
	v_add_f32_e32 v0, 1.0, v0
	v_rcp_f32_e32 v14, v0
	v_mul_f32_e32 v0, 0xbfb8aa3b, v11
	v_exp_f32_e32 v0, v0
	s_waitcnt vmcnt(1)
	v_pk_mul_f32 v[22:23], v[22:23], v[26:27]
	v_add_f32_e32 v0, 1.0, v0
	v_rcp_f32_e32 v15, v0
	v_pk_fma_f32 v[18:19], v[60:61], v[18:19], v[22:23] op_sel_hi:[0,1,1]
	v_and_b32_e32 v23, 0xffff0000, v4
	v_lshlrev_b32_e32 v22, 16, v4
	s_waitcnt vmcnt(0)
	v_pk_mul_f32 v[6:7], v[6:7], v[22:23]
	v_pk_mul_f32 v[10:11], v[10:11], v[14:15]
	v_pk_fma_f32 v[6:7], v[58:59], v[6:7], v[18:19] op_sel_hi:[0,1,1]
	v_pk_add_f32 v[6:7], v[42:43], v[6:7]
	v_and_b32_e32 v19, 0xffff0000, v21
	v_pk_mul_f32 v[6:7], v[6:7], v[10:11]
	v_and_b32_e32 v11, 0xffff0000, v25
	v_lshlrev_b32_e32 v10, 16, v25
	v_lshlrev_b32_e32 v18, 16, v21
	v_pk_mul_f32 v[10:11], v[28:29], v[10:11]
	v_pk_mul_f32 v[18:19], v[32:33], v[18:19]
	v_add_u32_e32 v0, 0xb06, v62
	v_pk_fma_f32 v[10:11], v[60:61], v[10:11], v[18:19] op_sel_hi:[0,1,1]
	v_and_b32_e32 v19, 0xffff0000, v17
	v_lshlrev_b32_e32 v18, 16, v17
	v_pk_mul_f32 v[16:17], v[36:37], v[18:19]
	v_lshl_add_u64 v[14:15], v[0:1], 2, s[62:63]
	v_pk_fma_f32 v[10:11], v[58:59], v[16:17], v[10:11] op_sel_hi:[0,1,1]
	v_and_b32_e32 v17, 0xffff0000, v13
	v_lshlrev_b32_e32 v16, 16, v13
	v_pk_mul_f32 v[12:13], v[48:49], v[16:17]
	v_add_co_u32_e32 v16, vcc, s4, v14
	v_and_b32_e32 v19, 0xffff0000, v9
	s_nop 0
	v_addc_co_u32_e32 v17, vcc, 0, v15, vcc
	global_load_dwordx2 v[16:17], v[16:17], off offset:2048
	v_lshlrev_b32_e32 v18, 16, v9
	v_pk_add_f32 v[10:11], v[40:41], v[10:11]
	s_movk_i32 s4, 0x1600
	v_mul_f32_e32 v0, 0xbfb8aa3b, v10
	v_exp_f32_e32 v0, v0
	v_cvt_pk_bf16_f32 v6, v6, v7
	v_add_f32_e32 v0, 1.0, v0
	v_rcp_f32_e32 v4, v0
	v_mul_f32_e32 v0, 0xbfb8aa3b, v11
	v_exp_f32_e32 v0, v0
	s_waitcnt vmcnt(0)
	v_pk_mul_f32 v[8:9], v[16:17], v[18:19]
	s_nop 0
	v_pk_fma_f32 v[8:9], v[60:61], v[12:13], v[8:9] op_sel_hi:[0,1,1]
	v_add_co_u32_e32 v12, vcc, s5, v14
	v_add_f32_e32 v0, 1.0, v0
	s_nop 0
	v_addc_co_u32_e32 v13, vcc, 0, v15, vcc
	global_load_dwordx2 v[12:13], v[12:13], off
	v_and_b32_e32 v15, 0xffff0000, v5
	v_lshlrev_b32_e32 v14, 16, v5
	v_rcp_f32_e32 v5, v0
	v_lshl_or_b32 v0, v66, 6, v67
	v_pk_mul_f32 v[4:5], v[10:11], v[4:5]
	s_waitcnt vmcnt(0)
	v_pk_mul_f32 v[12:13], v[12:13], v[14:15]
	s_nop 0
	v_pk_fma_f32 v[8:9], v[58:59], v[12:13], v[8:9] op_sel_hi:[0,1,1]
	v_pk_add_f32 v[8:9], v[44:45], v[8:9]
	s_nop 0
	v_pk_mul_f32 v[8:9], v[8:9], v[4:5]
	v_cvt_pk_bf16_f32 v5, v2, v3
	v_mov_b64_e32 v[2:3], s[90:91]
	v_mad_i64_i32 v[2:3], s[4:5], v0, s4, v[2:3]
	v_readlane_b32 s4, v252, 7
	v_cvt_pk_bf16_f32 v4, v52, v53
	v_cvt_pk_bf16_f32 v7, v8, v9
	v_add_u32_e32 v61, s4, v61
	v_readlane_b32 s4, v252, 22
	v_lshl_add_u64 v[2:3], v[2:3], 0, v[56:57]
	global_store_dwordx4 v[2:3], v[4:7], off sc0 sc1
	v_add_u32_e32 v59, s4, v59
	s_mov_b32 s4, 0x57fff
	v_cmp_lt_i32_e32 vcc, s4, v61
	s_or_b64 s[10:11], vcc, s[10:11]
	s_andn2_b64 exec, exec, s[10:11]
	s_cbranch_execz .LBB0_866

; __device__ __forceinline__ unsigned cvtpk(float lo, float hi) { f32x2 v = {lo, hi}; bf16x2_t b = __builtin_convertvector(v, bf16x2_t); return __builtin_bit_cast(unsigned, b); }
;     __device__ __forceinline__ void operator()(AccRef acc, const Unit& u, int wr, int wc, int fr, int fq) const {
;     ...
; #pragma unroll
;         for (int ai = 0; ai < 2; ++ai)
; #pragma unroll
;             for (int m = 0; m < 4; ++m) {
;                 const int row = row0 + ai * 128 + m * 16; bf16_t* rowp = XB + (size_t)row * DM + col0; float s = 0.f;
; #pragma unroll
;                 for (int bj = 0; bj < 2; ++bj) {
;                     const u32x4 xo = *(const u32x4*)(rowp + bj * 128);
;                     float v[8];
; #pragma unroll
;                     for (int k = 0; k < 4; ++k) { v[2 * k] = __uint_as_float(xo[k] << 16) + acc[ai][bj][m][k >> 1][(2 * k) & 3]; v[2 * k + 1] = __uint_as_float(xo[k] & 0xffff0000u) + acc[ai][bj][m][k >> 1][(2 * k + 1) & 3]; }
; #pragma unroll
;                     for (int k = 0; k < 8; ++k) s += v[k] * v[k];
;                     u32x4 w; w.x = cvtpk(v[0], v[1]); w.y = cvtpk(v[2], v[3]); w.z = cvtpk(v[4], v[5]); w.w = cvtpk(v[6], v[7]);
;                     st16_wt(rowp + bj * 128, w);
;                 }
;                 s += __shfl_xor(s, 16); s += __shfl_xor(s, 32);
;                 if (fq == 0) red[(ai * 128 + wr * 64 + m * 16 + fr) * 4 + wc] = s;
;                 asm volatile("" ::: "memory");
;             }
.LBB0_939:
	v_and_b32_e32 v144, 64, v213
	v_xor_b32_e32 v143, 16, v213
	v_add_u32_e32 v144, 64, v144
	v_cmp_lt_i32_e32 vcc, v143, v144
	s_lshl_b32 s51, s51, 8
	v_add_u32_e32 v142, s51, v146
	v_cndmask_b32_e32 v143, v213, v143, vcc
	v_lshlrev_b32_e32 v154, 2, v143
	v_xor_b32_e32 v143, 32, v213
	v_cmp_lt_i32_e32 vcc, v143, v144
	v_lshl_or_b32 v140, s50, 8, v148
	v_ashrrev_i32_e32 v141, 31, v140
	v_cndmask_b32_e32 v143, v213, v143, vcc
	v_lshlrev_b32_e32 v153, 2, v143
	v_ashrrev_i32_e32 v143, 31, v142
	v_lshlrev_b64 v[144:145], 11, v[142:143]
	v_lshl_add_u64 v[144:145], s[66:67], 0, v[144:145]
	v_lshl_add_u64 v[144:145], v[140:141], 1, v[144:145]
	v_mov_b64_e32 v[226:227], v[144:145]
	global_load_dwordx4 v[168:171], v[226:227], off
	global_load_dwordx4 v[172:175], v[226:227], off offset:256
	s_mov_b64 s[20:21], 0x8000
	s_nop 0
	v_lshl_add_u64 v[224:225], v[226:227], 0, s[20:21]
	global_load_dwordx4 v[176:179], v[224:225], off
	global_load_dwordx4 v[180:183], v[224:225], off offset:256
	s_mov_b64 s[20:21], 0x10000
	s_nop 0
	v_lshl_add_u64 v[224:225], v[226:227], 0, s[20:21]
	global_load_dwordx4 v[184:187], v[224:225], off
	global_load_dwordx4 v[188:191], v[224:225], off offset:256
	s_mov_b64 s[20:21], 0x18000
	s_nop 0
	v_lshl_add_u64 v[224:225], v[226:227], 0, s[20:21]
	global_load_dwordx4 v[192:195], v[224:225], off
	global_load_dwordx4 v[196:199], v[224:225], off offset:256
	s_mov_b64 s[20:21], 0x40000
	s_nop 0
	v_lshl_add_u64 v[224:225], v[226:227], 0, s[20:21]
	global_load_dwordx4 v[200:203], v[224:225], off
	global_load_dwordx4 v[204:207], v[224:225], off offset:256
	s_waitcnt vmcnt(9)
	v_lshlrev_b32_e32 v160, 16, v168
	v_and_b32_e32 v161, 0xffff0000, v168
	v_pk_add_f32 v[160:161], v[126:127], v[160:161]
	v_lshlrev_b32_e32 v126, 16, v169
	v_and_b32_e32 v127, 0xffff0000, v169
	v_pk_add_f32 v[162:163], v[128:129], v[126:127]
	v_lshlrev_b32_e32 v126, 16, v170
	v_and_b32_e32 v127, 0xffff0000, v170
	v_pk_add_f32 v[164:165], v[122:123], v[126:127]
	v_lshlrev_b32_e32 v122, 16, v171
	v_and_b32_e32 v123, 0xffff0000, v171
	v_pk_add_f32 v[166:167], v[124:125], v[122:123]
	v_cvt_pk_bf16_f32 v156, v160, v161
	v_cvt_pk_bf16_f32 v157, v162, v163
	v_cvt_pk_bf16_f32 v158, v164, v165
	v_cvt_pk_bf16_f32 v159, v166, v167
	global_store_dwordx4 v[144:145], v[156:159], off sc0 sc1
	v_pk_mul_f32 v[128:129], v[160:161], v[160:161]
	v_pk_mul_f32 v[126:127], v[162:163], v[162:163]
	v_add_f32_e32 v128, v128, v129
	v_add_f32_e32 v126, v126, v128
	v_pk_mul_f32 v[124:125], v[164:165], v[164:165]
	v_add_f32_e32 v126, v127, v126
	v_add_f32_e32 v124, v124, v126
	v_pk_mul_f32 v[122:123], v[166:167], v[166:167]
	v_add_f32_e32 v124, v125, v124
	v_add_f32_e32 v122, v122, v124
	v_add_f32_e32 v122, v123, v122
	s_waitcnt vmcnt(9)
	v_lshlrev_b32_e32 v160, 16, v172
	v_and_b32_e32 v161, 0xffff0000, v172
	v_lshlrev_b32_e32 v156, 16, v173
	v_and_b32_e32 v157, 0xffff0000, v173
	v_pk_add_f32 v[120:121], v[120:121], v[156:157]
	v_lshlrev_b32_e32 v156, 16, v174
	v_and_b32_e32 v157, 0xffff0000, v174
	v_pk_add_f32 v[118:119], v[118:119], v[160:161]
	v_pk_add_f32 v[156:157], v[114:115], v[156:157]
	v_lshlrev_b32_e32 v114, 16, v175
	v_and_b32_e32 v115, 0xffff0000, v175
	v_pk_add_f32 v[158:159], v[116:117], v[114:115]
	v_pk_mul_f32 v[114:115], v[118:119], v[118:119]
	v_pk_mul_f32 v[116:117], v[120:121], v[120:121]
	v_add_f32_e32 v114, v114, v122
	v_add_f32_e32 v114, v115, v114
	v_add_f32_e32 v114, v116, v114
	v_pk_mul_f32 v[160:161], v[156:157], v[156:157]
	v_add_f32_e32 v114, v117, v114
	v_add_f32_e32 v114, v160, v114
	v_pk_mul_f32 v[162:163], v[158:159], v[158:159]
	v_add_f32_e32 v114, v161, v114
	v_add_f32_e32 v114, v162, v114
	v_add_f32_e32 v122, v163, v114
	v_cvt_pk_bf16_f32 v114, v118, v119
	v_cvt_pk_bf16_f32 v115, v120, v121
	v_cvt_pk_bf16_f32 v116, v156, v157
	v_cvt_pk_bf16_f32 v117, v158, v159
	global_store_dwordx4 v[144:145], v[114:117], off offset:256 sc0 sc1
	s_mov_b64 s[20:21], 0x48000
	s_nop 0
	v_lshl_add_u64 v[224:225], v[226:227], 0, s[20:21]
	global_load_dwordx4 v[168:171], v[224:225], off
	global_load_dwordx4 v[172:175], v[224:225], off offset:256
	ds_bpermute_b32 v114, v154, v122
	s_waitcnt lgkmcnt(0)
	v_add_f32_e32 v114, v122, v114
	ds_bpermute_b32 v115, v153, v114
	s_and_saveexec_b64 s[20:21], s[38:39]
	s_cbranch_execz .LBB0_941
	s_waitcnt lgkmcnt(0)
	v_add_f32_e32 v114, v114, v115
	ds_write_b32 v150, v114
; __device__ __forceinline__ unsigned cvtpk(float lo, float hi) { f32x2 v = {lo, hi}; bf16x2_t b = __builtin_convertvector(v, bf16x2_t); return __builtin_bit_cast(unsigned, b); }
;     __device__ __forceinline__ void operator()(AccRef acc, const Unit& u, int wr, int wc, int fr, int fq) const {
;     ...
; #pragma unroll
;         for (int ai = 0; ai < 2; ++ai)
; #pragma unroll
;             for (int m = 0; m < 4; ++m) {
;                 const int row = row0 + ai * 128 + m * 16; bf16_t* rowp = XB + (size_t)row * DM + col0; float s = 0.f;
; #pragma unroll
;                 for (int bj = 0; bj < 2; ++bj) {
;                     const u32x4 xo = *(const u32x4*)(rowp + bj * 128);
;                     float v[8];
; #pragma unroll
;                     for (int k = 0; k < 4; ++k) { v[2 * k] = __uint_as_float(xo[k] << 16) + acc[ai][bj][m][k >> 1][(2 * k) & 3]; v[2 * k + 1] = __uint_as_float(xo[k] & 0xffff0000u) + acc[ai][bj][m][k >> 1][(2 * k + 1) & 3]; }
; #pragma unroll
;                     for (int k = 0; k < 8; ++k) s += v[k] * v[k];
;                     u32x4 w; w.x = cvtpk(v[0], v[1]); w.y = cvtpk(v[2], v[3]); w.z = cvtpk(v[4], v[5]); w.w = cvtpk(v[6], v[7]);
;                     st16_wt(rowp + bj * 128, w);
;                 }
;                 s += __shfl_xor(s, 16); s += __shfl_xor(s, 32);
;                 if (fq == 0) red[(ai * 128 + wr * 64 + m * 16 + fr) * 4 + wc] = s;
;                 asm volatile("" ::: "memory");
;             }
.LBB0_941:
	s_or_b64 exec, exec, s[20:21]
	v_or_b32_e32 v114, 16, v142
	s_waitcnt lgkmcnt(0)
	v_ashrrev_i32_e32 v115, 31, v114
	v_lshlrev_b64 v[114:115], 11, v[114:115]
	v_lshl_add_u64 v[114:115], s[66:67], 0, v[114:115]
	v_lshl_add_u64 v[114:115], v[140:141], 1, v[114:115]
	s_waitcnt vmcnt(11)
	v_lshlrev_b32_e32 v120, 16, v176
	v_and_b32_e32 v121, 0xffff0000, v176
	v_lshlrev_b32_e32 v116, 16, v177
	v_and_b32_e32 v117, 0xffff0000, v177
	v_pk_add_f32 v[112:113], v[112:113], v[116:117]
	v_lshlrev_b32_e32 v116, 16, v178
	v_and_b32_e32 v117, 0xffff0000, v178
	v_pk_add_f32 v[116:117], v[106:107], v[116:117]
	v_lshlrev_b32_e32 v106, 16, v179
	v_and_b32_e32 v107, 0xffff0000, v179
	v_pk_add_f32 v[110:111], v[110:111], v[120:121]
	v_pk_add_f32 v[118:119], v[108:109], v[106:107]
	v_cvt_pk_bf16_f32 v106, v110, v111
	v_cvt_pk_bf16_f32 v107, v112, v113
	v_cvt_pk_bf16_f32 v108, v116, v117
	v_cvt_pk_bf16_f32 v109, v118, v119
	global_store_dwordx4 v[114:115], v[106:109], off sc0 sc1
	v_pk_mul_f32 v[120:121], v[110:111], v[110:111]
	v_pk_mul_f32 v[122:123], v[112:113], v[112:113]
	v_pk_mul_f32 v[124:125], v[116:117], v[116:117]
	v_add_f32_e32 v116, v120, v121
	v_add_f32_e32 v116, v122, v116
	v_add_f32_e32 v116, v123, v116
	v_add_f32_e32 v116, v124, v116
	v_pk_mul_f32 v[126:127], v[118:119], v[118:119]
	v_add_f32_e32 v116, v125, v116
	v_add_f32_e32 v116, v126, v116
	v_add_f32_e32 v116, v127, v116
	s_waitcnt vmcnt(11)
	v_lshlrev_b32_e32 v110, 16, v180
	v_and_b32_e32 v111, 0xffff0000, v180
	v_lshlrev_b32_e32 v106, 16, v181
	v_and_b32_e32 v107, 0xffff0000, v181
	v_pk_add_f32 v[104:105], v[104:105], v[106:107]
	v_lshlrev_b32_e32 v106, 16, v182
	v_and_b32_e32 v107, 0xffff0000, v182
	v_pk_add_f32 v[102:103], v[102:103], v[110:111]
	v_pk_add_f32 v[106:107], v[98:99], v[106:107]
	v_lshlrev_b32_e32 v98, 16, v183
	v_and_b32_e32 v99, 0xffff0000, v183
	v_pk_add_f32 v[108:109], v[100:101], v[98:99]
	v_pk_mul_f32 v[98:99], v[102:103], v[102:103]
	v_pk_mul_f32 v[100:101], v[104:105], v[104:105]
	v_add_f32_e32 v98, v98, v116
	v_add_f32_e32 v98, v99, v98
	v_add_f32_e32 v98, v100, v98
	v_pk_mul_f32 v[110:111], v[106:107], v[106:107]
	v_add_f32_e32 v98, v101, v98
	v_add_f32_e32 v98, v110, v98
	v_pk_mul_f32 v[112:113], v[108:109], v[108:109]
	v_add_f32_e32 v98, v111, v98
	v_add_f32_e32 v98, v112, v98
	v_add_f32_e32 v110, v113, v98
	v_cvt_pk_bf16_f32 v98, v102, v103
	v_cvt_pk_bf16_f32 v99, v104, v105
	v_cvt_pk_bf16_f32 v100, v106, v107
	v_cvt_pk_bf16_f32 v101, v108, v109
	global_store_dwordx4 v[114:115], v[98:101], off offset:256 sc0 sc1
	s_mov_b64 s[20:21], 0x50000
	s_nop 0
	v_lshl_add_u64 v[224:225], v[226:227], 0, s[20:21]
	global_load_dwordx4 v[176:179], v[224:225], off
	global_load_dwordx4 v[180:183], v[224:225], off offset:256
	ds_bpermute_b32 v98, v154, v110
	s_waitcnt lgkmcnt(0)
	v_add_f32_e32 v98, v110, v98
	ds_bpermute_b32 v99, v153, v98
	s_and_saveexec_b64 s[20:21], s[38:39]
	s_cbranch_execz .LBB0_943
	s_waitcnt lgkmcnt(0)
	v_add_f32_e32 v98, v98, v99
	ds_write_b32 v150, v98 offset:256
.LBB0_943:
	s_or_b64 exec, exec, s[20:21]
	v_or_b32_e32 v98, 32, v142
	s_waitcnt lgkmcnt(0)
	v_ashrrev_i32_e32 v99, 31, v98
	v_lshlrev_b64 v[98:99], 11, v[98:99]
	v_lshl_add_u64 v[98:99], s[66:67], 0, v[98:99]
	v_lshl_add_u64 v[98:99], v[140:141], 1, v[98:99]
	s_waitcnt vmcnt(13)
	v_lshlrev_b32_e32 v104, 16, v184
	v_and_b32_e32 v105, 0xffff0000, v184
	v_lshlrev_b32_e32 v100, 16, v185
	v_and_b32_e32 v101, 0xffff0000, v185
	v_pk_add_f32 v[96:97], v[96:97], v[100:101]
	v_lshlrev_b32_e32 v100, 16, v186
	v_and_b32_e32 v101, 0xffff0000, v186
	v_pk_add_f32 v[100:101], v[90:91], v[100:101]
	v_lshlrev_b32_e32 v90, 16, v187
	v_and_b32_e32 v91, 0xffff0000, v187
	v_pk_add_f32 v[94:95], v[94:95], v[104:105]
	v_pk_add_f32 v[102:103], v[92:93], v[90:91]
	v_cvt_pk_bf16_f32 v90, v94, v95
	v_cvt_pk_bf16_f32 v91, v96, v97
	v_cvt_pk_bf16_f32 v92, v100, v101
	v_cvt_pk_bf16_f32 v93, v102, v103
	global_store_dwordx4 v[98:99], v[90:93], off sc0 sc1
	v_pk_mul_f32 v[104:105], v[94:95], v[94:95]
	v_pk_mul_f32 v[106:107], v[96:97], v[96:97]
	v_pk_mul_f32 v[108:109], v[100:101], v[100:101]
	v_add_f32_e32 v100, v104, v105
	v_add_f32_e32 v100, v106, v100
	v_add_f32_e32 v100, v107, v100
	v_add_f32_e32 v100, v108, v100
	v_pk_mul_f32 v[110:111], v[102:103], v[102:103]
	v_add_f32_e32 v100, v109, v100
	v_add_f32_e32 v100, v110, v100
	v_add_f32_e32 v100, v111, v100
	s_waitcnt vmcnt(13)
	v_lshlrev_b32_e32 v94, 16, v188
	v_and_b32_e32 v95, 0xffff0000, v188
	v_lshlrev_b32_e32 v90, 16, v189
	v_and_b32_e32 v91, 0xffff0000, v189
	v_pk_add_f32 v[88:89], v[88:89], v[90:91]
	v_lshlrev_b32_e32 v90, 16, v190
	v_and_b32_e32 v91, 0xffff0000, v190
	v_pk_add_f32 v[86:87], v[86:87], v[94:95]
	v_pk_add_f32 v[90:91], v[82:83], v[90:91]
	v_lshlrev_b32_e32 v82, 16, v191
	v_and_b32_e32 v83, 0xffff0000, v191
	v_pk_add_f32 v[92:93], v[84:85], v[82:83]
	v_pk_mul_f32 v[82:83], v[86:87], v[86:87]
	v_pk_mul_f32 v[84:85], v[88:89], v[88:89]
	v_add_f32_e32 v82, v82, v100
	v_add_f32_e32 v82, v83, v82
	v_add_f32_e32 v82, v84, v82
	v_pk_mul_f32 v[94:95], v[90:91], v[90:91]
	v_add_f32_e32 v82, v85, v82
	v_add_f32_e32 v82, v94, v82
	v_pk_mul_f32 v[96:97], v[92:93], v[92:93]
	v_add_f32_e32 v82, v95, v82
	v_add_f32_e32 v82, v96, v82
	v_add_f32_e32 v94, v97, v82
	v_cvt_pk_bf16_f32 v82, v86, v87
	v_cvt_pk_bf16_f32 v83, v88, v89
	v_cvt_pk_bf16_f32 v84, v90, v91
	v_cvt_pk_bf16_f32 v85, v92, v93
	global_store_dwordx4 v[98:99], v[82:85], off offset:256 sc0 sc1
	s_mov_b64 s[20:21], 0x58000
	s_nop 0
	v_lshl_add_u64 v[224:225], v[226:227], 0, s[20:21]
	global_load_dwordx4 v[184:187], v[224:225], off
	global_load_dwordx4 v[188:191], v[224:225], off offset:256
	ds_bpermute_b32 v82, v154, v94
	s_waitcnt lgkmcnt(0)
	v_add_f32_e32 v82, v94, v82
	ds_bpermute_b32 v83, v153, v82
	s_and_saveexec_b64 s[20:21], s[38:39]
	s_cbranch_execz .LBB0_945
	s_waitcnt lgkmcnt(0)
	v_add_f32_e32 v82, v82, v83
	ds_write_b32 v150, v82 offset:512
; __device__ __forceinline__ unsigned cvtpk(float lo, float hi) { f32x2 v = {lo, hi}; bf16x2_t b = __builtin_convertvector(v, bf16x2_t); return __builtin_bit_cast(unsigned, b); }
;     __device__ __forceinline__ void operator()(AccRef acc, const Unit& u, int wr, int wc, int fr, int fq) const {
;     ...
; #pragma unroll
;         for (int ai = 0; ai < 2; ++ai)
; #pragma unroll
;             for (int m = 0; m < 4; ++m) {
;                 const int row = row0 + ai * 128 + m * 16; bf16_t* rowp = XB + (size_t)row * DM + col0; float s = 0.f;
; #pragma unroll
;                 for (int bj = 0; bj < 2; ++bj) {
;                     const u32x4 xo = *(const u32x4*)(rowp + bj * 128);
;                     float v[8];
; #pragma unroll
;                     for (int k = 0; k < 4; ++k) { v[2 * k] = __uint_as_float(xo[k] << 16) + acc[ai][bj][m][k >> 1][(2 * k) & 3]; v[2 * k + 1] = __uint_as_float(xo[k] & 0xffff0000u) + acc[ai][bj][m][k >> 1][(2 * k + 1) & 3]; }
; #pragma unroll
;                     for (int k = 0; k < 8; ++k) s += v[k] * v[k];
;                     u32x4 w; w.x = cvtpk(v[0], v[1]); w.y = cvtpk(v[2], v[3]); w.z = cvtpk(v[4], v[5]); w.w = cvtpk(v[6], v[7]);
;                     st16_wt(rowp + bj * 128, w);
;                 }
;                 s += __shfl_xor(s, 16); s += __shfl_xor(s, 32);
;                 if (fq == 0) red[(ai * 128 + wr * 64 + m * 16 + fr) * 4 + wc] = s;
;                 asm volatile("" ::: "memory");
;             }
.LBB0_945:
	s_or_b64 exec, exec, s[20:21]
	v_or_b32_e32 v82, 48, v142
	s_waitcnt lgkmcnt(0)
	v_ashrrev_i32_e32 v83, 31, v82
	v_lshlrev_b64 v[82:83], 11, v[82:83]
	v_lshl_add_u64 v[82:83], s[66:67], 0, v[82:83]
	v_lshl_add_u64 v[82:83], v[140:141], 1, v[82:83]
	s_waitcnt vmcnt(15)
	v_lshlrev_b32_e32 v88, 16, v192
	v_and_b32_e32 v89, 0xffff0000, v192
	v_lshlrev_b32_e32 v84, 16, v193
	v_and_b32_e32 v85, 0xffff0000, v193
	v_pk_add_f32 v[80:81], v[80:81], v[84:85]
	v_lshlrev_b32_e32 v84, 16, v194
	v_and_b32_e32 v85, 0xffff0000, v194
	v_pk_add_f32 v[84:85], v[74:75], v[84:85]
	v_lshlrev_b32_e32 v74, 16, v195
	v_and_b32_e32 v75, 0xffff0000, v195
	v_pk_add_f32 v[78:79], v[78:79], v[88:89]
	v_pk_add_f32 v[86:87], v[76:77], v[74:75]
	v_cvt_pk_bf16_f32 v74, v78, v79
	v_cvt_pk_bf16_f32 v75, v80, v81
	v_cvt_pk_bf16_f32 v76, v84, v85
	v_cvt_pk_bf16_f32 v77, v86, v87
	global_store_dwordx4 v[82:83], v[74:77], off sc0 sc1
	v_pk_mul_f32 v[88:89], v[78:79], v[78:79]
	v_pk_mul_f32 v[90:91], v[80:81], v[80:81]
	v_pk_mul_f32 v[92:93], v[84:85], v[84:85]
	v_add_f32_e32 v84, v88, v89
	v_add_f32_e32 v84, v90, v84
	v_add_f32_e32 v84, v91, v84
	v_add_f32_e32 v84, v92, v84
	v_pk_mul_f32 v[94:95], v[86:87], v[86:87]
	v_add_f32_e32 v84, v93, v84
	v_add_f32_e32 v84, v94, v84
	v_add_f32_e32 v84, v95, v84
	s_waitcnt vmcnt(15)
	v_lshlrev_b32_e32 v78, 16, v196
	v_and_b32_e32 v79, 0xffff0000, v196
	v_lshlrev_b32_e32 v74, 16, v197
	v_and_b32_e32 v75, 0xffff0000, v197
	v_pk_add_f32 v[72:73], v[72:73], v[74:75]
	v_lshlrev_b32_e32 v74, 16, v198
	v_and_b32_e32 v75, 0xffff0000, v198
	v_pk_add_f32 v[70:71], v[70:71], v[78:79]
	v_pk_add_f32 v[74:75], v[66:67], v[74:75]
	v_lshlrev_b32_e32 v66, 16, v199
	v_and_b32_e32 v67, 0xffff0000, v199
	v_pk_add_f32 v[76:77], v[68:69], v[66:67]
	v_pk_mul_f32 v[66:67], v[70:71], v[70:71]
	v_pk_mul_f32 v[68:69], v[72:73], v[72:73]
	v_add_f32_e32 v66, v66, v84
	v_add_f32_e32 v66, v67, v66
	v_add_f32_e32 v66, v68, v66
	v_pk_mul_f32 v[78:79], v[74:75], v[74:75]
	v_add_f32_e32 v66, v69, v66
	v_add_f32_e32 v66, v78, v66
	v_pk_mul_f32 v[80:81], v[76:77], v[76:77]
	v_add_f32_e32 v66, v79, v66
	v_add_f32_e32 v66, v80, v66
	v_add_f32_e32 v78, v81, v66
	v_cvt_pk_bf16_f32 v66, v70, v71
	v_cvt_pk_bf16_f32 v67, v72, v73
	v_cvt_pk_bf16_f32 v68, v74, v75
	v_cvt_pk_bf16_f32 v69, v76, v77
	global_store_dwordx4 v[82:83], v[66:69], off offset:256 sc0 sc1
	ds_bpermute_b32 v66, v154, v78
	s_waitcnt lgkmcnt(0)
	v_add_f32_e32 v66, v78, v66
	ds_bpermute_b32 v67, v153, v66
	s_and_saveexec_b64 s[20:21], s[38:39]
	s_cbranch_execz .LBB0_947
	s_waitcnt lgkmcnt(0)
	v_add_f32_e32 v66, v66, v67
	ds_write_b32 v150, v66 offset:768
.LBB0_947:
	s_or_b64 exec, exec, s[20:21]
	s_waitcnt lgkmcnt(0)
	v_lshlrev_b64 v[66:67], 11, v[142:143]
	v_lshl_add_u64 v[66:67], s[66:67], 0, v[66:67]
	v_lshl_add_u64 v[66:67], v[140:141], 1, v[66:67]
	v_add_co_u32_e32 v74, vcc, 0x40000, v66
	s_mov_b64 s[20:21], 0x40000
	s_nop 0
	v_addc_co_u32_e32 v75, vcc, 0, v67, vcc
	v_lshl_add_u64 v[68:69], v[66:67], 0, s[20:21]
	s_waitcnt vmcnt(15)
	v_lshlrev_b32_e32 v76, 16, v200
	v_and_b32_e32 v77, 0xffff0000, v200
	v_pk_add_f32 v[76:77], v[62:63], v[76:77]
	v_lshlrev_b32_e32 v62, 16, v201
	v_and_b32_e32 v63, 0xffff0000, v201
	v_pk_add_f32 v[78:79], v[64:65], v[62:63]
	v_lshlrev_b32_e32 v62, 16, v202
	v_and_b32_e32 v63, 0xffff0000, v202
	v_pk_add_f32 v[80:81], v[58:59], v[62:63]
	v_lshlrev_b32_e32 v58, 16, v203
	v_and_b32_e32 v59, 0xffff0000, v203
	v_pk_add_f32 v[82:83], v[60:61], v[58:59]
	v_cvt_pk_bf16_f32 v70, v76, v77
	v_cvt_pk_bf16_f32 v71, v78, v79
	v_cvt_pk_bf16_f32 v72, v80, v81
	v_cvt_pk_bf16_f32 v73, v82, v83
	global_store_dwordx4 v[74:75], v[70:73], off sc0 sc1
	v_pk_mul_f32 v[64:65], v[76:77], v[76:77]
	v_pk_mul_f32 v[62:63], v[78:79], v[78:79]
	v_add_f32_e32 v64, v64, v65
	v_add_f32_e32 v62, v62, v64
	v_pk_mul_f32 v[60:61], v[80:81], v[80:81]
	v_add_f32_e32 v62, v63, v62
	v_add_f32_e32 v60, v60, v62
	v_pk_mul_f32 v[58:59], v[82:83], v[82:83]
	v_add_f32_e32 v60, v61, v60
	v_add_f32_e32 v58, v58, v60
	v_add_f32_e32 v58, v59, v58
	s_waitcnt vmcnt(15)
	v_lshlrev_b32_e32 v74, 16, v204
	v_and_b32_e32 v75, 0xffff0000, v204
	v_lshlrev_b32_e32 v70, 16, v205
	v_and_b32_e32 v71, 0xffff0000, v205
	v_pk_add_f32 v[56:57], v[56:57], v[70:71]
	v_lshlrev_b32_e32 v70, 16, v206
	v_and_b32_e32 v71, 0xffff0000, v206
	v_pk_add_f32 v[54:55], v[54:55], v[74:75]
	v_pk_add_f32 v[70:71], v[50:51], v[70:71]
	v_lshlrev_b32_e32 v50, 16, v207
	v_and_b32_e32 v51, 0xffff0000, v207
	v_pk_add_f32 v[72:73], v[52:53], v[50:51]
	v_pk_mul_f32 v[50:51], v[54:55], v[54:55]
	v_pk_mul_f32 v[52:53], v[56:57], v[56:57]
	v_add_f32_e32 v50, v50, v58
	v_add_f32_e32 v50, v51, v50
	v_add_f32_e32 v50, v52, v50
	v_pk_mul_f32 v[74:75], v[70:71], v[70:71]
	v_add_f32_e32 v50, v53, v50
	v_add_f32_e32 v50, v74, v50
	v_pk_mul_f32 v[76:77], v[72:73], v[72:73]
	v_add_f32_e32 v50, v75, v50
	v_add_f32_e32 v50, v76, v50
	v_add_f32_e32 v58, v77, v50
	v_cvt_pk_bf16_f32 v50, v54, v55
	v_cvt_pk_bf16_f32 v51, v56, v57
	v_cvt_pk_bf16_f32 v52, v70, v71
	v_cvt_pk_bf16_f32 v53, v72, v73
	global_store_dwordx4 v[68:69], v[50:53], off offset:256 sc0 sc1
	ds_bpermute_b32 v50, v154, v58
	s_waitcnt lgkmcnt(0)
	v_add_f32_e32 v50, v58, v50
	ds_bpermute_b32 v51, v153, v50
	s_and_saveexec_b64 s[20:21], s[38:39]
	s_cbranch_execz .LBB0_949
	s_waitcnt lgkmcnt(0)
	v_add_f32_e32 v50, v50, v51
	ds_write_b32 v150, v50 offset:2048
; __device__ __forceinline__ unsigned cvtpk(float lo, float hi) { f32x2 v = {lo, hi}; bf16x2_t b = __builtin_convertvector(v, bf16x2_t); return __builtin_bit_cast(unsigned, b); }
;     __device__ __forceinline__ void operator()(AccRef acc, const Unit& u, int wr, int wc, int fr, int fq) const {
;     ...
; #pragma unroll
;         for (int ai = 0; ai < 2; ++ai)
; #pragma unroll
;             for (int m = 0; m < 4; ++m) {
;                 const int row = row0 + ai * 128 + m * 16; bf16_t* rowp = XB + (size_t)row * DM + col0; float s = 0.f;
; #pragma unroll
;                 for (int bj = 0; bj < 2; ++bj) {
;                     const u32x4 xo = *(const u32x4*)(rowp + bj * 128);
;                     float v[8];
; #pragma unroll
;                     for (int k = 0; k < 4; ++k) { v[2 * k] = __uint_as_float(xo[k] << 16) + acc[ai][bj][m][k >> 1][(2 * k) & 3]; v[2 * k + 1] = __uint_as_float(xo[k] & 0xffff0000u) + acc[ai][bj][m][k >> 1][(2 * k + 1) & 3]; }
; #pragma unroll
;                     for (int k = 0; k < 8; ++k) s += v[k] * v[k];
;                     u32x4 w; w.x = cvtpk(v[0], v[1]); w.y = cvtpk(v[2], v[3]); w.z = cvtpk(v[4], v[5]); w.w = cvtpk(v[6], v[7]);
;                     st16_wt(rowp + bj * 128, w);
;                 }
;                 s += __shfl_xor(s, 16); s += __shfl_xor(s, 32);
;                 if (fq == 0) red[(ai * 128 + wr * 64 + m * 16 + fr) * 4 + wc] = s;
;                 asm volatile("" ::: "memory");
;             }
.LBB0_949:
	s_or_b64 exec, exec, s[20:21]
	v_add_co_u32_e32 v56, vcc, 0x48000, v66
	s_mov_b64 s[20:21], 0x48000
	s_nop 0
	v_addc_co_u32_e32 v57, vcc, 0, v67, vcc
	s_waitcnt lgkmcnt(0)
	v_lshl_add_u64 v[50:51], v[66:67], 0, s[20:21]
	s_waitcnt vmcnt(13)
	v_lshlrev_b32_e32 v58, 16, v168
	v_and_b32_e32 v59, 0xffff0000, v168
	v_pk_add_f32 v[58:59], v[46:47], v[58:59]
	v_lshlrev_b32_e32 v46, 16, v169
	v_and_b32_e32 v47, 0xffff0000, v169
	v_pk_add_f32 v[60:61], v[48:49], v[46:47]
	v_lshlrev_b32_e32 v46, 16, v170
	v_and_b32_e32 v47, 0xffff0000, v170
	v_pk_add_f32 v[62:63], v[42:43], v[46:47]
	v_lshlrev_b32_e32 v42, 16, v171
	v_and_b32_e32 v43, 0xffff0000, v171
	v_pk_add_f32 v[64:65], v[44:45], v[42:43]
	v_cvt_pk_bf16_f32 v52, v58, v59
	v_cvt_pk_bf16_f32 v53, v60, v61
	v_cvt_pk_bf16_f32 v54, v62, v63
	v_cvt_pk_bf16_f32 v55, v64, v65
	global_store_dwordx4 v[56:57], v[52:55], off sc0 sc1
	v_pk_mul_f32 v[48:49], v[58:59], v[58:59]
	v_pk_mul_f32 v[46:47], v[60:61], v[60:61]
	v_add_f32_e32 v48, v48, v49
	v_add_f32_e32 v46, v46, v48
	v_pk_mul_f32 v[44:45], v[62:63], v[62:63]
	v_add_f32_e32 v46, v47, v46
	v_add_f32_e32 v44, v44, v46
	v_pk_mul_f32 v[42:43], v[64:65], v[64:65]
	v_add_f32_e32 v44, v45, v44
	v_add_f32_e32 v42, v42, v44
	v_add_f32_e32 v42, v43, v42
	s_waitcnt vmcnt(13)
	v_lshlrev_b32_e32 v56, 16, v172
	v_and_b32_e32 v57, 0xffff0000, v172
	v_lshlrev_b32_e32 v52, 16, v173
	v_and_b32_e32 v53, 0xffff0000, v173
	v_pk_add_f32 v[40:41], v[40:41], v[52:53]
	v_lshlrev_b32_e32 v52, 16, v174
	v_and_b32_e32 v53, 0xffff0000, v174
	v_pk_add_f32 v[38:39], v[38:39], v[56:57]
	v_pk_add_f32 v[52:53], v[34:35], v[52:53]
	v_lshlrev_b32_e32 v34, 16, v175
	v_and_b32_e32 v35, 0xffff0000, v175
	v_pk_add_f32 v[54:55], v[36:37], v[34:35]
	v_pk_mul_f32 v[34:35], v[38:39], v[38:39]
	v_pk_mul_f32 v[36:37], v[40:41], v[40:41]
	v_add_f32_e32 v34, v34, v42
	v_add_f32_e32 v34, v35, v34
	v_add_f32_e32 v34, v36, v34
	v_pk_mul_f32 v[56:57], v[52:53], v[52:53]
	v_add_f32_e32 v34, v37, v34
	v_add_f32_e32 v34, v56, v34
	v_pk_mul_f32 v[58:59], v[54:55], v[54:55]
	v_add_f32_e32 v34, v57, v34
	v_add_f32_e32 v34, v58, v34
	v_add_f32_e32 v42, v59, v34
	v_cvt_pk_bf16_f32 v34, v38, v39
	v_cvt_pk_bf16_f32 v35, v40, v41
	v_cvt_pk_bf16_f32 v36, v52, v53
	v_cvt_pk_bf16_f32 v37, v54, v55
	global_store_dwordx4 v[50:51], v[34:37], off offset:256 sc0 sc1
	ds_bpermute_b32 v34, v154, v42
	s_waitcnt lgkmcnt(0)
	v_add_f32_e32 v34, v42, v34
	ds_bpermute_b32 v35, v153, v34
	s_and_saveexec_b64 s[20:21], s[38:39]
	s_cbranch_execz .LBB0_951
	s_waitcnt lgkmcnt(0)
	v_add_f32_e32 v34, v34, v35
	ds_write_b32 v150, v34 offset:2304
; __device__ __forceinline__ unsigned cvtpk(float lo, float hi) { f32x2 v = {lo, hi}; bf16x2_t b = __builtin_convertvector(v, bf16x2_t); return __builtin_bit_cast(unsigned, b); }
;     __device__ __forceinline__ void operator()(AccRef acc, const Unit& u, int wr, int wc, int fr, int fq) const {
;     ...
; #pragma unroll
;         for (int ai = 0; ai < 2; ++ai)
; #pragma unroll
;             for (int m = 0; m < 4; ++m) {
;                 const int row = row0 + ai * 128 + m * 16; bf16_t* rowp = XB + (size_t)row * DM + col0; float s = 0.f;
; #pragma unroll
;                 for (int bj = 0; bj < 2; ++bj) {
;                     const u32x4 xo = *(const u32x4*)(rowp + bj * 128);
;                     float v[8];
; #pragma unroll
;                     for (int k = 0; k < 4; ++k) { v[2 * k] = __uint_as_float(xo[k] << 16) + acc[ai][bj][m][k >> 1][(2 * k) & 3]; v[2 * k + 1] = __uint_as_float(xo[k] & 0xffff0000u) + acc[ai][bj][m][k >> 1][(2 * k + 1) & 3]; }
; #pragma unroll
;                     for (int k = 0; k < 8; ++k) s += v[k] * v[k];
;                     u32x4 w; w.x = cvtpk(v[0], v[1]); w.y = cvtpk(v[2], v[3]); w.z = cvtpk(v[4], v[5]); w.w = cvtpk(v[6], v[7]);
;                     st16_wt(rowp + bj * 128, w);
;                 }
;                 s += __shfl_xor(s, 16); s += __shfl_xor(s, 32);
;                 if (fq == 0) red[(ai * 128 + wr * 64 + m * 16 + fr) * 4 + wc] = s;
;                 asm volatile("" ::: "memory");
;             }
.LBB0_951:
	s_or_b64 exec, exec, s[20:21]
	s_waitcnt lgkmcnt(0)
	v_lshlrev_b64 v[34:35], 11, v[142:143]
	v_lshl_add_u64 v[34:35], s[66:67], 0, v[34:35]
	v_lshl_add_u64 v[34:35], v[140:141], 1, v[34:35]
	v_add_co_u32_e32 v42, vcc, 0x50000, v34
	s_mov_b64 s[20:21], 0x50000
	s_nop 0
	v_addc_co_u32_e32 v43, vcc, 0, v35, vcc
	v_lshl_add_u64 v[36:37], v[34:35], 0, s[20:21]
	s_waitcnt vmcnt(11)
	v_lshlrev_b32_e32 v44, 16, v176
	v_and_b32_e32 v45, 0xffff0000, v176
	v_pk_add_f32 v[44:45], v[30:31], v[44:45]
	v_lshlrev_b32_e32 v30, 16, v177
	v_and_b32_e32 v31, 0xffff0000, v177
	v_pk_add_f32 v[46:47], v[32:33], v[30:31]
	v_lshlrev_b32_e32 v30, 16, v178
	v_and_b32_e32 v31, 0xffff0000, v178
	v_pk_add_f32 v[48:49], v[26:27], v[30:31]
	v_lshlrev_b32_e32 v26, 16, v179
	v_and_b32_e32 v27, 0xffff0000, v179
	v_pk_add_f32 v[50:51], v[28:29], v[26:27]
	v_cvt_pk_bf16_f32 v38, v44, v45
	v_cvt_pk_bf16_f32 v39, v46, v47
	v_cvt_pk_bf16_f32 v40, v48, v49
	v_cvt_pk_bf16_f32 v41, v50, v51
	global_store_dwordx4 v[42:43], v[38:41], off sc0 sc1
	v_pk_mul_f32 v[32:33], v[44:45], v[44:45]
	v_pk_mul_f32 v[30:31], v[46:47], v[46:47]
	v_add_f32_e32 v32, v32, v33
	v_add_f32_e32 v30, v30, v32
	v_pk_mul_f32 v[28:29], v[48:49], v[48:49]
	v_add_f32_e32 v30, v31, v30
	v_add_f32_e32 v28, v28, v30
	v_pk_mul_f32 v[26:27], v[50:51], v[50:51]
	v_add_f32_e32 v28, v29, v28
	v_add_f32_e32 v26, v26, v28
	v_add_f32_e32 v26, v27, v26
	s_waitcnt vmcnt(11)
	v_lshlrev_b32_e32 v42, 16, v180
	v_and_b32_e32 v43, 0xffff0000, v180
	v_lshlrev_b32_e32 v38, 16, v181
	v_and_b32_e32 v39, 0xffff0000, v181
	v_pk_add_f32 v[24:25], v[24:25], v[38:39]
	v_lshlrev_b32_e32 v38, 16, v182
	v_and_b32_e32 v39, 0xffff0000, v182
	v_pk_add_f32 v[22:23], v[22:23], v[42:43]
	v_pk_add_f32 v[38:39], v[18:19], v[38:39]
	v_lshlrev_b32_e32 v18, 16, v183
	v_and_b32_e32 v19, 0xffff0000, v183
	v_pk_add_f32 v[40:41], v[20:21], v[18:19]
	v_pk_mul_f32 v[18:19], v[22:23], v[22:23]
	v_pk_mul_f32 v[20:21], v[24:25], v[24:25]
	v_add_f32_e32 v18, v18, v26
	v_add_f32_e32 v18, v19, v18
	v_add_f32_e32 v18, v20, v18
	v_pk_mul_f32 v[42:43], v[38:39], v[38:39]
	v_add_f32_e32 v18, v21, v18
	v_add_f32_e32 v18, v42, v18
	v_pk_mul_f32 v[44:45], v[40:41], v[40:41]
	v_add_f32_e32 v18, v43, v18
	v_add_f32_e32 v18, v44, v18
	v_add_f32_e32 v26, v45, v18
	v_cvt_pk_bf16_f32 v18, v22, v23
	v_cvt_pk_bf16_f32 v19, v24, v25
	v_cvt_pk_bf16_f32 v20, v38, v39
	v_cvt_pk_bf16_f32 v21, v40, v41
	global_store_dwordx4 v[36:37], v[18:21], off offset:256 sc0 sc1
	ds_bpermute_b32 v18, v154, v26
	s_waitcnt lgkmcnt(0)
	v_add_f32_e32 v18, v26, v18
	ds_bpermute_b32 v19, v153, v18
	s_and_saveexec_b64 s[20:21], s[38:39]
	s_cbranch_execz .LBB0_953
	s_waitcnt lgkmcnt(0)
	v_add_f32_e32 v18, v18, v19
	ds_write_b32 v150, v18 offset:2560
.LBB0_953:
	s_or_b64 exec, exec, s[20:21]
	v_add_co_u32_e32 v24, vcc, 0x58000, v34
	s_mov_b64 s[20:21], 0x58000
	s_nop 0
	v_addc_co_u32_e32 v25, vcc, 0, v35, vcc
	s_waitcnt lgkmcnt(0)
	v_lshl_add_u64 v[18:19], v[34:35], 0, s[20:21]
	s_waitcnt vmcnt(9)
	v_lshlrev_b32_e32 v26, 16, v184
	v_and_b32_e32 v27, 0xffff0000, v184
	v_pk_add_f32 v[26:27], v[14:15], v[26:27]
	v_lshlrev_b32_e32 v14, 16, v185
	v_and_b32_e32 v15, 0xffff0000, v185
	v_pk_add_f32 v[28:29], v[16:17], v[14:15]
	v_lshlrev_b32_e32 v14, 16, v186
	v_and_b32_e32 v15, 0xffff0000, v186
	v_pk_add_f32 v[30:31], v[10:11], v[14:15]
	v_lshlrev_b32_e32 v10, 16, v187
	v_and_b32_e32 v11, 0xffff0000, v187
	v_pk_add_f32 v[32:33], v[12:13], v[10:11]
	v_cvt_pk_bf16_f32 v20, v26, v27
	v_cvt_pk_bf16_f32 v21, v28, v29
	v_cvt_pk_bf16_f32 v22, v30, v31
	v_cvt_pk_bf16_f32 v23, v32, v33
	global_store_dwordx4 v[24:25], v[20:23], off sc0 sc1
	v_pk_mul_f32 v[16:17], v[26:27], v[26:27]
	v_pk_mul_f32 v[14:15], v[28:29], v[28:29]
	v_add_f32_e32 v16, v16, v17
	v_add_f32_e32 v14, v14, v16
	v_pk_mul_f32 v[12:13], v[30:31], v[30:31]
	v_add_f32_e32 v14, v15, v14
	v_add_f32_e32 v12, v12, v14
	v_pk_mul_f32 v[10:11], v[32:33], v[32:33]
	v_add_f32_e32 v12, v13, v12
	v_add_f32_e32 v10, v10, v12
	v_add_f32_e32 v10, v11, v10
	s_waitcnt vmcnt(9)
	v_lshlrev_b32_e32 v24, 16, v188
	v_and_b32_e32 v25, 0xffff0000, v188
	v_lshlrev_b32_e32 v20, 16, v189
	v_and_b32_e32 v21, 0xffff0000, v189
	v_pk_add_f32 v[8:9], v[8:9], v[20:21]
	v_lshlrev_b32_e32 v20, 16, v190
	v_and_b32_e32 v21, 0xffff0000, v190
	v_pk_add_f32 v[6:7], v[6:7], v[24:25]
	v_pk_add_f32 v[20:21], v[2:3], v[20:21]
	v_lshlrev_b32_e32 v2, 16, v191
	v_and_b32_e32 v3, 0xffff0000, v191
	v_pk_add_f32 v[22:23], v[4:5], v[2:3]
	v_pk_mul_f32 v[2:3], v[6:7], v[6:7]
	v_pk_mul_f32 v[4:5], v[8:9], v[8:9]
	v_add_f32_e32 v2, v2, v10
	v_add_f32_e32 v2, v3, v2
	v_add_f32_e32 v2, v4, v2
	v_pk_mul_f32 v[24:25], v[20:21], v[20:21]
	v_add_f32_e32 v2, v5, v2
	v_add_f32_e32 v2, v24, v2
	v_pk_mul_f32 v[26:27], v[22:23], v[22:23]
	v_add_f32_e32 v2, v25, v2
	v_add_f32_e32 v2, v26, v2
	v_add_f32_e32 v10, v27, v2
	v_cvt_pk_bf16_f32 v2, v6, v7
	v_cvt_pk_bf16_f32 v3, v8, v9
	v_cvt_pk_bf16_f32 v4, v20, v21
	v_cvt_pk_bf16_f32 v5, v22, v23
	global_store_dwordx4 v[18:19], v[2:5], off offset:256 sc0 sc1
	ds_bpermute_b32 v2, v154, v10
	s_waitcnt lgkmcnt(0)
	v_add_f32_e32 v2, v10, v2
	ds_bpermute_b32 v3, v153, v2
	s_and_saveexec_b64 s[20:21], s[38:39]
	s_cbranch_execz .LBB0_955
	s_waitcnt lgkmcnt(0)
	v_add_f32_e32 v2, v2, v3
	ds_write_b32 v150, v2 offset:2816
